# opt39: opt26 + mid-segment s_setprio 0/1 flip pair deleted in all 8 GEMM K-loops (4 per iteration)
# speedup vs baseline: 1.0033x; 1.0033x over previous
; #define PG8_STAGE(bufoff, gbase, voff) do { _Pragma("unroll") for (int _i = 0; _i < 2; ++_i) \
;         __builtin_amdgcn_global_load_lds((const unsigned*)((const char*)(gbase) + (voff)[_i]), (LAS unsigned*)(lds + (bufoff) + ldsw + _i * 8192), 16, 0, 0); } while (0)
; #define PG8_LDA(dst, b, h) do { _Pragma("unroll") for (int m = 0; m < 4; ++m) _Pragma("unroll") for (int k = 0; k < 2; ++k) dst[m][k] = *(const LAS bf16x8*)(lds + PG8_SA(b, h) + aoff + m * 2048 + k * 1024); } while (0)
; #define PG8_LDB(dst, b, h) do { _Pragma("unroll") for (int n = 0; n < 2; ++n) _Pragma("unroll") for (int k = 0; k < 2; ++k) dst[n][k] = *(const LAS bf16x8*)(lds + PG8_SB(b, h) + boff + n * 2048 + k * 1024); } while (0)
; #define PG8_MMA(ai, bj, At, Bt) do { __builtin_amdgcn_s_setprio(1); _Pragma("unroll") for (int m = 0; m < 4; ++m) _Pragma("unroll") for (int n = 0; n < 2; ++n) _Pragma("unroll") for (int k = 0; k < 2; ++k) \
;         acc[ai][bj][m][n] = __builtin_amdgcn_mfma_f32_16x16x32_bf16(Bt[n][k], At[m][k], acc[ai][bj][m][n], 0, 0, 0); __builtin_amdgcn_s_setprio(0); } while (0)
; #define PG8_WAIT_V(n) asm volatile("s_waitcnt vmcnt(" #n ")" ::: "memory")
; #define PG8_WAIT_L(n) asm volatile("s_waitcnt lgkmcnt(" #n ")" ::: "memory")
; #define PG8_BAR __builtin_amdgcn_s_barrier()
; #define PG8_SCHED __builtin_amdgcn_sched_barrier(0)
; template <class Epi>
; __device__ __forceinline__ void gemm_phase(LAS unsigned char* lds, const Gemm g, const StaticOrder& S, const Epi& E) {
;     ...
;             PG8_LDB(B0, 0, 0); PG8_LDB(B1, 0, 1); PG8_SCHED; PG8_LDA(At, 0, 0); PG8_STAGE(PG8_SA(1, 1), a1 + hsA, voffA);
;             PG8_WAIT_V(8); PG8_WAIT_L(0); PG8_BAR; PG8_MMA(0, 0, At, B0); PG8_MMA(0, 1, At, B1); PG8_BAR; PG8_SCHED;
.LBB0_214:
	ds_read_b128 v[144:147], v155
	ds_read_b128 v[148:151], v155 offset:1024
	ds_read_b128 v[162:165], v155 offset:2048
	ds_read_b128 v[166:169], v155 offset:3072
	ds_read_b128 v[180:183], v156
	ds_read_b128 v[184:187], v156 offset:1024
	ds_read_b128 v[188:191], v156 offset:2048
	ds_read_b128 v[192:195], v156 offset:3072
	s_add_u32 s38, s58, 0xfffc0080
	s_addc_u32 s39, s59, -1
	s_cmp_eq_u32 s37, 12
	s_cselect_b32 s63, s6, s39
	s_cselect_b32 s62, s7, s38
	s_cselect_b32 s61, s11, s36
	s_cselect_b32 s60, s13, s35
	s_add_i32 m0, s19, 0xc000
	ds_read_b128 v[196:199], v157
	ds_read_b128 v[200:203], v157 offset:1024
	ds_read_b128 v[204:207], v157 offset:2048
	ds_read_b128 v[208:211], v157 offset:3072
	ds_read_b128 v[212:215], v157 offset:4096
	ds_read_b128 v[216:219], v157 offset:5120
	ds_read_b128 v[220:223], v157 offset:6144
	ds_read_b128 v[224:227], v157 offset:7168
	global_load_lds_dwordx4 v136, s[58:59]
	s_add_i32 m0, s19, 0xe000
	s_nop 0
	global_load_lds_dwordx4 v138, s[58:59]
	s_waitcnt vmcnt(8)
	s_waitcnt lgkmcnt(0)
	s_barrier
	s_setprio 1
	s_waitcnt lgkmcnt(0)
	v_mfma_f32_16x16x32_bf16 v[124:127], v[144:147], v[196:199], v[124:127]
	v_mfma_f32_16x16x32_bf16 v[120:123], v[162:165], v[196:199], v[120:123]
	v_mfma_f32_16x16x32_bf16 v[108:111], v[144:147], v[204:207], v[108:111]
	v_mfma_f32_16x16x32_bf16 v[104:107], v[162:165], v[204:207], v[104:107]
	v_mfma_f32_16x16x32_bf16 v[92:95], v[144:147], v[212:215], v[92:95]
	v_mfma_f32_16x16x32_bf16 v[88:91], v[162:165], v[212:215], v[88:91]
	v_mfma_f32_16x16x32_bf16 v[76:79], v[144:147], v[220:223], v[76:79]
	v_mfma_f32_16x16x32_bf16 v[72:75], v[162:165], v[220:223], v[72:75]
	v_mfma_f32_16x16x32_bf16 v[124:127], v[148:151], v[200:203], v[124:127]
	v_mfma_f32_16x16x32_bf16 v[120:123], v[166:169], v[200:203], v[120:123]
	v_mfma_f32_16x16x32_bf16 v[108:111], v[148:151], v[208:211], v[108:111]
	v_mfma_f32_16x16x32_bf16 v[104:107], v[166:169], v[208:211], v[104:107]
	v_mfma_f32_16x16x32_bf16 v[92:95], v[148:151], v[216:219], v[92:95]
	v_mfma_f32_16x16x32_bf16 v[88:91], v[166:169], v[216:219], v[88:91]
	v_mfma_f32_16x16x32_bf16 v[76:79], v[148:151], v[224:227], v[76:79]
	v_mfma_f32_16x16x32_bf16 v[72:75], v[166:169], v[224:227], v[72:75]


; #define PG8_STAGE(bufoff, gbase, voff) do { _Pragma("unroll") for (int _i = 0; _i < 2; ++_i) \
;         __builtin_amdgcn_global_load_lds((const unsigned*)((const char*)(gbase) + (voff)[_i]), (LAS unsigned*)(lds + (bufoff) + ldsw + _i * 8192), 16, 0, 0); } while (0)
; #define PG8_LDA(dst, b, h) do { _Pragma("unroll") for (int m = 0; m < 4; ++m) _Pragma("unroll") for (int k = 0; k < 2; ++k) dst[m][k] = *(const LAS bf16x8*)(lds + PG8_SA(b, h) + aoff + m * 2048 + k * 1024); } while (0)
; #define PG8_MMA(ai, bj, At, Bt) do { __builtin_amdgcn_s_setprio(1); _Pragma("unroll") for (int m = 0; m < 4; ++m) _Pragma("unroll") for (int n = 0; n < 2; ++n) _Pragma("unroll") for (int k = 0; k < 2; ++k) \
;         acc[ai][bj][m][n] = __builtin_amdgcn_mfma_f32_16x16x32_bf16(Bt[n][k], At[m][k], acc[ai][bj][m][n], 0, 0, 0); __builtin_amdgcn_s_setprio(0); } while (0)
; #define PG8_WAIT_V(n) asm volatile("s_waitcnt vmcnt(" #n ")" ::: "memory")
; #define PG8_WAIT_L(n) asm volatile("s_waitcnt lgkmcnt(" #n ")" ::: "memory")
; #define PG8_BAR __builtin_amdgcn_s_barrier()
; #define PG8_SCHED __builtin_amdgcn_sched_barrier(0)
; template <class Epi>
; __device__ __forceinline__ void gemm_phase(LAS unsigned char* lds, const Gemm g, const StaticOrder& S, const Epi& E) {
;     ...
;             PG8_WAIT_V(8); PG8_WAIT_L(0); PG8_BAR; PG8_MMA(0, 0, At, B0); PG8_MMA(0, 1, At, B1); PG8_BAR; PG8_SCHED;
;             PG8_LDA(At, 0, 1); PG8_STAGE(PG8_SB(0, 0), b2, voffB); PG8_STAGE(PG8_SB(0, 1), b2 + hsB, voffB); PG8_STAGE(PG8_SA(0, 0), a2, voffA);
;             PG8_WAIT_V(8); PG8_WAIT_L(0); PG8_BAR; PG8_MMA(1, 0, At, B0); PG8_MMA(1, 1, At, B1); PG8_BAR; PG8_SCHED;
	v_mfma_f32_16x16x32_bf16 v[116:119], v[180:183], v[196:199], v[116:119]
	v_mfma_f32_16x16x32_bf16 v[112:115], v[188:191], v[196:199], v[112:115]
	v_mfma_f32_16x16x32_bf16 v[100:103], v[180:183], v[204:207], v[100:103]
	v_mfma_f32_16x16x32_bf16 v[96:99], v[188:191], v[204:207], v[96:99]
	v_mfma_f32_16x16x32_bf16 v[84:87], v[180:183], v[212:215], v[84:87]
	v_mfma_f32_16x16x32_bf16 v[80:83], v[188:191], v[212:215], v[80:83]
	v_mfma_f32_16x16x32_bf16 v[68:71], v[180:183], v[220:223], v[68:71]
	v_mfma_f32_16x16x32_bf16 v[64:67], v[188:191], v[220:223], v[64:67]
	v_mfma_f32_16x16x32_bf16 v[116:119], v[184:187], v[200:203], v[116:119]
	v_mfma_f32_16x16x32_bf16 v[112:115], v[192:195], v[200:203], v[112:115]
	v_mfma_f32_16x16x32_bf16 v[100:103], v[184:187], v[208:211], v[100:103]
	v_mfma_f32_16x16x32_bf16 v[96:99], v[192:195], v[208:211], v[96:99]
	v_mfma_f32_16x16x32_bf16 v[84:87], v[184:187], v[216:219], v[84:87]
	v_mfma_f32_16x16x32_bf16 v[80:83], v[192:195], v[216:219], v[80:83]
	v_mfma_f32_16x16x32_bf16 v[68:71], v[184:187], v[224:227], v[68:71]
	v_mfma_f32_16x16x32_bf16 v[64:67], v[192:195], v[224:227], v[64:67]
	s_setprio 0
	s_barrier
	s_add_i32 s38, s30, s16
	s_mov_b32 m0, s38
	ds_read_b128 v[196:199], v157 offset:16384
	ds_read_b128 v[200:203], v157 offset:17408
	ds_read_b128 v[204:207], v157 offset:18432
	ds_read_b128 v[208:211], v157 offset:19456
	ds_read_b128 v[212:215], v157 offset:20480
	ds_read_b128 v[216:219], v157 offset:21504
	ds_read_b128 v[220:223], v157 offset:22528
	ds_read_b128 v[224:227], v157 offset:23552
	global_load_lds_dwordx4 v132, s[60:61]
	s_add_i32 m0, s38, 0x2000
	s_add_u32 s38, s60, 0x40000
	s_addc_u32 s39, s61, 0
	s_add_i32 s40, s31, s16
	global_load_lds_dwordx4 v128, s[60:61]
	s_mov_b32 m0, s40
	s_nop 0
	global_load_lds_dwordx4 v132, s[38:39]
	s_add_i32 m0, s40, 0x2000
	s_nop 0
	global_load_lds_dwordx4 v128, s[38:39]
	s_mov_b32 m0, s19
	s_nop 0
	global_load_lds_dwordx4 v134, s[62:63]
	s_mov_b32 m0, s22
	s_nop 0
	global_load_lds_dwordx4 v130, s[62:63]
	s_waitcnt vmcnt(8)
	s_waitcnt lgkmcnt(0)
	s_barrier
	s_setprio 1
	s_waitcnt lgkmcnt(0)
	v_mfma_f32_16x16x32_bf16 v[60:63], v[144:147], v[196:199], v[60:63]
	v_mfma_f32_16x16x32_bf16 v[56:59], v[162:165], v[196:199], v[56:59]
	v_mfma_f32_16x16x32_bf16 v[44:47], v[144:147], v[204:207], v[44:47]
	v_mfma_f32_16x16x32_bf16 v[40:43], v[162:165], v[204:207], v[40:43]
	v_mfma_f32_16x16x32_bf16 v[28:31], v[144:147], v[212:215], v[28:31]
	v_mfma_f32_16x16x32_bf16 v[24:27], v[162:165], v[212:215], v[24:27]
	v_mfma_f32_16x16x32_bf16 v[12:15], v[144:147], v[220:223], v[12:15]
	v_mfma_f32_16x16x32_bf16 v[8:11], v[162:165], v[220:223], v[8:11]
	v_mfma_f32_16x16x32_bf16 v[60:63], v[148:151], v[200:203], v[60:63]
	v_mfma_f32_16x16x32_bf16 v[56:59], v[166:169], v[200:203], v[56:59]
	v_mfma_f32_16x16x32_bf16 v[44:47], v[148:151], v[208:211], v[44:47]
	v_mfma_f32_16x16x32_bf16 v[40:43], v[166:169], v[208:211], v[40:43]
	v_mfma_f32_16x16x32_bf16 v[28:31], v[148:151], v[216:219], v[28:31]
	v_mfma_f32_16x16x32_bf16 v[24:27], v[166:169], v[216:219], v[24:27]
	v_mfma_f32_16x16x32_bf16 v[12:15], v[148:151], v[224:227], v[12:15]
	v_mfma_f32_16x16x32_bf16 v[8:11], v[166:169], v[224:227], v[8:11]


; #define PG8_STAGE(bufoff, gbase, voff) do { _Pragma("unroll") for (int _i = 0; _i < 2; ++_i) \
;         __builtin_amdgcn_global_load_lds((const unsigned*)((const char*)(gbase) + (voff)[_i]), (LAS unsigned*)(lds + (bufoff) + ldsw + _i * 8192), 16, 0, 0); } while (0)
; #define PG8_LDA(dst, b, h) do { _Pragma("unroll") for (int m = 0; m < 4; ++m) _Pragma("unroll") for (int k = 0; k < 2; ++k) dst[m][k] = *(const LAS bf16x8*)(lds + PG8_SA(b, h) + aoff + m * 2048 + k * 1024); } while (0)
; #define PG8_LDB(dst, b, h) do { _Pragma("unroll") for (int n = 0; n < 2; ++n) _Pragma("unroll") for (int k = 0; k < 2; ++k) dst[n][k] = *(const LAS bf16x8*)(lds + PG8_SB(b, h) + boff + n * 2048 + k * 1024); } while (0)
; #define PG8_MMA(ai, bj, At, Bt) do { __builtin_amdgcn_s_setprio(1); _Pragma("unroll") for (int m = 0; m < 4; ++m) _Pragma("unroll") for (int n = 0; n < 2; ++n) _Pragma("unroll") for (int k = 0; k < 2; ++k) \
;         acc[ai][bj][m][n] = __builtin_amdgcn_mfma_f32_16x16x32_bf16(Bt[n][k], At[m][k], acc[ai][bj][m][n], 0, 0, 0); __builtin_amdgcn_s_setprio(0); } while (0)
; #define PG8_WAIT_V(n) asm volatile("s_waitcnt vmcnt(" #n ")" ::: "memory")
; #define PG8_WAIT_L(n) asm volatile("s_waitcnt lgkmcnt(" #n ")" ::: "memory")
; #define PG8_BAR __builtin_amdgcn_s_barrier()
; #define PG8_SCHED __builtin_amdgcn_sched_barrier(0)
; template <class Epi>
; __device__ __forceinline__ void gemm_phase(LAS unsigned char* lds, const Gemm g, const StaticOrder& S, const Epi& E) {
;     ...
;             PG8_WAIT_V(8); PG8_WAIT_L(0); PG8_BAR; PG8_MMA(1, 0, At, B0); PG8_MMA(1, 1, At, B1); PG8_BAR; PG8_SCHED;
;             PG8_LDB(B0, 1, 0); PG8_LDB(B1, 1, 1); PG8_SCHED; PG8_LDA(At, 1, 0); PG8_STAGE(PG8_SA(0, 1), a2 + hsA, voffA);
;             PG8_WAIT_V(8); PG8_WAIT_L(0); PG8_BAR; PG8_MMA(0, 0, At, B0); PG8_MMA(0, 1, At, B1); PG8_BAR; PG8_SCHED;
	v_mfma_f32_16x16x32_bf16 v[52:55], v[180:183], v[196:199], v[52:55]
	v_mfma_f32_16x16x32_bf16 v[48:51], v[188:191], v[196:199], v[48:51]
	v_mfma_f32_16x16x32_bf16 v[36:39], v[180:183], v[204:207], v[36:39]
	v_mfma_f32_16x16x32_bf16 v[32:35], v[188:191], v[204:207], v[32:35]
	v_mfma_f32_16x16x32_bf16 v[20:23], v[180:183], v[212:215], v[20:23]
	v_mfma_f32_16x16x32_bf16 v[16:19], v[188:191], v[212:215], v[16:19]
	v_mfma_f32_16x16x32_bf16 v[4:7], v[180:183], v[220:223], v[4:7]
	v_mfma_f32_16x16x32_bf16 v[0:3], v[188:191], v[220:223], v[0:3]
	v_mfma_f32_16x16x32_bf16 v[52:55], v[184:187], v[200:203], v[52:55]
	v_mfma_f32_16x16x32_bf16 v[48:51], v[192:195], v[200:203], v[48:51]
	v_mfma_f32_16x16x32_bf16 v[36:39], v[184:187], v[208:211], v[36:39]
	v_mfma_f32_16x16x32_bf16 v[32:35], v[192:195], v[208:211], v[32:35]
	v_mfma_f32_16x16x32_bf16 v[20:23], v[184:187], v[216:219], v[20:23]
	v_mfma_f32_16x16x32_bf16 v[16:19], v[192:195], v[216:219], v[16:19]
	v_mfma_f32_16x16x32_bf16 v[4:7], v[184:187], v[224:227], v[4:7]
	v_mfma_f32_16x16x32_bf16 v[0:3], v[192:195], v[224:227], v[0:3]
	s_setprio 0
	s_barrier
	s_add_i32 s40, 0, 0x18000
	v_add_u32_e32 v159, s40, v153
	s_add_i32 s41, 0, 0x1c000
	ds_read_b128 v[144:147], v159
	ds_read_b128 v[148:151], v159 offset:1024
	ds_read_b128 v[162:165], v159 offset:2048
	ds_read_b128 v[166:169], v159 offset:3072
	v_add_u32_e32 v159, s41, v153
	ds_read_b128 v[180:183], v159
	ds_read_b128 v[184:187], v159 offset:1024
	ds_read_b128 v[188:191], v159 offset:2048
	ds_read_b128 v[192:195], v159 offset:3072
	s_add_u32 s38, s62, 0x40000
	s_addc_u32 s39, s63, 0
	s_mov_b32 m0, s23
	ds_read_b128 v[196:199], v157 offset:32768
	ds_read_b128 v[200:203], v157 offset:33792
	ds_read_b128 v[204:207], v157 offset:34816
	ds_read_b128 v[208:211], v157 offset:35840
	ds_read_b128 v[212:215], v157 offset:36864
	ds_read_b128 v[216:219], v157 offset:37888
	ds_read_b128 v[220:223], v157 offset:38912
	ds_read_b128 v[224:227], v157 offset:39936
	global_load_lds_dwordx4 v134, s[38:39]
	s_mov_b32 m0, s24
	s_nop 0
	global_load_lds_dwordx4 v130, s[38:39]
	s_waitcnt vmcnt(8)
	s_waitcnt lgkmcnt(0)
	s_barrier
	s_setprio 1
	s_waitcnt lgkmcnt(0)
	v_mfma_f32_16x16x32_bf16 v[124:127], v[144:147], v[196:199], v[124:127]
	v_mfma_f32_16x16x32_bf16 v[120:123], v[162:165], v[196:199], v[120:123]
	v_mfma_f32_16x16x32_bf16 v[108:111], v[144:147], v[204:207], v[108:111]
	v_mfma_f32_16x16x32_bf16 v[104:107], v[162:165], v[204:207], v[104:107]
	v_mfma_f32_16x16x32_bf16 v[92:95], v[144:147], v[212:215], v[92:95]
	v_mfma_f32_16x16x32_bf16 v[88:91], v[162:165], v[212:215], v[88:91]
	v_mfma_f32_16x16x32_bf16 v[76:79], v[144:147], v[220:223], v[76:79]
	v_mfma_f32_16x16x32_bf16 v[72:75], v[162:165], v[220:223], v[72:75]
	v_mfma_f32_16x16x32_bf16 v[124:127], v[148:151], v[200:203], v[124:127]
	v_mfma_f32_16x16x32_bf16 v[120:123], v[166:169], v[200:203], v[120:123]
	v_mfma_f32_16x16x32_bf16 v[108:111], v[148:151], v[208:211], v[108:111]
	v_mfma_f32_16x16x32_bf16 v[104:107], v[166:169], v[208:211], v[104:107]
	v_mfma_f32_16x16x32_bf16 v[92:95], v[148:151], v[216:219], v[92:95]
	v_mfma_f32_16x16x32_bf16 v[88:91], v[166:169], v[216:219], v[88:91]
	v_mfma_f32_16x16x32_bf16 v[76:79], v[148:151], v[224:227], v[76:79]
	v_mfma_f32_16x16x32_bf16 v[72:75], v[166:169], v[224:227], v[72:75]


; #define PG8_STAGE(bufoff, gbase, voff) do { _Pragma("unroll") for (int _i = 0; _i < 2; ++_i) \
;         __builtin_amdgcn_global_load_lds((const unsigned*)((const char*)(gbase) + (voff)[_i]), (LAS unsigned*)(lds + (bufoff) + ldsw + _i * 8192), 16, 0, 0); } while (0)
; #define PG8_LDA(dst, b, h) do { _Pragma("unroll") for (int m = 0; m < 4; ++m) _Pragma("unroll") for (int k = 0; k < 2; ++k) dst[m][k] = *(const LAS bf16x8*)(lds + PG8_SA(b, h) + aoff + m * 2048 + k * 1024); } while (0)
; #define PG8_MMA(ai, bj, At, Bt) do { __builtin_amdgcn_s_setprio(1); _Pragma("unroll") for (int m = 0; m < 4; ++m) _Pragma("unroll") for (int n = 0; n < 2; ++n) _Pragma("unroll") for (int k = 0; k < 2; ++k) \
;         acc[ai][bj][m][n] = __builtin_amdgcn_mfma_f32_16x16x32_bf16(Bt[n][k], At[m][k], acc[ai][bj][m][n], 0, 0, 0); __builtin_amdgcn_s_setprio(0); } while (0)
; #define PG8_WAIT_V(n) asm volatile("s_waitcnt vmcnt(" #n ")" ::: "memory")
; #define PG8_WAIT_L(n) asm volatile("s_waitcnt lgkmcnt(" #n ")" ::: "memory")
; #define PG8_BAR __builtin_amdgcn_s_barrier()
; #define PG8_SCHED __builtin_amdgcn_sched_barrier(0)
; template <class Epi>
; __device__ __forceinline__ void gemm_phase(LAS unsigned char* lds, const Gemm g, const StaticOrder& S, const Epi& E) {
;     ...
;             PG8_WAIT_V(8); PG8_WAIT_L(0); PG8_BAR; PG8_MMA(0, 0, At, B0); PG8_MMA(0, 1, At, B1); PG8_BAR; PG8_SCHED;
;             PG8_LDA(At, 1, 1); PG8_STAGE(PG8_SB(1, 0), b3, voffB); PG8_STAGE(PG8_SB(1, 1), b3 + hsB, voffB); PG8_STAGE(PG8_SA(1, 0), a3, voffA);
;             PG8_WAIT_V(8); PG8_WAIT_L(0); PG8_BAR; PG8_MMA(1, 0, At, B0); PG8_MMA(1, 1, At, B1); PG8_BAR; PG8_SCHED;
	v_mfma_f32_16x16x32_bf16 v[116:119], v[180:183], v[196:199], v[116:119]
	v_mfma_f32_16x16x32_bf16 v[112:115], v[188:191], v[196:199], v[112:115]
	v_mfma_f32_16x16x32_bf16 v[100:103], v[180:183], v[204:207], v[100:103]
	v_mfma_f32_16x16x32_bf16 v[96:99], v[188:191], v[204:207], v[96:99]
	v_mfma_f32_16x16x32_bf16 v[84:87], v[180:183], v[212:215], v[84:87]
	v_mfma_f32_16x16x32_bf16 v[80:83], v[188:191], v[212:215], v[80:83]
	v_mfma_f32_16x16x32_bf16 v[68:71], v[180:183], v[220:223], v[68:71]
	v_mfma_f32_16x16x32_bf16 v[64:67], v[188:191], v[220:223], v[64:67]
	v_mfma_f32_16x16x32_bf16 v[116:119], v[184:187], v[200:203], v[116:119]
	v_mfma_f32_16x16x32_bf16 v[112:115], v[192:195], v[200:203], v[112:115]
	v_mfma_f32_16x16x32_bf16 v[100:103], v[184:187], v[208:211], v[100:103]
	v_mfma_f32_16x16x32_bf16 v[96:99], v[192:195], v[208:211], v[96:99]
	v_mfma_f32_16x16x32_bf16 v[84:87], v[184:187], v[216:219], v[84:87]
	v_mfma_f32_16x16x32_bf16 v[80:83], v[192:195], v[216:219], v[80:83]
	v_mfma_f32_16x16x32_bf16 v[68:71], v[184:187], v[224:227], v[68:71]
	v_mfma_f32_16x16x32_bf16 v[64:67], v[192:195], v[224:227], v[64:67]
	s_setprio 0
	s_barrier
	s_add_u32 s98, s60, 0x80
	s_addc_u32 s99, s61, 0
	s_add_u32 s100, s62, 0x80
	s_addc_u32 s101, s63, 0
	s_add_i32 s38, s40, s16
	s_mov_b32 m0, s38
	ds_read_b128 v[196:199], v157 offset:49152
	ds_read_b128 v[200:203], v157 offset:50176
	ds_read_b128 v[204:207], v157 offset:51200
	ds_read_b128 v[208:211], v157 offset:52224
	ds_read_b128 v[212:215], v157 offset:53248
	ds_read_b128 v[216:219], v157 offset:54272
	ds_read_b128 v[220:223], v157 offset:55296
	ds_read_b128 v[224:227], v157 offset:56320
	global_load_lds_dwordx4 v132, s[98:99]
	s_add_i32 m0, s38, 0x2000
	s_add_u32 s38, s60, 0x40080
	s_addc_u32 s39, s61, 0
	s_add_i32 s40, s41, s16
	global_load_lds_dwordx4 v128, s[98:99]
	s_mov_b32 m0, s40
	s_nop 0
	global_load_lds_dwordx4 v132, s[38:39]
	s_add_i32 m0, s40, 0x2000
	s_nop 0
	global_load_lds_dwordx4 v128, s[38:39]
	s_mov_b32 m0, s25
	s_nop 0
	global_load_lds_dwordx4 v134, s[100:101]
	s_mov_b32 m0, s26
	s_nop 0
	global_load_lds_dwordx4 v130, s[100:101]
	s_waitcnt vmcnt(8)
	s_waitcnt lgkmcnt(0)
	s_barrier
	s_setprio 1
	s_waitcnt lgkmcnt(0)
	v_mfma_f32_16x16x32_bf16 v[60:63], v[144:147], v[196:199], v[60:63]
	v_mfma_f32_16x16x32_bf16 v[56:59], v[162:165], v[196:199], v[56:59]
	v_mfma_f32_16x16x32_bf16 v[44:47], v[144:147], v[204:207], v[44:47]
	v_mfma_f32_16x16x32_bf16 v[40:43], v[162:165], v[204:207], v[40:43]
	v_mfma_f32_16x16x32_bf16 v[28:31], v[144:147], v[212:215], v[28:31]
	v_mfma_f32_16x16x32_bf16 v[24:27], v[162:165], v[212:215], v[24:27]
	v_mfma_f32_16x16x32_bf16 v[12:15], v[144:147], v[220:223], v[12:15]
	v_mfma_f32_16x16x32_bf16 v[8:11], v[162:165], v[220:223], v[8:11]
	v_mfma_f32_16x16x32_bf16 v[60:63], v[148:151], v[200:203], v[60:63]
	v_mfma_f32_16x16x32_bf16 v[56:59], v[166:169], v[200:203], v[56:59]
	v_mfma_f32_16x16x32_bf16 v[44:47], v[148:151], v[208:211], v[44:47]
	v_mfma_f32_16x16x32_bf16 v[40:43], v[166:169], v[208:211], v[40:43]
	v_mfma_f32_16x16x32_bf16 v[28:31], v[148:151], v[216:219], v[28:31]
	v_mfma_f32_16x16x32_bf16 v[24:27], v[166:169], v[216:219], v[24:27]
	v_mfma_f32_16x16x32_bf16 v[12:15], v[148:151], v[224:227], v[12:15]
	v_mfma_f32_16x16x32_bf16 v[8:11], v[166:169], v[224:227], v[8:11]


; #define PG8_MMA(ai, bj, At, Bt) do { __builtin_amdgcn_s_setprio(1); _Pragma("unroll") for (int m = 0; m < 4; ++m) _Pragma("unroll") for (int n = 0; n < 2; ++n) _Pragma("unroll") for (int k = 0; k < 2; ++k) \
;         acc[ai][bj][m][n] = __builtin_amdgcn_mfma_f32_16x16x32_bf16(Bt[n][k], At[m][k], acc[ai][bj][m][n], 0, 0, 0); __builtin_amdgcn_s_setprio(0); } while (0)
; #define PG8_WAIT_V(n) asm volatile("s_waitcnt vmcnt(" #n ")" ::: "memory")
; #define PG8_WAIT_L(n) asm volatile("s_waitcnt lgkmcnt(" #n ")" ::: "memory")
; #define PG8_BAR __builtin_amdgcn_s_barrier()
; #define PG8_SCHED __builtin_amdgcn_sched_barrier(0)
; template <class Epi>
; __device__ __forceinline__ void gemm_phase(LAS unsigned char* lds, const Gemm g, const StaticOrder& S, const Epi& E) {
;     ...
;         for (int t = 0; t < nt; t += 2) {
;     ...
;             PG8_WAIT_V(8); PG8_WAIT_L(0); PG8_BAR; PG8_MMA(1, 0, At, B0); PG8_MMA(1, 1, At, B1); PG8_BAR; PG8_SCHED;
;         }
	v_mfma_f32_16x16x32_bf16 v[52:55], v[180:183], v[196:199], v[52:55]
	v_mfma_f32_16x16x32_bf16 v[48:51], v[188:191], v[196:199], v[48:51]
	v_mfma_f32_16x16x32_bf16 v[36:39], v[180:183], v[204:207], v[36:39]
	v_mfma_f32_16x16x32_bf16 v[32:35], v[188:191], v[204:207], v[32:35]
	v_mfma_f32_16x16x32_bf16 v[20:23], v[180:183], v[212:215], v[20:23]
	v_mfma_f32_16x16x32_bf16 v[16:19], v[188:191], v[212:215], v[16:19]
	v_mfma_f32_16x16x32_bf16 v[4:7], v[180:183], v[220:223], v[4:7]
	v_mfma_f32_16x16x32_bf16 v[0:3], v[188:191], v[220:223], v[0:3]
	v_mfma_f32_16x16x32_bf16 v[52:55], v[184:187], v[200:203], v[52:55]
	v_mfma_f32_16x16x32_bf16 v[48:51], v[192:195], v[200:203], v[48:51]
	v_mfma_f32_16x16x32_bf16 v[36:39], v[184:187], v[208:211], v[36:39]
	v_mfma_f32_16x16x32_bf16 v[32:35], v[192:195], v[208:211], v[32:35]
	v_mfma_f32_16x16x32_bf16 v[20:23], v[184:187], v[216:219], v[20:23]
	v_mfma_f32_16x16x32_bf16 v[16:19], v[192:195], v[216:219], v[16:19]
	v_mfma_f32_16x16x32_bf16 v[4:7], v[184:187], v[224:227], v[4:7]
	v_mfma_f32_16x16x32_bf16 v[0:3], v[192:195], v[224:227], v[0:3]
	s_setprio 0
	s_barrier
	s_add_i32 s37, s37, 2
	s_add_u32 s58, s58, 0x100
	s_addc_u32 s59, s59, 0
	s_add_u32 s35, s35, 0x100
	s_addc_u32 s36, s36, 0
	s_cmp_gt_u32 s37, 13
	s_cbranch_scc0 .LBB0_214
	s_and_b64 vcc, exec, s[8:9]
	s_cbranch_vccz .LBB0_217
	s_barrier

; #define PG8_STAGE(bufoff, gbase, voff) do { _Pragma("unroll") for (int _i = 0; _i < 2; ++_i) \
;         __builtin_amdgcn_global_load_lds((const unsigned*)((const char*)(gbase) + (voff)[_i]), (LAS unsigned*)(lds + (bufoff) + ldsw + _i * 8192), 16, 0, 0); } while (0)
; #define PG8_LDA(dst, b, h) do { _Pragma("unroll") for (int m = 0; m < 4; ++m) _Pragma("unroll") for (int k = 0; k < 2; ++k) dst[m][k] = *(const LAS bf16x8*)(lds + PG8_SA(b, h) + aoff + m * 2048 + k * 1024); } while (0)
; #define PG8_LDB(dst, b, h) do { _Pragma("unroll") for (int n = 0; n < 2; ++n) _Pragma("unroll") for (int k = 0; k < 2; ++k) dst[n][k] = *(const LAS bf16x8*)(lds + PG8_SB(b, h) + boff + n * 2048 + k * 1024); } while (0)
; #define PG8_MMA(ai, bj, At, Bt) do { __builtin_amdgcn_s_setprio(1); _Pragma("unroll") for (int m = 0; m < 4; ++m) _Pragma("unroll") for (int n = 0; n < 2; ++n) _Pragma("unroll") for (int k = 0; k < 2; ++k) \
;         acc[ai][bj][m][n] = __builtin_amdgcn_mfma_f32_16x16x32_bf16(Bt[n][k], At[m][k], acc[ai][bj][m][n], 0, 0, 0); __builtin_amdgcn_s_setprio(0); } while (0)
; #define PG8_WAIT_V(n) asm volatile("s_waitcnt vmcnt(" #n ")" ::: "memory")
; #define PG8_WAIT_L(n) asm volatile("s_waitcnt lgkmcnt(" #n ")" ::: "memory")
; #define PG8_BAR __builtin_amdgcn_s_barrier()
; #define PG8_SCHED __builtin_amdgcn_sched_barrier(0)
; template <class Epi>
; __device__ __forceinline__ void gemm_phase(LAS unsigned char* lds, const Gemm g, const StaticOrder& S, const Epi& E) {
;     ...
;             PG8_LDB(B0, 0, 0); PG8_LDB(B1, 0, 1); PG8_SCHED; PG8_LDA(At, 0, 0); PG8_STAGE(PG8_SA(1, 1), a1 + hsA, voffA);
;             PG8_WAIT_V(8); PG8_WAIT_L(0); PG8_BAR; PG8_MMA(0, 0, At, B0); PG8_MMA(0, 1, At, B1); PG8_BAR; PG8_SCHED;
.LBB0_296:
	ds_read_b128 v[144:147], v157
	ds_read_b128 v[148:151], v157 offset:1024
	ds_read_b128 v[164:167], v157 offset:2048
	ds_read_b128 v[168:171], v157 offset:3072
	ds_read_b128 v[180:183], v158
	ds_read_b128 v[184:187], v158 offset:1024
	ds_read_b128 v[188:191], v158 offset:2048
	ds_read_b128 v[192:195], v158 offset:3072
	s_add_u32 s60, s12, 0x100
	s_addc_u32 s61, s13, 0
	s_cmp_eq_u32 s34, 40
	s_cselect_b32 s65, s1, s61
	s_cselect_b32 s64, s0, s60
	s_cselect_b32 s63, s59, s7
	s_cselect_b32 s62, s58, s6
	s_add_i32 m0, s5, 0xc000
	ds_read_b128 v[196:199], v159
	ds_read_b128 v[200:203], v159 offset:1024
	ds_read_b128 v[204:207], v159 offset:2048
	ds_read_b128 v[208:211], v159 offset:3072
	ds_read_b128 v[212:215], v159 offset:4096
	ds_read_b128 v[216:219], v159 offset:5120
	ds_read_b128 v[220:223], v159 offset:6144
	ds_read_b128 v[224:227], v159 offset:7168
	global_load_lds_dwordx4 v136, s[12:13]
	s_add_i32 m0, s5, 0xe000
	s_nop 0
	global_load_lds_dwordx4 v138, s[12:13]
	s_waitcnt vmcnt(8)
	s_waitcnt lgkmcnt(0)
	s_barrier
	s_setprio 1
	s_waitcnt lgkmcnt(0)
	v_mfma_f32_16x16x32_bf16 v[124:127], v[144:147], v[196:199], v[124:127]
	v_mfma_f32_16x16x32_bf16 v[120:123], v[164:167], v[196:199], v[120:123]
	v_mfma_f32_16x16x32_bf16 v[108:111], v[144:147], v[204:207], v[108:111]
	v_mfma_f32_16x16x32_bf16 v[104:107], v[164:167], v[204:207], v[104:107]
	v_mfma_f32_16x16x32_bf16 v[92:95], v[144:147], v[212:215], v[92:95]
	v_mfma_f32_16x16x32_bf16 v[88:91], v[164:167], v[212:215], v[88:91]
	v_mfma_f32_16x16x32_bf16 v[76:79], v[144:147], v[220:223], v[76:79]
	v_mfma_f32_16x16x32_bf16 v[72:75], v[164:167], v[220:223], v[72:75]
	v_mfma_f32_16x16x32_bf16 v[124:127], v[148:151], v[200:203], v[124:127]
	v_mfma_f32_16x16x32_bf16 v[120:123], v[168:171], v[200:203], v[120:123]
	v_mfma_f32_16x16x32_bf16 v[108:111], v[148:151], v[208:211], v[108:111]
	v_mfma_f32_16x16x32_bf16 v[104:107], v[168:171], v[208:211], v[104:107]
	v_mfma_f32_16x16x32_bf16 v[92:95], v[148:151], v[216:219], v[92:95]
	v_mfma_f32_16x16x32_bf16 v[88:91], v[168:171], v[216:219], v[88:91]
	v_mfma_f32_16x16x32_bf16 v[76:79], v[148:151], v[224:227], v[76:79]
	v_mfma_f32_16x16x32_bf16 v[72:75], v[168:171], v[224:227], v[72:75]


; #define PG8_STAGE(bufoff, gbase, voff) do { _Pragma("unroll") for (int _i = 0; _i < 2; ++_i) \
;         __builtin_amdgcn_global_load_lds((const unsigned*)((const char*)(gbase) + (voff)[_i]), (LAS unsigned*)(lds + (bufoff) + ldsw + _i * 8192), 16, 0, 0); } while (0)
; #define PG8_LDA(dst, b, h) do { _Pragma("unroll") for (int m = 0; m < 4; ++m) _Pragma("unroll") for (int k = 0; k < 2; ++k) dst[m][k] = *(const LAS bf16x8*)(lds + PG8_SA(b, h) + aoff + m * 2048 + k * 1024); } while (0)
; #define PG8_MMA(ai, bj, At, Bt) do { __builtin_amdgcn_s_setprio(1); _Pragma("unroll") for (int m = 0; m < 4; ++m) _Pragma("unroll") for (int n = 0; n < 2; ++n) _Pragma("unroll") for (int k = 0; k < 2; ++k) \
;         acc[ai][bj][m][n] = __builtin_amdgcn_mfma_f32_16x16x32_bf16(Bt[n][k], At[m][k], acc[ai][bj][m][n], 0, 0, 0); __builtin_amdgcn_s_setprio(0); } while (0)
; #define PG8_WAIT_V(n) asm volatile("s_waitcnt vmcnt(" #n ")" ::: "memory")
; #define PG8_WAIT_L(n) asm volatile("s_waitcnt lgkmcnt(" #n ")" ::: "memory")
; #define PG8_BAR __builtin_amdgcn_s_barrier()
; #define PG8_SCHED __builtin_amdgcn_sched_barrier(0)
; template <class Epi>
; __device__ __forceinline__ void gemm_phase(LAS unsigned char* lds, const Gemm g, const StaticOrder& S, const Epi& E) {
;     ...
;             PG8_WAIT_V(8); PG8_WAIT_L(0); PG8_BAR; PG8_MMA(0, 0, At, B0); PG8_MMA(0, 1, At, B1); PG8_BAR; PG8_SCHED;
;             PG8_LDA(At, 0, 1); PG8_STAGE(PG8_SB(0, 0), b2, voffB); PG8_STAGE(PG8_SB(0, 1), b2 + hsB, voffB); PG8_STAGE(PG8_SA(0, 0), a2, voffA);
;             PG8_WAIT_V(8); PG8_WAIT_L(0); PG8_BAR; PG8_MMA(1, 0, At, B0); PG8_MMA(1, 1, At, B1); PG8_BAR; PG8_SCHED;
	v_mfma_f32_16x16x32_bf16 v[116:119], v[180:183], v[196:199], v[116:119]
	v_mfma_f32_16x16x32_bf16 v[112:115], v[188:191], v[196:199], v[112:115]
	v_mfma_f32_16x16x32_bf16 v[100:103], v[180:183], v[204:207], v[100:103]
	v_mfma_f32_16x16x32_bf16 v[96:99], v[188:191], v[204:207], v[96:99]
	v_mfma_f32_16x16x32_bf16 v[84:87], v[180:183], v[212:215], v[84:87]
	v_mfma_f32_16x16x32_bf16 v[80:83], v[188:191], v[212:215], v[80:83]
	v_mfma_f32_16x16x32_bf16 v[68:71], v[180:183], v[220:223], v[68:71]
	v_mfma_f32_16x16x32_bf16 v[64:67], v[188:191], v[220:223], v[64:67]
	v_mfma_f32_16x16x32_bf16 v[116:119], v[184:187], v[200:203], v[116:119]
	v_mfma_f32_16x16x32_bf16 v[112:115], v[192:195], v[200:203], v[112:115]
	v_mfma_f32_16x16x32_bf16 v[100:103], v[184:187], v[208:211], v[100:103]
	v_mfma_f32_16x16x32_bf16 v[96:99], v[192:195], v[208:211], v[96:99]
	v_mfma_f32_16x16x32_bf16 v[84:87], v[184:187], v[216:219], v[84:87]
	v_mfma_f32_16x16x32_bf16 v[80:83], v[192:195], v[216:219], v[80:83]
	v_mfma_f32_16x16x32_bf16 v[68:71], v[184:187], v[224:227], v[68:71]
	v_mfma_f32_16x16x32_bf16 v[64:67], v[192:195], v[224:227], v[64:67]
	s_setprio 0
	s_barrier
	s_add_i32 s12, s27, s4
	s_mov_b32 m0, s12
	ds_read_b128 v[196:199], v159 offset:16384
	ds_read_b128 v[200:203], v159 offset:17408
	ds_read_b128 v[204:207], v159 offset:18432
	ds_read_b128 v[208:211], v159 offset:19456
	ds_read_b128 v[212:215], v159 offset:20480
	ds_read_b128 v[216:219], v159 offset:21504
	ds_read_b128 v[220:223], v159 offset:22528
	ds_read_b128 v[224:227], v159 offset:23552
	global_load_lds_dwordx4 v130, s[62:63]
	s_add_i32 m0, s12, 0x2000
	s_add_u32 s12, s62, 0xb0000
	s_addc_u32 s13, s63, 0
	s_add_i32 s35, s28, s4
	global_load_lds_dwordx4 v134, s[62:63]
	s_mov_b32 m0, s35
	s_nop 0
	global_load_lds_dwordx4 v130, s[12:13]
	s_add_i32 m0, s35, 0x2000
	s_nop 0
	global_load_lds_dwordx4 v134, s[12:13]
	s_mov_b32 m0, s5
	s_nop 0
	global_load_lds_dwordx4 v128, s[64:65]
	s_mov_b32 m0, s16
	s_nop 0
	global_load_lds_dwordx4 v132, s[64:65]
	s_waitcnt vmcnt(8)
	s_waitcnt lgkmcnt(0)
	s_barrier
	s_setprio 1
	s_waitcnt lgkmcnt(0)
	v_mfma_f32_16x16x32_bf16 v[60:63], v[144:147], v[196:199], v[60:63]
	v_mfma_f32_16x16x32_bf16 v[56:59], v[164:167], v[196:199], v[56:59]
	v_mfma_f32_16x16x32_bf16 v[44:47], v[144:147], v[204:207], v[44:47]
	v_mfma_f32_16x16x32_bf16 v[40:43], v[164:167], v[204:207], v[40:43]
	v_mfma_f32_16x16x32_bf16 v[28:31], v[144:147], v[212:215], v[28:31]
	v_mfma_f32_16x16x32_bf16 v[24:27], v[164:167], v[212:215], v[24:27]
	v_mfma_f32_16x16x32_bf16 v[12:15], v[144:147], v[220:223], v[12:15]
	v_mfma_f32_16x16x32_bf16 v[8:11], v[164:167], v[220:223], v[8:11]
	v_mfma_f32_16x16x32_bf16 v[60:63], v[148:151], v[200:203], v[60:63]
	v_mfma_f32_16x16x32_bf16 v[56:59], v[168:171], v[200:203], v[56:59]
	v_mfma_f32_16x16x32_bf16 v[44:47], v[148:151], v[208:211], v[44:47]
	v_mfma_f32_16x16x32_bf16 v[40:43], v[168:171], v[208:211], v[40:43]
	v_mfma_f32_16x16x32_bf16 v[28:31], v[148:151], v[216:219], v[28:31]
	v_mfma_f32_16x16x32_bf16 v[24:27], v[168:171], v[216:219], v[24:27]
	v_mfma_f32_16x16x32_bf16 v[12:15], v[148:151], v[224:227], v[12:15]
	v_mfma_f32_16x16x32_bf16 v[8:11], v[168:171], v[224:227], v[8:11]


; #define PG8_STAGE(bufoff, gbase, voff) do { _Pragma("unroll") for (int _i = 0; _i < 2; ++_i) \
;         __builtin_amdgcn_global_load_lds((const unsigned*)((const char*)(gbase) + (voff)[_i]), (LAS unsigned*)(lds + (bufoff) + ldsw + _i * 8192), 16, 0, 0); } while (0)
; #define PG8_LDA(dst, b, h) do { _Pragma("unroll") for (int m = 0; m < 4; ++m) _Pragma("unroll") for (int k = 0; k < 2; ++k) dst[m][k] = *(const LAS bf16x8*)(lds + PG8_SA(b, h) + aoff + m * 2048 + k * 1024); } while (0)
; #define PG8_LDB(dst, b, h) do { _Pragma("unroll") for (int n = 0; n < 2; ++n) _Pragma("unroll") for (int k = 0; k < 2; ++k) dst[n][k] = *(const LAS bf16x8*)(lds + PG8_SB(b, h) + boff + n * 2048 + k * 1024); } while (0)
; #define PG8_MMA(ai, bj, At, Bt) do { __builtin_amdgcn_s_setprio(1); _Pragma("unroll") for (int m = 0; m < 4; ++m) _Pragma("unroll") for (int n = 0; n < 2; ++n) _Pragma("unroll") for (int k = 0; k < 2; ++k) \
;         acc[ai][bj][m][n] = __builtin_amdgcn_mfma_f32_16x16x32_bf16(Bt[n][k], At[m][k], acc[ai][bj][m][n], 0, 0, 0); __builtin_amdgcn_s_setprio(0); } while (0)
; #define PG8_WAIT_V(n) asm volatile("s_waitcnt vmcnt(" #n ")" ::: "memory")
; #define PG8_WAIT_L(n) asm volatile("s_waitcnt lgkmcnt(" #n ")" ::: "memory")
; #define PG8_BAR __builtin_amdgcn_s_barrier()
; #define PG8_SCHED __builtin_amdgcn_sched_barrier(0)
; template <class Epi>
; __device__ __forceinline__ void gemm_phase(LAS unsigned char* lds, const Gemm g, const StaticOrder& S, const Epi& E) {
;     ...
;             PG8_WAIT_V(8); PG8_WAIT_L(0); PG8_BAR; PG8_MMA(1, 0, At, B0); PG8_MMA(1, 1, At, B1); PG8_BAR; PG8_SCHED;
;             PG8_LDB(B0, 1, 0); PG8_LDB(B1, 1, 1); PG8_SCHED; PG8_LDA(At, 1, 0); PG8_STAGE(PG8_SA(0, 1), a2 + hsA, voffA);
;             PG8_WAIT_V(8); PG8_WAIT_L(0); PG8_BAR; PG8_MMA(0, 0, At, B0); PG8_MMA(0, 1, At, B1); PG8_BAR; PG8_SCHED;
	v_mfma_f32_16x16x32_bf16 v[52:55], v[180:183], v[196:199], v[52:55]
	v_mfma_f32_16x16x32_bf16 v[48:51], v[188:191], v[196:199], v[48:51]
	v_mfma_f32_16x16x32_bf16 v[36:39], v[180:183], v[204:207], v[36:39]
	v_mfma_f32_16x16x32_bf16 v[32:35], v[188:191], v[204:207], v[32:35]
	v_mfma_f32_16x16x32_bf16 v[20:23], v[180:183], v[212:215], v[20:23]
	v_mfma_f32_16x16x32_bf16 v[16:19], v[188:191], v[212:215], v[16:19]
	v_mfma_f32_16x16x32_bf16 v[4:7], v[180:183], v[220:223], v[4:7]
	v_mfma_f32_16x16x32_bf16 v[0:3], v[188:191], v[220:223], v[0:3]
	v_mfma_f32_16x16x32_bf16 v[52:55], v[184:187], v[200:203], v[52:55]
	v_mfma_f32_16x16x32_bf16 v[48:51], v[192:195], v[200:203], v[48:51]
	v_mfma_f32_16x16x32_bf16 v[36:39], v[184:187], v[208:211], v[36:39]
	v_mfma_f32_16x16x32_bf16 v[32:35], v[192:195], v[208:211], v[32:35]
	v_mfma_f32_16x16x32_bf16 v[20:23], v[184:187], v[216:219], v[20:23]
	v_mfma_f32_16x16x32_bf16 v[16:19], v[192:195], v[216:219], v[16:19]
	v_mfma_f32_16x16x32_bf16 v[4:7], v[184:187], v[224:227], v[4:7]
	v_mfma_f32_16x16x32_bf16 v[0:3], v[192:195], v[224:227], v[0:3]
	s_setprio 0
	s_barrier
	s_add_i32 s35, 0, 0x18000
	v_add_u32_e32 v163, s35, v155
	s_add_i32 s36, 0, 0x1c000
	ds_read_b128 v[144:147], v163
	ds_read_b128 v[148:151], v163 offset:1024
	ds_read_b128 v[164:167], v163 offset:2048
	ds_read_b128 v[168:171], v163 offset:3072
	v_add_u32_e32 v163, s36, v155
	ds_read_b128 v[180:183], v163
	ds_read_b128 v[184:187], v163 offset:1024
	ds_read_b128 v[188:191], v163 offset:2048
	ds_read_b128 v[192:195], v163 offset:3072
	s_add_u32 s12, s64, 0xb0000
	s_addc_u32 s13, s65, 0
	s_mov_b32 m0, s17
	ds_read_b128 v[196:199], v159 offset:32768
	ds_read_b128 v[200:203], v159 offset:33792
	ds_read_b128 v[204:207], v159 offset:34816
	ds_read_b128 v[208:211], v159 offset:35840
	ds_read_b128 v[212:215], v159 offset:36864
	ds_read_b128 v[216:219], v159 offset:37888
	ds_read_b128 v[220:223], v159 offset:38912
	ds_read_b128 v[224:227], v159 offset:39936
	global_load_lds_dwordx4 v128, s[12:13]
	s_mov_b32 m0, s18
	s_nop 0
	global_load_lds_dwordx4 v132, s[12:13]
	s_waitcnt vmcnt(8)
	s_waitcnt lgkmcnt(0)
	s_barrier
	s_setprio 1
	s_waitcnt lgkmcnt(0)
	v_mfma_f32_16x16x32_bf16 v[124:127], v[144:147], v[196:199], v[124:127]
	v_mfma_f32_16x16x32_bf16 v[120:123], v[164:167], v[196:199], v[120:123]
	v_mfma_f32_16x16x32_bf16 v[108:111], v[144:147], v[204:207], v[108:111]
	v_mfma_f32_16x16x32_bf16 v[104:107], v[164:167], v[204:207], v[104:107]
	v_mfma_f32_16x16x32_bf16 v[92:95], v[144:147], v[212:215], v[92:95]
	v_mfma_f32_16x16x32_bf16 v[88:91], v[164:167], v[212:215], v[88:91]
	v_mfma_f32_16x16x32_bf16 v[76:79], v[144:147], v[220:223], v[76:79]
	v_mfma_f32_16x16x32_bf16 v[72:75], v[164:167], v[220:223], v[72:75]
	v_mfma_f32_16x16x32_bf16 v[124:127], v[148:151], v[200:203], v[124:127]
	v_mfma_f32_16x16x32_bf16 v[120:123], v[168:171], v[200:203], v[120:123]
	v_mfma_f32_16x16x32_bf16 v[108:111], v[148:151], v[208:211], v[108:111]
	v_mfma_f32_16x16x32_bf16 v[104:107], v[168:171], v[208:211], v[104:107]
	v_mfma_f32_16x16x32_bf16 v[92:95], v[148:151], v[216:219], v[92:95]
	v_mfma_f32_16x16x32_bf16 v[88:91], v[168:171], v[216:219], v[88:91]
	v_mfma_f32_16x16x32_bf16 v[76:79], v[148:151], v[224:227], v[76:79]
	v_mfma_f32_16x16x32_bf16 v[72:75], v[168:171], v[224:227], v[72:75]


; #define PG8_STAGE(bufoff, gbase, voff) do { _Pragma("unroll") for (int _i = 0; _i < 2; ++_i) \
;         __builtin_amdgcn_global_load_lds((const unsigned*)((const char*)(gbase) + (voff)[_i]), (LAS unsigned*)(lds + (bufoff) + ldsw + _i * 8192), 16, 0, 0); } while (0)
; #define PG8_LDA(dst, b, h) do { _Pragma("unroll") for (int m = 0; m < 4; ++m) _Pragma("unroll") for (int k = 0; k < 2; ++k) dst[m][k] = *(const LAS bf16x8*)(lds + PG8_SA(b, h) + aoff + m * 2048 + k * 1024); } while (0)
; #define PG8_MMA(ai, bj, At, Bt) do { __builtin_amdgcn_s_setprio(1); _Pragma("unroll") for (int m = 0; m < 4; ++m) _Pragma("unroll") for (int n = 0; n < 2; ++n) _Pragma("unroll") for (int k = 0; k < 2; ++k) \
;         acc[ai][bj][m][n] = __builtin_amdgcn_mfma_f32_16x16x32_bf16(Bt[n][k], At[m][k], acc[ai][bj][m][n], 0, 0, 0); __builtin_amdgcn_s_setprio(0); } while (0)
; #define PG8_WAIT_V(n) asm volatile("s_waitcnt vmcnt(" #n ")" ::: "memory")
; #define PG8_WAIT_L(n) asm volatile("s_waitcnt lgkmcnt(" #n ")" ::: "memory")
; #define PG8_BAR __builtin_amdgcn_s_barrier()
; #define PG8_SCHED __builtin_amdgcn_sched_barrier(0)
; template <class Epi>
; __device__ __forceinline__ void gemm_phase(LAS unsigned char* lds, const Gemm g, const StaticOrder& S, const Epi& E) {
;     ...
;             PG8_WAIT_V(8); PG8_WAIT_L(0); PG8_BAR; PG8_MMA(0, 0, At, B0); PG8_MMA(0, 1, At, B1); PG8_BAR; PG8_SCHED;
;             PG8_LDA(At, 1, 1); PG8_STAGE(PG8_SB(1, 0), b3, voffB); PG8_STAGE(PG8_SB(1, 1), b3 + hsB, voffB); PG8_STAGE(PG8_SA(1, 0), a3, voffA);
;             PG8_WAIT_V(8); PG8_WAIT_L(0); PG8_BAR; PG8_MMA(1, 0, At, B0); PG8_MMA(1, 1, At, B1); PG8_BAR; PG8_SCHED;
	v_mfma_f32_16x16x32_bf16 v[116:119], v[180:183], v[196:199], v[116:119]
	v_mfma_f32_16x16x32_bf16 v[112:115], v[188:191], v[196:199], v[112:115]
	v_mfma_f32_16x16x32_bf16 v[100:103], v[180:183], v[204:207], v[100:103]
	v_mfma_f32_16x16x32_bf16 v[96:99], v[188:191], v[204:207], v[96:99]
	v_mfma_f32_16x16x32_bf16 v[84:87], v[180:183], v[212:215], v[84:87]
	v_mfma_f32_16x16x32_bf16 v[80:83], v[188:191], v[212:215], v[80:83]
	v_mfma_f32_16x16x32_bf16 v[68:71], v[180:183], v[220:223], v[68:71]
	v_mfma_f32_16x16x32_bf16 v[64:67], v[188:191], v[220:223], v[64:67]
	v_mfma_f32_16x16x32_bf16 v[116:119], v[184:187], v[200:203], v[116:119]
	v_mfma_f32_16x16x32_bf16 v[112:115], v[192:195], v[200:203], v[112:115]
	v_mfma_f32_16x16x32_bf16 v[100:103], v[184:187], v[208:211], v[100:103]
	v_mfma_f32_16x16x32_bf16 v[96:99], v[192:195], v[208:211], v[96:99]
	v_mfma_f32_16x16x32_bf16 v[84:87], v[184:187], v[216:219], v[84:87]
	v_mfma_f32_16x16x32_bf16 v[80:83], v[192:195], v[216:219], v[80:83]
	v_mfma_f32_16x16x32_bf16 v[68:71], v[184:187], v[224:227], v[68:71]
	v_mfma_f32_16x16x32_bf16 v[64:67], v[192:195], v[224:227], v[64:67]
	s_setprio 0
	s_barrier
	s_add_u32 s98, s62, 0x80
	s_addc_u32 s99, s63, 0
	s_add_u32 s100, s64, 0x80
	s_addc_u32 s101, s65, 0
	s_add_i32 s12, s35, s4
	s_mov_b32 m0, s12
	ds_read_b128 v[196:199], v159 offset:49152
	ds_read_b128 v[200:203], v159 offset:50176
	ds_read_b128 v[204:207], v159 offset:51200
	ds_read_b128 v[208:211], v159 offset:52224
	ds_read_b128 v[212:215], v159 offset:53248
	ds_read_b128 v[216:219], v159 offset:54272
	ds_read_b128 v[220:223], v159 offset:55296
	ds_read_b128 v[224:227], v159 offset:56320
	global_load_lds_dwordx4 v130, s[98:99]
	s_add_i32 m0, s12, 0x2000
	s_add_u32 s12, s62, 0xb0080
	s_addc_u32 s13, s63, 0
	s_add_i32 s35, s36, s4
	global_load_lds_dwordx4 v134, s[98:99]
	s_mov_b32 m0, s35
	s_nop 0
	global_load_lds_dwordx4 v130, s[12:13]
	s_add_i32 m0, s35, 0x2000
	s_nop 0
	global_load_lds_dwordx4 v134, s[12:13]
	s_mov_b32 m0, s22
	s_nop 0
	global_load_lds_dwordx4 v128, s[100:101]
	s_mov_b32 m0, s23
	s_nop 0
	global_load_lds_dwordx4 v132, s[100:101]
	s_waitcnt vmcnt(8)
	s_waitcnt lgkmcnt(0)
	s_barrier
	s_setprio 1
	s_waitcnt lgkmcnt(0)
	v_mfma_f32_16x16x32_bf16 v[60:63], v[144:147], v[196:199], v[60:63]
	v_mfma_f32_16x16x32_bf16 v[56:59], v[164:167], v[196:199], v[56:59]
	v_mfma_f32_16x16x32_bf16 v[44:47], v[144:147], v[204:207], v[44:47]
	v_mfma_f32_16x16x32_bf16 v[40:43], v[164:167], v[204:207], v[40:43]
	v_mfma_f32_16x16x32_bf16 v[28:31], v[144:147], v[212:215], v[28:31]
	v_mfma_f32_16x16x32_bf16 v[24:27], v[164:167], v[212:215], v[24:27]
	v_mfma_f32_16x16x32_bf16 v[12:15], v[144:147], v[220:223], v[12:15]
	v_mfma_f32_16x16x32_bf16 v[8:11], v[164:167], v[220:223], v[8:11]
	v_mfma_f32_16x16x32_bf16 v[60:63], v[148:151], v[200:203], v[60:63]
	v_mfma_f32_16x16x32_bf16 v[56:59], v[168:171], v[200:203], v[56:59]
	v_mfma_f32_16x16x32_bf16 v[44:47], v[148:151], v[208:211], v[44:47]
	v_mfma_f32_16x16x32_bf16 v[40:43], v[168:171], v[208:211], v[40:43]
	v_mfma_f32_16x16x32_bf16 v[28:31], v[148:151], v[216:219], v[28:31]
	v_mfma_f32_16x16x32_bf16 v[24:27], v[168:171], v[216:219], v[24:27]
	v_mfma_f32_16x16x32_bf16 v[12:15], v[148:151], v[224:227], v[12:15]
	v_mfma_f32_16x16x32_bf16 v[8:11], v[168:171], v[224:227], v[8:11]


; #define PG8_MMA(ai, bj, At, Bt) do { __builtin_amdgcn_s_setprio(1); _Pragma("unroll") for (int m = 0; m < 4; ++m) _Pragma("unroll") for (int n = 0; n < 2; ++n) _Pragma("unroll") for (int k = 0; k < 2; ++k) \
;         acc[ai][bj][m][n] = __builtin_amdgcn_mfma_f32_16x16x32_bf16(Bt[n][k], At[m][k], acc[ai][bj][m][n], 0, 0, 0); __builtin_amdgcn_s_setprio(0); } while (0)
; #define PG8_WAIT_V(n) asm volatile("s_waitcnt vmcnt(" #n ")" ::: "memory")
; #define PG8_WAIT_L(n) asm volatile("s_waitcnt lgkmcnt(" #n ")" ::: "memory")
; #define PG8_BAR __builtin_amdgcn_s_barrier()
; #define PG8_SCHED __builtin_amdgcn_sched_barrier(0)
; template <class Epi>
; __device__ __forceinline__ void gemm_phase(LAS unsigned char* lds, const Gemm g, const StaticOrder& S, const Epi& E) {
;     ...
;         for (int t = 0; t < nt; t += 2) {
;     ...
;             PG8_WAIT_V(8); PG8_WAIT_L(0); PG8_BAR; PG8_MMA(1, 0, At, B0); PG8_MMA(1, 1, At, B1); PG8_BAR; PG8_SCHED;
;         }
	v_mfma_f32_16x16x32_bf16 v[52:55], v[180:183], v[196:199], v[52:55]
	v_mfma_f32_16x16x32_bf16 v[48:51], v[188:191], v[196:199], v[48:51]
	v_mfma_f32_16x16x32_bf16 v[36:39], v[180:183], v[204:207], v[36:39]
	v_mfma_f32_16x16x32_bf16 v[32:35], v[188:191], v[204:207], v[32:35]
	v_mfma_f32_16x16x32_bf16 v[20:23], v[180:183], v[212:215], v[20:23]
	v_mfma_f32_16x16x32_bf16 v[16:19], v[188:191], v[212:215], v[16:19]
	v_mfma_f32_16x16x32_bf16 v[4:7], v[180:183], v[220:223], v[4:7]
	v_mfma_f32_16x16x32_bf16 v[0:3], v[188:191], v[220:223], v[0:3]
	v_mfma_f32_16x16x32_bf16 v[52:55], v[184:187], v[200:203], v[52:55]
	v_mfma_f32_16x16x32_bf16 v[48:51], v[192:195], v[200:203], v[48:51]
	v_mfma_f32_16x16x32_bf16 v[36:39], v[184:187], v[208:211], v[36:39]
	v_mfma_f32_16x16x32_bf16 v[32:35], v[192:195], v[208:211], v[32:35]
	v_mfma_f32_16x16x32_bf16 v[20:23], v[184:187], v[216:219], v[20:23]
	v_mfma_f32_16x16x32_bf16 v[16:19], v[192:195], v[216:219], v[16:19]
	v_mfma_f32_16x16x32_bf16 v[4:7], v[184:187], v[224:227], v[4:7]
	v_mfma_f32_16x16x32_bf16 v[0:3], v[192:195], v[224:227], v[0:3]
	s_setprio 0
	s_barrier
	s_add_i32 s34, s34, 2
	s_add_u32 s6, s6, 0x100
	s_addc_u32 s7, s7, 0
	s_cmp_gt_u32 s34, 41
	s_mov_b64 s[12:13], s[60:61]
	s_cbranch_scc0 .LBB0_296
	s_and_b64 vcc, exec, s[42:43]
	s_cbranch_vccz .LBB0_299
	s_barrier

; #define PG8_STAGE(bufoff, gbase, voff) do { _Pragma("unroll") for (int _i = 0; _i < 2; ++_i) \
;         __builtin_amdgcn_global_load_lds((const unsigned*)((const char*)(gbase) + (voff)[_i]), (LAS unsigned*)(lds + (bufoff) + ldsw + _i * 8192), 16, 0, 0); } while (0)
; #define PG8_LDA(dst, b, h) do { _Pragma("unroll") for (int m = 0; m < 4; ++m) _Pragma("unroll") for (int k = 0; k < 2; ++k) dst[m][k] = *(const LAS bf16x8*)(lds + PG8_SA(b, h) + aoff + m * 2048 + k * 1024); } while (0)
; #define PG8_LDB(dst, b, h) do { _Pragma("unroll") for (int n = 0; n < 2; ++n) _Pragma("unroll") for (int k = 0; k < 2; ++k) dst[n][k] = *(const LAS bf16x8*)(lds + PG8_SB(b, h) + boff + n * 2048 + k * 1024); } while (0)
; #define PG8_MMA(ai, bj, At, Bt) do { __builtin_amdgcn_s_setprio(1); _Pragma("unroll") for (int m = 0; m < 4; ++m) _Pragma("unroll") for (int n = 0; n < 2; ++n) _Pragma("unroll") for (int k = 0; k < 2; ++k) \
;         acc[ai][bj][m][n] = __builtin_amdgcn_mfma_f32_16x16x32_bf16(Bt[n][k], At[m][k], acc[ai][bj][m][n], 0, 0, 0); __builtin_amdgcn_s_setprio(0); } while (0)
; #define PG8_WAIT_V(n) asm volatile("s_waitcnt vmcnt(" #n ")" ::: "memory")
; #define PG8_WAIT_L(n) asm volatile("s_waitcnt lgkmcnt(" #n ")" ::: "memory")
; #define PG8_BAR __builtin_amdgcn_s_barrier()
; #define PG8_SCHED __builtin_amdgcn_sched_barrier(0)
; template <class Epi>
; __device__ __forceinline__ void gemm_phase(LAS unsigned char* lds, const Gemm g, const StaticOrder& S, const Epi& E) {
;     ...
;             PG8_LDB(B0, 0, 0); PG8_LDB(B1, 0, 1); PG8_SCHED; PG8_LDA(At, 0, 0); PG8_STAGE(PG8_SA(1, 1), a1 + hsA, voffA);
;             PG8_WAIT_V(8); PG8_WAIT_L(0); PG8_BAR; PG8_MMA(0, 0, At, B0); PG8_MMA(0, 1, At, B1); PG8_BAR; PG8_SCHED;
.LBB0_414:
	ds_read_b128 v[152:155], v167
	ds_read_b128 v[156:159], v167 offset:1024
	ds_read_b128 v[162:165], v167 offset:2048
	ds_read_b128 v[180:183], v167 offset:3072
	ds_read_b128 v[184:187], v168
	ds_read_b128 v[188:191], v168 offset:1024
	ds_read_b128 v[192:195], v168 offset:2048
	ds_read_b128 v[196:199], v168 offset:3072
	s_add_u32 s12, s10, 0xfffc0080
	s_addc_u32 s13, s11, -1
	s_cmp_eq_u32 s17, 12
	s_cselect_b32 s87, s0, s13
	s_cselect_b32 s86, s2, s12
	s_cselect_b32 s13, s3, s15
	s_cselect_b32 s12, s6, s7
	s_add_i32 m0, s5, 0xc000
	ds_read_b128 v[200:203], v169
	ds_read_b128 v[204:207], v169 offset:1024
	ds_read_b128 v[208:211], v169 offset:2048
	ds_read_b128 v[212:215], v169 offset:3072
	ds_read_b128 v[216:219], v169 offset:4096
	ds_read_b128 v[220:223], v169 offset:5120
	ds_read_b128 v[224:227], v169 offset:6144
	ds_read_b128 v[228:231], v169 offset:7168
	global_load_lds_dwordx4 v144, s[10:11]
	s_add_i32 m0, s5, 0xe000
	s_nop 0
	global_load_lds_dwordx4 v146, s[10:11]
	s_waitcnt vmcnt(8)
	s_waitcnt lgkmcnt(0)
	s_barrier
	s_setprio 1
	s_waitcnt lgkmcnt(0)
	v_mfma_f32_16x16x32_bf16 v[124:127], v[152:155], v[200:203], v[124:127]
	v_mfma_f32_16x16x32_bf16 v[120:123], v[162:165], v[200:203], v[120:123]
	v_mfma_f32_16x16x32_bf16 v[108:111], v[152:155], v[208:211], v[108:111]
	v_mfma_f32_16x16x32_bf16 v[104:107], v[162:165], v[208:211], v[104:107]
	v_mfma_f32_16x16x32_bf16 v[92:95], v[152:155], v[216:219], v[92:95]
	v_mfma_f32_16x16x32_bf16 v[88:91], v[162:165], v[216:219], v[88:91]
	v_mfma_f32_16x16x32_bf16 v[76:79], v[152:155], v[224:227], v[76:79]
	v_mfma_f32_16x16x32_bf16 v[72:75], v[162:165], v[224:227], v[72:75]
	v_mfma_f32_16x16x32_bf16 v[124:127], v[156:159], v[204:207], v[124:127]
	v_mfma_f32_16x16x32_bf16 v[120:123], v[180:183], v[204:207], v[120:123]
	v_mfma_f32_16x16x32_bf16 v[108:111], v[156:159], v[212:215], v[108:111]
	v_mfma_f32_16x16x32_bf16 v[104:107], v[180:183], v[212:215], v[104:107]
	v_mfma_f32_16x16x32_bf16 v[92:95], v[156:159], v[220:223], v[92:95]
	v_mfma_f32_16x16x32_bf16 v[88:91], v[180:183], v[220:223], v[88:91]
	v_mfma_f32_16x16x32_bf16 v[76:79], v[156:159], v[228:231], v[76:79]
	v_mfma_f32_16x16x32_bf16 v[72:75], v[180:183], v[228:231], v[72:75]


; #define PG8_STAGE(bufoff, gbase, voff) do { _Pragma("unroll") for (int _i = 0; _i < 2; ++_i) \
;         __builtin_amdgcn_global_load_lds((const unsigned*)((const char*)(gbase) + (voff)[_i]), (LAS unsigned*)(lds + (bufoff) + ldsw + _i * 8192), 16, 0, 0); } while (0)
; #define PG8_LDA(dst, b, h) do { _Pragma("unroll") for (int m = 0; m < 4; ++m) _Pragma("unroll") for (int k = 0; k < 2; ++k) dst[m][k] = *(const LAS bf16x8*)(lds + PG8_SA(b, h) + aoff + m * 2048 + k * 1024); } while (0)
; #define PG8_MMA(ai, bj, At, Bt) do { __builtin_amdgcn_s_setprio(1); _Pragma("unroll") for (int m = 0; m < 4; ++m) _Pragma("unroll") for (int n = 0; n < 2; ++n) _Pragma("unroll") for (int k = 0; k < 2; ++k) \
;         acc[ai][bj][m][n] = __builtin_amdgcn_mfma_f32_16x16x32_bf16(Bt[n][k], At[m][k], acc[ai][bj][m][n], 0, 0, 0); __builtin_amdgcn_s_setprio(0); } while (0)
; #define PG8_WAIT_V(n) asm volatile("s_waitcnt vmcnt(" #n ")" ::: "memory")
; #define PG8_WAIT_L(n) asm volatile("s_waitcnt lgkmcnt(" #n ")" ::: "memory")
; #define PG8_BAR __builtin_amdgcn_s_barrier()
; #define PG8_SCHED __builtin_amdgcn_sched_barrier(0)
; template <class Epi>
; __device__ __forceinline__ void gemm_phase(LAS unsigned char* lds, const Gemm g, const StaticOrder& S, const Epi& E) {
;     ...
;             PG8_WAIT_V(8); PG8_WAIT_L(0); PG8_BAR; PG8_MMA(0, 0, At, B0); PG8_MMA(0, 1, At, B1); PG8_BAR; PG8_SCHED;
;             PG8_LDA(At, 0, 1); PG8_STAGE(PG8_SB(0, 0), b2, voffB); PG8_STAGE(PG8_SB(0, 1), b2 + hsB, voffB); PG8_STAGE(PG8_SA(0, 0), a2, voffA);
;             PG8_WAIT_V(8); PG8_WAIT_L(0); PG8_BAR; PG8_MMA(1, 0, At, B0); PG8_MMA(1, 1, At, B1); PG8_BAR; PG8_SCHED;
	v_mfma_f32_16x16x32_bf16 v[116:119], v[184:187], v[200:203], v[116:119]
	v_mfma_f32_16x16x32_bf16 v[112:115], v[192:195], v[200:203], v[112:115]
	v_mfma_f32_16x16x32_bf16 v[100:103], v[184:187], v[208:211], v[100:103]
	v_mfma_f32_16x16x32_bf16 v[96:99], v[192:195], v[208:211], v[96:99]
	v_mfma_f32_16x16x32_bf16 v[84:87], v[184:187], v[216:219], v[84:87]
	v_mfma_f32_16x16x32_bf16 v[80:83], v[192:195], v[216:219], v[80:83]
	v_mfma_f32_16x16x32_bf16 v[68:71], v[184:187], v[224:227], v[68:71]
	v_mfma_f32_16x16x32_bf16 v[64:67], v[192:195], v[224:227], v[64:67]
	v_mfma_f32_16x16x32_bf16 v[116:119], v[188:191], v[204:207], v[116:119]
	v_mfma_f32_16x16x32_bf16 v[112:115], v[196:199], v[204:207], v[112:115]
	v_mfma_f32_16x16x32_bf16 v[100:103], v[188:191], v[212:215], v[100:103]
	v_mfma_f32_16x16x32_bf16 v[96:99], v[196:199], v[212:215], v[96:99]
	v_mfma_f32_16x16x32_bf16 v[84:87], v[188:191], v[220:223], v[84:87]
	v_mfma_f32_16x16x32_bf16 v[80:83], v[196:199], v[220:223], v[80:83]
	v_mfma_f32_16x16x32_bf16 v[68:71], v[188:191], v[228:231], v[68:71]
	v_mfma_f32_16x16x32_bf16 v[64:67], v[196:199], v[228:231], v[64:67]
	s_setprio 0
	s_barrier
	s_add_i32 s19, s65, s4
	s_mov_b32 m0, s19
	ds_read_b128 v[200:203], v169 offset:16384
	ds_read_b128 v[204:207], v169 offset:17408
	ds_read_b128 v[208:211], v169 offset:18432
	ds_read_b128 v[212:215], v169 offset:19456
	ds_read_b128 v[216:219], v169 offset:20480
	ds_read_b128 v[220:223], v169 offset:21504
	ds_read_b128 v[224:227], v169 offset:22528
	ds_read_b128 v[228:231], v169 offset:23552
	global_load_lds_dwordx4 v130, s[12:13]
	s_add_i32 m0, s19, 0x2000
	s_add_u32 s24, s12, 0x40000
	s_addc_u32 s25, s13, 0
	s_add_i32 s19, s76, s4
	global_load_lds_dwordx4 v134, s[12:13]
	s_mov_b32 m0, s19
	s_nop 0
	global_load_lds_dwordx4 v130, s[24:25]
	s_add_i32 m0, s19, 0x2000
	s_nop 0
	global_load_lds_dwordx4 v134, s[24:25]
	s_mov_b32 m0, s5
	s_nop 0
	global_load_lds_dwordx4 v128, s[86:87]
	s_mov_b32 m0, s62
	s_nop 0
	global_load_lds_dwordx4 v132, s[86:87]
	s_waitcnt vmcnt(8)
	s_waitcnt lgkmcnt(0)
	s_barrier
	s_setprio 1
	s_waitcnt lgkmcnt(0)
	v_mfma_f32_16x16x32_bf16 v[60:63], v[152:155], v[200:203], v[60:63]
	v_mfma_f32_16x16x32_bf16 v[56:59], v[162:165], v[200:203], v[56:59]
	v_mfma_f32_16x16x32_bf16 v[44:47], v[152:155], v[208:211], v[44:47]
	v_mfma_f32_16x16x32_bf16 v[40:43], v[162:165], v[208:211], v[40:43]
	v_mfma_f32_16x16x32_bf16 v[28:31], v[152:155], v[216:219], v[28:31]
	v_mfma_f32_16x16x32_bf16 v[24:27], v[162:165], v[216:219], v[24:27]
	v_mfma_f32_16x16x32_bf16 v[12:15], v[152:155], v[224:227], v[12:15]
	v_mfma_f32_16x16x32_bf16 v[8:11], v[162:165], v[224:227], v[8:11]
	v_mfma_f32_16x16x32_bf16 v[60:63], v[156:159], v[204:207], v[60:63]
	v_mfma_f32_16x16x32_bf16 v[56:59], v[180:183], v[204:207], v[56:59]
	v_mfma_f32_16x16x32_bf16 v[44:47], v[156:159], v[212:215], v[44:47]
	v_mfma_f32_16x16x32_bf16 v[40:43], v[180:183], v[212:215], v[40:43]
	v_mfma_f32_16x16x32_bf16 v[28:31], v[156:159], v[220:223], v[28:31]
	v_mfma_f32_16x16x32_bf16 v[24:27], v[180:183], v[220:223], v[24:27]
	v_mfma_f32_16x16x32_bf16 v[12:15], v[156:159], v[228:231], v[12:15]
	v_mfma_f32_16x16x32_bf16 v[8:11], v[180:183], v[228:231], v[8:11]


; #define PG8_STAGE(bufoff, gbase, voff) do { _Pragma("unroll") for (int _i = 0; _i < 2; ++_i) \
;         __builtin_amdgcn_global_load_lds((const unsigned*)((const char*)(gbase) + (voff)[_i]), (LAS unsigned*)(lds + (bufoff) + ldsw + _i * 8192), 16, 0, 0); } while (0)
; #define PG8_LDA(dst, b, h) do { _Pragma("unroll") for (int m = 0; m < 4; ++m) _Pragma("unroll") for (int k = 0; k < 2; ++k) dst[m][k] = *(const LAS bf16x8*)(lds + PG8_SA(b, h) + aoff + m * 2048 + k * 1024); } while (0)
; #define PG8_LDB(dst, b, h) do { _Pragma("unroll") for (int n = 0; n < 2; ++n) _Pragma("unroll") for (int k = 0; k < 2; ++k) dst[n][k] = *(const LAS bf16x8*)(lds + PG8_SB(b, h) + boff + n * 2048 + k * 1024); } while (0)
; #define PG8_MMA(ai, bj, At, Bt) do { __builtin_amdgcn_s_setprio(1); _Pragma("unroll") for (int m = 0; m < 4; ++m) _Pragma("unroll") for (int n = 0; n < 2; ++n) _Pragma("unroll") for (int k = 0; k < 2; ++k) \
;         acc[ai][bj][m][n] = __builtin_amdgcn_mfma_f32_16x16x32_bf16(Bt[n][k], At[m][k], acc[ai][bj][m][n], 0, 0, 0); __builtin_amdgcn_s_setprio(0); } while (0)
; #define PG8_WAIT_V(n) asm volatile("s_waitcnt vmcnt(" #n ")" ::: "memory")
; #define PG8_WAIT_L(n) asm volatile("s_waitcnt lgkmcnt(" #n ")" ::: "memory")
; #define PG8_BAR __builtin_amdgcn_s_barrier()
; #define PG8_SCHED __builtin_amdgcn_sched_barrier(0)
; template <class Epi>
; __device__ __forceinline__ void gemm_phase(LAS unsigned char* lds, const Gemm g, const StaticOrder& S, const Epi& E) {
;     ...
;             PG8_WAIT_V(8); PG8_WAIT_L(0); PG8_BAR; PG8_MMA(1, 0, At, B0); PG8_MMA(1, 1, At, B1); PG8_BAR; PG8_SCHED;
;             PG8_LDB(B0, 1, 0); PG8_LDB(B1, 1, 1); PG8_SCHED; PG8_LDA(At, 1, 0); PG8_STAGE(PG8_SA(0, 1), a2 + hsA, voffA);
;             PG8_WAIT_V(8); PG8_WAIT_L(0); PG8_BAR; PG8_MMA(0, 0, At, B0); PG8_MMA(0, 1, At, B1); PG8_BAR; PG8_SCHED;
	v_mfma_f32_16x16x32_bf16 v[52:55], v[184:187], v[200:203], v[52:55]
	v_mfma_f32_16x16x32_bf16 v[48:51], v[192:195], v[200:203], v[48:51]
	v_mfma_f32_16x16x32_bf16 v[36:39], v[184:187], v[208:211], v[36:39]
	v_mfma_f32_16x16x32_bf16 v[32:35], v[192:195], v[208:211], v[32:35]
	v_mfma_f32_16x16x32_bf16 v[20:23], v[184:187], v[216:219], v[20:23]
	v_mfma_f32_16x16x32_bf16 v[16:19], v[192:195], v[216:219], v[16:19]
	v_mfma_f32_16x16x32_bf16 v[4:7], v[184:187], v[224:227], v[4:7]
	v_mfma_f32_16x16x32_bf16 v[0:3], v[192:195], v[224:227], v[0:3]
	v_mfma_f32_16x16x32_bf16 v[52:55], v[188:191], v[204:207], v[52:55]
	v_mfma_f32_16x16x32_bf16 v[48:51], v[196:199], v[204:207], v[48:51]
	v_mfma_f32_16x16x32_bf16 v[36:39], v[188:191], v[212:215], v[36:39]
	v_mfma_f32_16x16x32_bf16 v[32:35], v[196:199], v[212:215], v[32:35]
	v_mfma_f32_16x16x32_bf16 v[20:23], v[188:191], v[220:223], v[20:23]
	v_mfma_f32_16x16x32_bf16 v[16:19], v[196:199], v[220:223], v[16:19]
	v_mfma_f32_16x16x32_bf16 v[4:7], v[188:191], v[228:231], v[4:7]
	v_mfma_f32_16x16x32_bf16 v[0:3], v[196:199], v[228:231], v[0:3]
	s_setprio 0
	s_barrier
	s_add_i32 s19, 0, 0x18000
	v_add_u32_e32 v136, s19, v166
	s_add_i32 s22, 0, 0x1c000
	ds_read_b128 v[152:155], v136
	ds_read_b128 v[156:159], v136 offset:1024
	ds_read_b128 v[162:165], v136 offset:2048
	ds_read_b128 v[180:183], v136 offset:3072
	v_add_u32_e32 v136, s22, v166
	ds_read_b128 v[184:187], v136
	ds_read_b128 v[188:191], v136 offset:1024
	ds_read_b128 v[192:195], v136 offset:2048
	ds_read_b128 v[196:199], v136 offset:3072
	s_add_u32 s24, s86, 0x40000
	s_addc_u32 s25, s87, 0
	s_mov_b32 m0, s63
	ds_read_b128 v[200:203], v169 offset:32768
	ds_read_b128 v[204:207], v169 offset:33792
	ds_read_b128 v[208:211], v169 offset:34816
	ds_read_b128 v[212:215], v169 offset:35840
	ds_read_b128 v[216:219], v169 offset:36864
	ds_read_b128 v[220:223], v169 offset:37888
	ds_read_b128 v[224:227], v169 offset:38912
	ds_read_b128 v[228:231], v169 offset:39936
	global_load_lds_dwordx4 v128, s[24:25]
	s_mov_b32 m0, s74
	s_nop 0
	global_load_lds_dwordx4 v132, s[24:25]
	s_waitcnt vmcnt(8)
	s_waitcnt lgkmcnt(0)
	s_barrier
	s_setprio 1
	s_waitcnt lgkmcnt(0)
	v_mfma_f32_16x16x32_bf16 v[124:127], v[152:155], v[200:203], v[124:127]
	v_mfma_f32_16x16x32_bf16 v[120:123], v[162:165], v[200:203], v[120:123]
	v_mfma_f32_16x16x32_bf16 v[108:111], v[152:155], v[208:211], v[108:111]
	v_mfma_f32_16x16x32_bf16 v[104:107], v[162:165], v[208:211], v[104:107]
	v_mfma_f32_16x16x32_bf16 v[92:95], v[152:155], v[216:219], v[92:95]
	v_mfma_f32_16x16x32_bf16 v[88:91], v[162:165], v[216:219], v[88:91]
	v_mfma_f32_16x16x32_bf16 v[76:79], v[152:155], v[224:227], v[76:79]
	v_mfma_f32_16x16x32_bf16 v[72:75], v[162:165], v[224:227], v[72:75]
	v_mfma_f32_16x16x32_bf16 v[124:127], v[156:159], v[204:207], v[124:127]
	v_mfma_f32_16x16x32_bf16 v[120:123], v[180:183], v[204:207], v[120:123]
	v_mfma_f32_16x16x32_bf16 v[108:111], v[156:159], v[212:215], v[108:111]
	v_mfma_f32_16x16x32_bf16 v[104:107], v[180:183], v[212:215], v[104:107]
	v_mfma_f32_16x16x32_bf16 v[92:95], v[156:159], v[220:223], v[92:95]
	v_mfma_f32_16x16x32_bf16 v[88:91], v[180:183], v[220:223], v[88:91]
	v_mfma_f32_16x16x32_bf16 v[76:79], v[156:159], v[228:231], v[76:79]
	v_mfma_f32_16x16x32_bf16 v[72:75], v[180:183], v[228:231], v[72:75]


; #define PG8_STAGE(bufoff, gbase, voff) do { _Pragma("unroll") for (int _i = 0; _i < 2; ++_i) \
;         __builtin_amdgcn_global_load_lds((const unsigned*)((const char*)(gbase) + (voff)[_i]), (LAS unsigned*)(lds + (bufoff) + ldsw + _i * 8192), 16, 0, 0); } while (0)
; #define PG8_LDA(dst, b, h) do { _Pragma("unroll") for (int m = 0; m < 4; ++m) _Pragma("unroll") for (int k = 0; k < 2; ++k) dst[m][k] = *(const LAS bf16x8*)(lds + PG8_SA(b, h) + aoff + m * 2048 + k * 1024); } while (0)
; #define PG8_MMA(ai, bj, At, Bt) do { __builtin_amdgcn_s_setprio(1); _Pragma("unroll") for (int m = 0; m < 4; ++m) _Pragma("unroll") for (int n = 0; n < 2; ++n) _Pragma("unroll") for (int k = 0; k < 2; ++k) \
;         acc[ai][bj][m][n] = __builtin_amdgcn_mfma_f32_16x16x32_bf16(Bt[n][k], At[m][k], acc[ai][bj][m][n], 0, 0, 0); __builtin_amdgcn_s_setprio(0); } while (0)
; #define PG8_WAIT_V(n) asm volatile("s_waitcnt vmcnt(" #n ")" ::: "memory")
; #define PG8_WAIT_L(n) asm volatile("s_waitcnt lgkmcnt(" #n ")" ::: "memory")
; #define PG8_BAR __builtin_amdgcn_s_barrier()
; #define PG8_SCHED __builtin_amdgcn_sched_barrier(0)
; template <class Epi>
; __device__ __forceinline__ void gemm_phase(LAS unsigned char* lds, const Gemm g, const StaticOrder& S, const Epi& E) {
;     ...
;             PG8_WAIT_V(8); PG8_WAIT_L(0); PG8_BAR; PG8_MMA(0, 0, At, B0); PG8_MMA(0, 1, At, B1); PG8_BAR; PG8_SCHED;
;             PG8_LDA(At, 1, 1); PG8_STAGE(PG8_SB(1, 0), b3, voffB); PG8_STAGE(PG8_SB(1, 1), b3 + hsB, voffB); PG8_STAGE(PG8_SA(1, 0), a3, voffA);
;             PG8_WAIT_V(8); PG8_WAIT_L(0); PG8_BAR; PG8_MMA(1, 0, At, B0); PG8_MMA(1, 1, At, B1); PG8_BAR; PG8_SCHED;
	v_mfma_f32_16x16x32_bf16 v[116:119], v[184:187], v[200:203], v[116:119]
	v_mfma_f32_16x16x32_bf16 v[112:115], v[192:195], v[200:203], v[112:115]
	v_mfma_f32_16x16x32_bf16 v[100:103], v[184:187], v[208:211], v[100:103]
	v_mfma_f32_16x16x32_bf16 v[96:99], v[192:195], v[208:211], v[96:99]
	v_mfma_f32_16x16x32_bf16 v[84:87], v[184:187], v[216:219], v[84:87]
	v_mfma_f32_16x16x32_bf16 v[80:83], v[192:195], v[216:219], v[80:83]
	v_mfma_f32_16x16x32_bf16 v[68:71], v[184:187], v[224:227], v[68:71]
	v_mfma_f32_16x16x32_bf16 v[64:67], v[192:195], v[224:227], v[64:67]
	v_mfma_f32_16x16x32_bf16 v[116:119], v[188:191], v[204:207], v[116:119]
	v_mfma_f32_16x16x32_bf16 v[112:115], v[196:199], v[204:207], v[112:115]
	v_mfma_f32_16x16x32_bf16 v[100:103], v[188:191], v[212:215], v[100:103]
	v_mfma_f32_16x16x32_bf16 v[96:99], v[196:199], v[212:215], v[96:99]
	v_mfma_f32_16x16x32_bf16 v[84:87], v[188:191], v[220:223], v[84:87]
	v_mfma_f32_16x16x32_bf16 v[80:83], v[196:199], v[220:223], v[80:83]
	v_mfma_f32_16x16x32_bf16 v[68:71], v[188:191], v[228:231], v[68:71]
	v_mfma_f32_16x16x32_bf16 v[64:67], v[196:199], v[228:231], v[64:67]
	s_setprio 0
	s_barrier
	s_add_u32 s98, s12, 0x80
	s_addc_u32 s99, s13, 0
	s_add_u32 s100, s86, 0x80
	s_addc_u32 s101, s87, 0
	s_add_i32 s19, s19, s4
	s_mov_b32 m0, s19
	ds_read_b128 v[200:203], v169 offset:49152
	ds_read_b128 v[204:207], v169 offset:50176
	ds_read_b128 v[208:211], v169 offset:51200
	ds_read_b128 v[212:215], v169 offset:52224
	ds_read_b128 v[216:219], v169 offset:53248
	ds_read_b128 v[220:223], v169 offset:54272
	ds_read_b128 v[224:227], v169 offset:55296
	ds_read_b128 v[228:231], v169 offset:56320
	global_load_lds_dwordx4 v130, s[98:99]
	s_add_i32 m0, s19, 0x2000
	s_add_u32 s12, s12, 0x40080
	s_addc_u32 s13, s13, 0
	s_add_i32 s19, s22, s4
	global_load_lds_dwordx4 v134, s[98:99]
	s_mov_b32 m0, s19
	s_nop 0
	global_load_lds_dwordx4 v130, s[12:13]
	s_add_i32 m0, s19, 0x2000
	s_nop 0
	global_load_lds_dwordx4 v134, s[12:13]
	s_mov_b32 m0, s16
	s_nop 0
	global_load_lds_dwordx4 v128, s[100:101]
	s_mov_b32 m0, s33
	s_nop 0
	global_load_lds_dwordx4 v132, s[100:101]
	s_waitcnt vmcnt(8)
	s_waitcnt lgkmcnt(0)
	s_barrier
	s_setprio 1
	s_waitcnt lgkmcnt(0)
	v_mfma_f32_16x16x32_bf16 v[60:63], v[152:155], v[200:203], v[60:63]
	v_mfma_f32_16x16x32_bf16 v[56:59], v[162:165], v[200:203], v[56:59]
	v_mfma_f32_16x16x32_bf16 v[44:47], v[152:155], v[208:211], v[44:47]
	v_mfma_f32_16x16x32_bf16 v[40:43], v[162:165], v[208:211], v[40:43]
	v_mfma_f32_16x16x32_bf16 v[28:31], v[152:155], v[216:219], v[28:31]
	v_mfma_f32_16x16x32_bf16 v[24:27], v[162:165], v[216:219], v[24:27]
	v_mfma_f32_16x16x32_bf16 v[12:15], v[152:155], v[224:227], v[12:15]
	v_mfma_f32_16x16x32_bf16 v[8:11], v[162:165], v[224:227], v[8:11]
	v_mfma_f32_16x16x32_bf16 v[60:63], v[156:159], v[204:207], v[60:63]
	v_mfma_f32_16x16x32_bf16 v[56:59], v[180:183], v[204:207], v[56:59]
	v_mfma_f32_16x16x32_bf16 v[44:47], v[156:159], v[212:215], v[44:47]
	v_mfma_f32_16x16x32_bf16 v[40:43], v[180:183], v[212:215], v[40:43]
	v_mfma_f32_16x16x32_bf16 v[28:31], v[156:159], v[220:223], v[28:31]
	v_mfma_f32_16x16x32_bf16 v[24:27], v[180:183], v[220:223], v[24:27]
	v_mfma_f32_16x16x32_bf16 v[12:15], v[156:159], v[228:231], v[12:15]
	v_mfma_f32_16x16x32_bf16 v[8:11], v[180:183], v[228:231], v[8:11]


; #define PG8_MMA(ai, bj, At, Bt) do { __builtin_amdgcn_s_setprio(1); _Pragma("unroll") for (int m = 0; m < 4; ++m) _Pragma("unroll") for (int n = 0; n < 2; ++n) _Pragma("unroll") for (int k = 0; k < 2; ++k) \
;         acc[ai][bj][m][n] = __builtin_amdgcn_mfma_f32_16x16x32_bf16(Bt[n][k], At[m][k], acc[ai][bj][m][n], 0, 0, 0); __builtin_amdgcn_s_setprio(0); } while (0)
; #define PG8_WAIT_V(n) asm volatile("s_waitcnt vmcnt(" #n ")" ::: "memory")
; #define PG8_WAIT_L(n) asm volatile("s_waitcnt lgkmcnt(" #n ")" ::: "memory")
; #define PG8_BAR __builtin_amdgcn_s_barrier()
; #define PG8_SCHED __builtin_amdgcn_sched_barrier(0)
; template <class Epi>
; __device__ __forceinline__ void gemm_phase(LAS unsigned char* lds, const Gemm g, const StaticOrder& S, const Epi& E) {
;     ...
;         for (int t = 0; t < nt; t += 2) {
;     ...
;             PG8_WAIT_V(8); PG8_WAIT_L(0); PG8_BAR; PG8_MMA(1, 0, At, B0); PG8_MMA(1, 1, At, B1); PG8_BAR; PG8_SCHED;
;         }
	v_mfma_f32_16x16x32_bf16 v[52:55], v[184:187], v[200:203], v[52:55]
	v_mfma_f32_16x16x32_bf16 v[48:51], v[192:195], v[200:203], v[48:51]
	v_mfma_f32_16x16x32_bf16 v[36:39], v[184:187], v[208:211], v[36:39]
	v_mfma_f32_16x16x32_bf16 v[32:35], v[192:195], v[208:211], v[32:35]
	v_mfma_f32_16x16x32_bf16 v[20:23], v[184:187], v[216:219], v[20:23]
	v_mfma_f32_16x16x32_bf16 v[16:19], v[192:195], v[216:219], v[16:19]
	v_mfma_f32_16x16x32_bf16 v[4:7], v[184:187], v[224:227], v[4:7]
	v_mfma_f32_16x16x32_bf16 v[0:3], v[192:195], v[224:227], v[0:3]
	v_mfma_f32_16x16x32_bf16 v[52:55], v[188:191], v[204:207], v[52:55]
	v_mfma_f32_16x16x32_bf16 v[48:51], v[196:199], v[204:207], v[48:51]
	v_mfma_f32_16x16x32_bf16 v[36:39], v[188:191], v[212:215], v[36:39]
	v_mfma_f32_16x16x32_bf16 v[32:35], v[196:199], v[212:215], v[32:35]
	v_mfma_f32_16x16x32_bf16 v[20:23], v[188:191], v[220:223], v[20:23]
	v_mfma_f32_16x16x32_bf16 v[16:19], v[196:199], v[220:223], v[16:19]
	v_mfma_f32_16x16x32_bf16 v[4:7], v[188:191], v[228:231], v[4:7]
	v_mfma_f32_16x16x32_bf16 v[0:3], v[196:199], v[228:231], v[0:3]
	s_setprio 0
	s_barrier
	s_add_i32 s17, s17, 2
	s_add_u32 s10, s10, 0x100
	s_addc_u32 s11, s11, 0
	s_add_u32 s7, s7, 0x100
	s_addc_u32 s15, s15, 0
	s_cmp_gt_u32 s17, 13
	s_cbranch_scc0 .LBB0_414
	s_and_b64 vcc, exec, s[58:59]
	s_cbranch_vccz .LBB0_417
	s_barrier

; #define PG8_STAGE(bufoff, gbase, voff) do { _Pragma("unroll") for (int _i = 0; _i < 2; ++_i) \
;         __builtin_amdgcn_global_load_lds((const unsigned*)((const char*)(gbase) + (voff)[_i]), (LAS unsigned*)(lds + (bufoff) + ldsw + _i * 8192), 16, 0, 0); } while (0)
; #define PG8_LDA(dst, b, h) do { _Pragma("unroll") for (int m = 0; m < 4; ++m) _Pragma("unroll") for (int k = 0; k < 2; ++k) dst[m][k] = *(const LAS bf16x8*)(lds + PG8_SA(b, h) + aoff + m * 2048 + k * 1024); } while (0)
; #define PG8_LDB(dst, b, h) do { _Pragma("unroll") for (int n = 0; n < 2; ++n) _Pragma("unroll") for (int k = 0; k < 2; ++k) dst[n][k] = *(const LAS bf16x8*)(lds + PG8_SB(b, h) + boff + n * 2048 + k * 1024); } while (0)
; #define PG8_MMA(ai, bj, At, Bt) do { __builtin_amdgcn_s_setprio(1); _Pragma("unroll") for (int m = 0; m < 4; ++m) _Pragma("unroll") for (int n = 0; n < 2; ++n) _Pragma("unroll") for (int k = 0; k < 2; ++k) \
;         acc[ai][bj][m][n] = __builtin_amdgcn_mfma_f32_16x16x32_bf16(Bt[n][k], At[m][k], acc[ai][bj][m][n], 0, 0, 0); __builtin_amdgcn_s_setprio(0); } while (0)
; #define PG8_WAIT_V(n) asm volatile("s_waitcnt vmcnt(" #n ")" ::: "memory")
; #define PG8_WAIT_L(n) asm volatile("s_waitcnt lgkmcnt(" #n ")" ::: "memory")
; #define PG8_BAR __builtin_amdgcn_s_barrier()
; #define PG8_SCHED __builtin_amdgcn_sched_barrier(0)
; template <class Epi>
; __device__ __forceinline__ void gemm_phase(LAS unsigned char* lds, const Gemm g, const StaticOrder& S, const Epi& E) {
;     ...
;             PG8_LDB(B0, 0, 0); PG8_LDB(B1, 0, 1); PG8_SCHED; PG8_LDA(At, 0, 0); PG8_STAGE(PG8_SA(1, 1), a1 + hsA, voffA);
;             PG8_WAIT_V(8); PG8_WAIT_L(0); PG8_BAR; PG8_MMA(0, 0, At, B0); PG8_MMA(0, 1, At, B1); PG8_BAR; PG8_SCHED;
.LBB0_720:
	ds_read_b128 v[128:131], v182
	ds_read_b128 v[132:135], v182 offset:1024
	ds_read_b128 v[136:139], v182 offset:2048
	ds_read_b128 v[140:143], v182 offset:3072
	ds_read_b128 v[166:169], v183
	ds_read_b128 v[188:191], v183 offset:1024
	ds_read_b128 v[192:195], v183 offset:2048
	ds_read_b128 v[196:199], v183 offset:3072
	s_add_u32 s39, s62, 0xfffc0080
	s_addc_u32 s40, s63, -1
	s_cmp_eq_u32 s38, 12
	s_cselect_b32 s67, s6, s40
	s_cselect_b32 s66, s7, s39
	s_cselect_b32 s65, s15, s37
	s_cselect_b32 s64, s35, s36
	s_add_i32 m0, s4, 0xc000
	ds_read_b128 v[200:203], v184
	ds_read_b128 v[204:207], v184 offset:1024
	ds_read_b128 v[208:211], v184 offset:2048
	ds_read_b128 v[212:215], v184 offset:3072
	ds_read_b128 v[216:219], v184 offset:4096
	ds_read_b128 v[220:223], v184 offset:5120
	ds_read_b128 v[224:227], v184 offset:6144
	ds_read_b128 v[228:231], v184 offset:7168
	global_load_lds_dwordx4 v156, s[62:63]
	s_add_i32 m0, s4, 0xe000
	s_nop 0
	global_load_lds_dwordx4 v158, s[62:63]
	s_waitcnt vmcnt(8)
	s_waitcnt lgkmcnt(0)
	s_barrier
	s_setprio 1
	s_waitcnt lgkmcnt(0)
	v_mfma_f32_16x16x32_bf16 v[124:127], v[128:131], v[200:203], v[124:127]
	v_mfma_f32_16x16x32_bf16 v[120:123], v[136:139], v[200:203], v[120:123]
	v_mfma_f32_16x16x32_bf16 v[108:111], v[128:131], v[208:211], v[108:111]
	v_mfma_f32_16x16x32_bf16 v[104:107], v[136:139], v[208:211], v[104:107]
	v_mfma_f32_16x16x32_bf16 v[92:95], v[128:131], v[216:219], v[92:95]
	v_mfma_f32_16x16x32_bf16 v[88:91], v[136:139], v[216:219], v[88:91]
	v_mfma_f32_16x16x32_bf16 v[76:79], v[128:131], v[224:227], v[76:79]
	v_mfma_f32_16x16x32_bf16 v[72:75], v[136:139], v[224:227], v[72:75]
	v_mfma_f32_16x16x32_bf16 v[124:127], v[132:135], v[204:207], v[124:127]
	v_mfma_f32_16x16x32_bf16 v[120:123], v[140:143], v[204:207], v[120:123]
	v_mfma_f32_16x16x32_bf16 v[108:111], v[132:135], v[212:215], v[108:111]
	v_mfma_f32_16x16x32_bf16 v[104:107], v[140:143], v[212:215], v[104:107]
	v_mfma_f32_16x16x32_bf16 v[92:95], v[132:135], v[220:223], v[92:95]
	v_mfma_f32_16x16x32_bf16 v[88:91], v[140:143], v[220:223], v[88:91]
	v_mfma_f32_16x16x32_bf16 v[76:79], v[132:135], v[228:231], v[76:79]
	v_mfma_f32_16x16x32_bf16 v[72:75], v[140:143], v[228:231], v[72:75]


; #define PG8_STAGE(bufoff, gbase, voff) do { _Pragma("unroll") for (int _i = 0; _i < 2; ++_i) \
;         __builtin_amdgcn_global_load_lds((const unsigned*)((const char*)(gbase) + (voff)[_i]), (LAS unsigned*)(lds + (bufoff) + ldsw + _i * 8192), 16, 0, 0); } while (0)
; #define PG8_LDA(dst, b, h) do { _Pragma("unroll") for (int m = 0; m < 4; ++m) _Pragma("unroll") for (int k = 0; k < 2; ++k) dst[m][k] = *(const LAS bf16x8*)(lds + PG8_SA(b, h) + aoff + m * 2048 + k * 1024); } while (0)
; #define PG8_MMA(ai, bj, At, Bt) do { __builtin_amdgcn_s_setprio(1); _Pragma("unroll") for (int m = 0; m < 4; ++m) _Pragma("unroll") for (int n = 0; n < 2; ++n) _Pragma("unroll") for (int k = 0; k < 2; ++k) \
;         acc[ai][bj][m][n] = __builtin_amdgcn_mfma_f32_16x16x32_bf16(Bt[n][k], At[m][k], acc[ai][bj][m][n], 0, 0, 0); __builtin_amdgcn_s_setprio(0); } while (0)
; #define PG8_WAIT_V(n) asm volatile("s_waitcnt vmcnt(" #n ")" ::: "memory")
; #define PG8_WAIT_L(n) asm volatile("s_waitcnt lgkmcnt(" #n ")" ::: "memory")
; #define PG8_BAR __builtin_amdgcn_s_barrier()
; #define PG8_SCHED __builtin_amdgcn_sched_barrier(0)
; template <class Epi>
; __device__ __forceinline__ void gemm_phase(LAS unsigned char* lds, const Gemm g, const StaticOrder& S, const Epi& E) {
;     ...
;             PG8_WAIT_V(8); PG8_WAIT_L(0); PG8_BAR; PG8_MMA(0, 0, At, B0); PG8_MMA(0, 1, At, B1); PG8_BAR; PG8_SCHED;
;             PG8_LDA(At, 0, 1); PG8_STAGE(PG8_SB(0, 0), b2, voffB); PG8_STAGE(PG8_SB(0, 1), b2 + hsB, voffB); PG8_STAGE(PG8_SA(0, 0), a2, voffA);
;             PG8_WAIT_V(8); PG8_WAIT_L(0); PG8_BAR; PG8_MMA(1, 0, At, B0); PG8_MMA(1, 1, At, B1); PG8_BAR; PG8_SCHED;
	v_mfma_f32_16x16x32_bf16 v[116:119], v[166:169], v[200:203], v[116:119]
	v_mfma_f32_16x16x32_bf16 v[112:115], v[192:195], v[200:203], v[112:115]
	v_mfma_f32_16x16x32_bf16 v[100:103], v[166:169], v[208:211], v[100:103]
	v_mfma_f32_16x16x32_bf16 v[96:99], v[192:195], v[208:211], v[96:99]
	v_mfma_f32_16x16x32_bf16 v[84:87], v[166:169], v[216:219], v[84:87]
	v_mfma_f32_16x16x32_bf16 v[80:83], v[192:195], v[216:219], v[80:83]
	v_mfma_f32_16x16x32_bf16 v[68:71], v[166:169], v[224:227], v[68:71]
	v_mfma_f32_16x16x32_bf16 v[64:67], v[192:195], v[224:227], v[64:67]
	v_mfma_f32_16x16x32_bf16 v[116:119], v[188:191], v[204:207], v[116:119]
	v_mfma_f32_16x16x32_bf16 v[112:115], v[196:199], v[204:207], v[112:115]
	v_mfma_f32_16x16x32_bf16 v[100:103], v[188:191], v[212:215], v[100:103]
	v_mfma_f32_16x16x32_bf16 v[96:99], v[196:199], v[212:215], v[96:99]
	v_mfma_f32_16x16x32_bf16 v[84:87], v[188:191], v[220:223], v[84:87]
	v_mfma_f32_16x16x32_bf16 v[80:83], v[196:199], v[220:223], v[80:83]
	v_mfma_f32_16x16x32_bf16 v[68:71], v[188:191], v[228:231], v[68:71]
	v_mfma_f32_16x16x32_bf16 v[64:67], v[196:199], v[228:231], v[64:67]
	s_setprio 0
	s_barrier
	s_add_i32 s39, s27, s3
	s_mov_b32 m0, s39
	ds_read_b128 v[200:203], v184 offset:16384
	ds_read_b128 v[204:207], v184 offset:17408
	ds_read_b128 v[208:211], v184 offset:18432
	ds_read_b128 v[212:215], v184 offset:19456
	ds_read_b128 v[216:219], v184 offset:20480
	ds_read_b128 v[220:223], v184 offset:21504
	ds_read_b128 v[224:227], v184 offset:22528
	ds_read_b128 v[228:231], v184 offset:23552
	global_load_lds_dwordx4 v146, s[64:65]
	s_add_i32 m0, s39, 0x2000
	s_add_u32 s40, s64, 0x40000
	s_addc_u32 s41, s65, 0
	s_add_i32 s39, s28, s3
	global_load_lds_dwordx4 v150, s[64:65]
	s_mov_b32 m0, s39
	s_nop 0
	global_load_lds_dwordx4 v146, s[40:41]
	s_add_i32 m0, s39, 0x2000
	s_nop 0
	global_load_lds_dwordx4 v150, s[40:41]
	s_mov_b32 m0, s4
	s_nop 0
	global_load_lds_dwordx4 v144, s[66:67]
	s_mov_b32 m0, s5
	s_nop 0
	global_load_lds_dwordx4 v148, s[66:67]
	s_waitcnt vmcnt(8)
	s_waitcnt lgkmcnt(0)
	s_barrier
	s_setprio 1
	s_waitcnt lgkmcnt(0)
	v_mfma_f32_16x16x32_bf16 v[60:63], v[128:131], v[200:203], v[60:63]
	v_mfma_f32_16x16x32_bf16 v[56:59], v[136:139], v[200:203], v[56:59]
	v_mfma_f32_16x16x32_bf16 v[44:47], v[128:131], v[208:211], v[44:47]
	v_mfma_f32_16x16x32_bf16 v[40:43], v[136:139], v[208:211], v[40:43]
	v_mfma_f32_16x16x32_bf16 v[28:31], v[128:131], v[216:219], v[28:31]
	v_mfma_f32_16x16x32_bf16 v[24:27], v[136:139], v[216:219], v[24:27]
	v_mfma_f32_16x16x32_bf16 v[12:15], v[128:131], v[224:227], v[12:15]
	v_mfma_f32_16x16x32_bf16 v[8:11], v[136:139], v[224:227], v[8:11]
	v_mfma_f32_16x16x32_bf16 v[60:63], v[132:135], v[204:207], v[60:63]
	v_mfma_f32_16x16x32_bf16 v[56:59], v[140:143], v[204:207], v[56:59]
	v_mfma_f32_16x16x32_bf16 v[44:47], v[132:135], v[212:215], v[44:47]
	v_mfma_f32_16x16x32_bf16 v[40:43], v[140:143], v[212:215], v[40:43]
	v_mfma_f32_16x16x32_bf16 v[28:31], v[132:135], v[220:223], v[28:31]
	v_mfma_f32_16x16x32_bf16 v[24:27], v[140:143], v[220:223], v[24:27]
	v_mfma_f32_16x16x32_bf16 v[12:15], v[132:135], v[228:231], v[12:15]
	v_mfma_f32_16x16x32_bf16 v[8:11], v[140:143], v[228:231], v[8:11]


; #define PG8_STAGE(bufoff, gbase, voff) do { _Pragma("unroll") for (int _i = 0; _i < 2; ++_i) \
;         __builtin_amdgcn_global_load_lds((const unsigned*)((const char*)(gbase) + (voff)[_i]), (LAS unsigned*)(lds + (bufoff) + ldsw + _i * 8192), 16, 0, 0); } while (0)
; #define PG8_LDA(dst, b, h) do { _Pragma("unroll") for (int m = 0; m < 4; ++m) _Pragma("unroll") for (int k = 0; k < 2; ++k) dst[m][k] = *(const LAS bf16x8*)(lds + PG8_SA(b, h) + aoff + m * 2048 + k * 1024); } while (0)
; #define PG8_LDB(dst, b, h) do { _Pragma("unroll") for (int n = 0; n < 2; ++n) _Pragma("unroll") for (int k = 0; k < 2; ++k) dst[n][k] = *(const LAS bf16x8*)(lds + PG8_SB(b, h) + boff + n * 2048 + k * 1024); } while (0)
; #define PG8_MMA(ai, bj, At, Bt) do { __builtin_amdgcn_s_setprio(1); _Pragma("unroll") for (int m = 0; m < 4; ++m) _Pragma("unroll") for (int n = 0; n < 2; ++n) _Pragma("unroll") for (int k = 0; k < 2; ++k) \
;         acc[ai][bj][m][n] = __builtin_amdgcn_mfma_f32_16x16x32_bf16(Bt[n][k], At[m][k], acc[ai][bj][m][n], 0, 0, 0); __builtin_amdgcn_s_setprio(0); } while (0)
; #define PG8_WAIT_V(n) asm volatile("s_waitcnt vmcnt(" #n ")" ::: "memory")
; #define PG8_WAIT_L(n) asm volatile("s_waitcnt lgkmcnt(" #n ")" ::: "memory")
; #define PG8_BAR __builtin_amdgcn_s_barrier()
; #define PG8_SCHED __builtin_amdgcn_sched_barrier(0)
; template <class Epi>
; __device__ __forceinline__ void gemm_phase(LAS unsigned char* lds, const Gemm g, const StaticOrder& S, const Epi& E) {
;     ...
;             PG8_WAIT_V(8); PG8_WAIT_L(0); PG8_BAR; PG8_MMA(1, 0, At, B0); PG8_MMA(1, 1, At, B1); PG8_BAR; PG8_SCHED;
;             PG8_LDB(B0, 1, 0); PG8_LDB(B1, 1, 1); PG8_SCHED; PG8_LDA(At, 1, 0); PG8_STAGE(PG8_SA(0, 1), a2 + hsA, voffA);
;             PG8_WAIT_V(8); PG8_WAIT_L(0); PG8_BAR; PG8_MMA(0, 0, At, B0); PG8_MMA(0, 1, At, B1); PG8_BAR; PG8_SCHED;
	v_mfma_f32_16x16x32_bf16 v[52:55], v[166:169], v[200:203], v[52:55]
	v_mfma_f32_16x16x32_bf16 v[48:51], v[192:195], v[200:203], v[48:51]
	v_mfma_f32_16x16x32_bf16 v[36:39], v[166:169], v[208:211], v[36:39]
	v_mfma_f32_16x16x32_bf16 v[32:35], v[192:195], v[208:211], v[32:35]
	v_mfma_f32_16x16x32_bf16 v[20:23], v[166:169], v[216:219], v[20:23]
	v_mfma_f32_16x16x32_bf16 v[16:19], v[192:195], v[216:219], v[16:19]
	v_mfma_f32_16x16x32_bf16 v[4:7], v[166:169], v[224:227], v[4:7]
	v_mfma_f32_16x16x32_bf16 v[0:3], v[192:195], v[224:227], v[0:3]
	v_mfma_f32_16x16x32_bf16 v[52:55], v[188:191], v[204:207], v[52:55]
	v_mfma_f32_16x16x32_bf16 v[48:51], v[196:199], v[204:207], v[48:51]
	v_mfma_f32_16x16x32_bf16 v[36:39], v[188:191], v[212:215], v[36:39]
	v_mfma_f32_16x16x32_bf16 v[32:35], v[196:199], v[212:215], v[32:35]
	v_mfma_f32_16x16x32_bf16 v[20:23], v[188:191], v[220:223], v[20:23]
	v_mfma_f32_16x16x32_bf16 v[16:19], v[196:199], v[220:223], v[16:19]
	v_mfma_f32_16x16x32_bf16 v[4:7], v[188:191], v[228:231], v[4:7]
	v_mfma_f32_16x16x32_bf16 v[0:3], v[196:199], v[228:231], v[0:3]
	s_setprio 0
	s_barrier
	s_add_i32 s39, 0, 0x18000
	s_add_i32 s42, 0, 0x1c000
	v_add_u32_e32 v140, s39, v173
	v_add_u32_e32 v152, s42, v173
	ds_read_b128 v[128:131], v140
	ds_read_b128 v[132:135], v140 offset:1024
	ds_read_b128 v[136:139], v140 offset:2048
	ds_read_b128 v[140:143], v140 offset:3072
	ds_read_b128 v[166:169], v152
	ds_read_b128 v[188:191], v152 offset:1024
	ds_read_b128 v[192:195], v152 offset:2048
	ds_read_b128 v[196:199], v152 offset:3072
	s_add_u32 s40, s66, 0x40000
	s_addc_u32 s41, s67, 0
	s_mov_b32 m0, s16
	ds_read_b128 v[200:203], v184 offset:32768
	ds_read_b128 v[204:207], v184 offset:33792
	ds_read_b128 v[208:211], v184 offset:34816
	ds_read_b128 v[212:215], v184 offset:35840
	ds_read_b128 v[216:219], v184 offset:36864
	ds_read_b128 v[220:223], v184 offset:37888
	ds_read_b128 v[224:227], v184 offset:38912
	ds_read_b128 v[228:231], v184 offset:39936
	global_load_lds_dwordx4 v144, s[40:41]
	s_mov_b32 m0, s17
	s_nop 0
	global_load_lds_dwordx4 v148, s[40:41]
	s_waitcnt vmcnt(8)
	s_waitcnt lgkmcnt(0)
	s_barrier
	s_setprio 1
	s_waitcnt lgkmcnt(0)
	v_mfma_f32_16x16x32_bf16 v[124:127], v[128:131], v[200:203], v[124:127]
	v_mfma_f32_16x16x32_bf16 v[120:123], v[136:139], v[200:203], v[120:123]
	v_mfma_f32_16x16x32_bf16 v[108:111], v[128:131], v[208:211], v[108:111]
	v_mfma_f32_16x16x32_bf16 v[104:107], v[136:139], v[208:211], v[104:107]
	v_mfma_f32_16x16x32_bf16 v[92:95], v[128:131], v[216:219], v[92:95]
	v_mfma_f32_16x16x32_bf16 v[88:91], v[136:139], v[216:219], v[88:91]
	v_mfma_f32_16x16x32_bf16 v[76:79], v[128:131], v[224:227], v[76:79]
	v_mfma_f32_16x16x32_bf16 v[72:75], v[136:139], v[224:227], v[72:75]
	v_mfma_f32_16x16x32_bf16 v[124:127], v[132:135], v[204:207], v[124:127]
	v_mfma_f32_16x16x32_bf16 v[120:123], v[140:143], v[204:207], v[120:123]
	v_mfma_f32_16x16x32_bf16 v[108:111], v[132:135], v[212:215], v[108:111]
	v_mfma_f32_16x16x32_bf16 v[104:107], v[140:143], v[212:215], v[104:107]
	v_mfma_f32_16x16x32_bf16 v[92:95], v[132:135], v[220:223], v[92:95]
	v_mfma_f32_16x16x32_bf16 v[88:91], v[140:143], v[220:223], v[88:91]
	v_mfma_f32_16x16x32_bf16 v[76:79], v[132:135], v[228:231], v[76:79]
	v_mfma_f32_16x16x32_bf16 v[72:75], v[140:143], v[228:231], v[72:75]


; #define PG8_STAGE(bufoff, gbase, voff) do { _Pragma("unroll") for (int _i = 0; _i < 2; ++_i) \
;         __builtin_amdgcn_global_load_lds((const unsigned*)((const char*)(gbase) + (voff)[_i]), (LAS unsigned*)(lds + (bufoff) + ldsw + _i * 8192), 16, 0, 0); } while (0)
; #define PG8_LDA(dst, b, h) do { _Pragma("unroll") for (int m = 0; m < 4; ++m) _Pragma("unroll") for (int k = 0; k < 2; ++k) dst[m][k] = *(const LAS bf16x8*)(lds + PG8_SA(b, h) + aoff + m * 2048 + k * 1024); } while (0)
; #define PG8_MMA(ai, bj, At, Bt) do { __builtin_amdgcn_s_setprio(1); _Pragma("unroll") for (int m = 0; m < 4; ++m) _Pragma("unroll") for (int n = 0; n < 2; ++n) _Pragma("unroll") for (int k = 0; k < 2; ++k) \
;         acc[ai][bj][m][n] = __builtin_amdgcn_mfma_f32_16x16x32_bf16(Bt[n][k], At[m][k], acc[ai][bj][m][n], 0, 0, 0); __builtin_amdgcn_s_setprio(0); } while (0)
; #define PG8_WAIT_V(n) asm volatile("s_waitcnt vmcnt(" #n ")" ::: "memory")
; #define PG8_WAIT_L(n) asm volatile("s_waitcnt lgkmcnt(" #n ")" ::: "memory")
; #define PG8_BAR __builtin_amdgcn_s_barrier()
; #define PG8_SCHED __builtin_amdgcn_sched_barrier(0)
; template <class Epi>
; __device__ __forceinline__ void gemm_phase(LAS unsigned char* lds, const Gemm g, const StaticOrder& S, const Epi& E) {
;     ...
;             PG8_WAIT_V(8); PG8_WAIT_L(0); PG8_BAR; PG8_MMA(0, 0, At, B0); PG8_MMA(0, 1, At, B1); PG8_BAR; PG8_SCHED;
;             PG8_LDA(At, 1, 1); PG8_STAGE(PG8_SB(1, 0), b3, voffB); PG8_STAGE(PG8_SB(1, 1), b3 + hsB, voffB); PG8_STAGE(PG8_SA(1, 0), a3, voffA);
;             PG8_WAIT_V(8); PG8_WAIT_L(0); PG8_BAR; PG8_MMA(1, 0, At, B0); PG8_MMA(1, 1, At, B1); PG8_BAR; PG8_SCHED;
	v_mfma_f32_16x16x32_bf16 v[116:119], v[166:169], v[200:203], v[116:119]
	v_mfma_f32_16x16x32_bf16 v[112:115], v[192:195], v[200:203], v[112:115]
	v_mfma_f32_16x16x32_bf16 v[100:103], v[166:169], v[208:211], v[100:103]
	v_mfma_f32_16x16x32_bf16 v[96:99], v[192:195], v[208:211], v[96:99]
	v_mfma_f32_16x16x32_bf16 v[84:87], v[166:169], v[216:219], v[84:87]
	v_mfma_f32_16x16x32_bf16 v[80:83], v[192:195], v[216:219], v[80:83]
	v_mfma_f32_16x16x32_bf16 v[68:71], v[166:169], v[224:227], v[68:71]
	v_mfma_f32_16x16x32_bf16 v[64:67], v[192:195], v[224:227], v[64:67]
	v_mfma_f32_16x16x32_bf16 v[116:119], v[188:191], v[204:207], v[116:119]
	v_mfma_f32_16x16x32_bf16 v[112:115], v[196:199], v[204:207], v[112:115]
	v_mfma_f32_16x16x32_bf16 v[100:103], v[188:191], v[212:215], v[100:103]
	v_mfma_f32_16x16x32_bf16 v[96:99], v[196:199], v[212:215], v[96:99]
	v_mfma_f32_16x16x32_bf16 v[84:87], v[188:191], v[220:223], v[84:87]
	v_mfma_f32_16x16x32_bf16 v[80:83], v[196:199], v[220:223], v[80:83]
	v_mfma_f32_16x16x32_bf16 v[68:71], v[188:191], v[228:231], v[68:71]
	v_mfma_f32_16x16x32_bf16 v[64:67], v[196:199], v[228:231], v[64:67]
	s_setprio 0
	s_barrier
	s_add_u32 s98, s64, 0x80
	s_addc_u32 s99, s65, 0
	s_add_u32 s100, s66, 0x80
	s_addc_u32 s101, s67, 0
	s_add_i32 s39, s39, s3
	s_mov_b32 m0, s39
	ds_read_b128 v[200:203], v184 offset:49152
	ds_read_b128 v[204:207], v184 offset:50176
	ds_read_b128 v[208:211], v184 offset:51200
	ds_read_b128 v[212:215], v184 offset:52224
	ds_read_b128 v[216:219], v184 offset:53248
	ds_read_b128 v[220:223], v184 offset:54272
	ds_read_b128 v[224:227], v184 offset:55296
	ds_read_b128 v[228:231], v184 offset:56320
	global_load_lds_dwordx4 v146, s[98:99]
	s_add_i32 m0, s39, 0x2000
	s_add_u32 s40, s64, 0x40080
	s_addc_u32 s41, s65, 0
	s_add_i32 s39, s42, s3
	global_load_lds_dwordx4 v150, s[98:99]
	s_mov_b32 m0, s39
	s_nop 0
	global_load_lds_dwordx4 v146, s[40:41]
	s_add_i32 m0, s39, 0x2000
	s_nop 0
	global_load_lds_dwordx4 v150, s[40:41]
	s_mov_b32 m0, s22
	s_nop 0
	global_load_lds_dwordx4 v144, s[100:101]
	s_mov_b32 m0, s23
	s_nop 0
	global_load_lds_dwordx4 v148, s[100:101]
	s_waitcnt vmcnt(8)
	s_waitcnt lgkmcnt(0)
	s_barrier
	s_setprio 1
	s_waitcnt lgkmcnt(0)
	v_mfma_f32_16x16x32_bf16 v[60:63], v[128:131], v[200:203], v[60:63]
	v_mfma_f32_16x16x32_bf16 v[56:59], v[136:139], v[200:203], v[56:59]
	v_mfma_f32_16x16x32_bf16 v[44:47], v[128:131], v[208:211], v[44:47]
	v_mfma_f32_16x16x32_bf16 v[40:43], v[136:139], v[208:211], v[40:43]
	v_mfma_f32_16x16x32_bf16 v[28:31], v[128:131], v[216:219], v[28:31]
	v_mfma_f32_16x16x32_bf16 v[24:27], v[136:139], v[216:219], v[24:27]
	v_mfma_f32_16x16x32_bf16 v[12:15], v[128:131], v[224:227], v[12:15]
	v_mfma_f32_16x16x32_bf16 v[8:11], v[136:139], v[224:227], v[8:11]
	v_mfma_f32_16x16x32_bf16 v[60:63], v[132:135], v[204:207], v[60:63]
	v_mfma_f32_16x16x32_bf16 v[56:59], v[140:143], v[204:207], v[56:59]
	v_mfma_f32_16x16x32_bf16 v[44:47], v[132:135], v[212:215], v[44:47]
	v_mfma_f32_16x16x32_bf16 v[40:43], v[140:143], v[212:215], v[40:43]
	v_mfma_f32_16x16x32_bf16 v[28:31], v[132:135], v[220:223], v[28:31]
	v_mfma_f32_16x16x32_bf16 v[24:27], v[140:143], v[220:223], v[24:27]
	v_mfma_f32_16x16x32_bf16 v[12:15], v[132:135], v[228:231], v[12:15]
	v_mfma_f32_16x16x32_bf16 v[8:11], v[140:143], v[228:231], v[8:11]


; #define PG8_MMA(ai, bj, At, Bt) do { __builtin_amdgcn_s_setprio(1); _Pragma("unroll") for (int m = 0; m < 4; ++m) _Pragma("unroll") for (int n = 0; n < 2; ++n) _Pragma("unroll") for (int k = 0; k < 2; ++k) \
;         acc[ai][bj][m][n] = __builtin_amdgcn_mfma_f32_16x16x32_bf16(Bt[n][k], At[m][k], acc[ai][bj][m][n], 0, 0, 0); __builtin_amdgcn_s_setprio(0); } while (0)
; #define PG8_WAIT_V(n) asm volatile("s_waitcnt vmcnt(" #n ")" ::: "memory")
; #define PG8_WAIT_L(n) asm volatile("s_waitcnt lgkmcnt(" #n ")" ::: "memory")
; #define PG8_BAR __builtin_amdgcn_s_barrier()
; #define PG8_SCHED __builtin_amdgcn_sched_barrier(0)
; template <class Epi>
; __device__ __forceinline__ void gemm_phase(LAS unsigned char* lds, const Gemm g, const StaticOrder& S, const Epi& E) {
;     ...
;         for (int t = 0; t < nt; t += 2) {
;     ...
;             PG8_WAIT_V(8); PG8_WAIT_L(0); PG8_BAR; PG8_MMA(1, 0, At, B0); PG8_MMA(1, 1, At, B1); PG8_BAR; PG8_SCHED;
;         }
	v_mfma_f32_16x16x32_bf16 v[52:55], v[166:169], v[200:203], v[52:55]
	v_mfma_f32_16x16x32_bf16 v[48:51], v[192:195], v[200:203], v[48:51]
	v_mfma_f32_16x16x32_bf16 v[36:39], v[166:169], v[208:211], v[36:39]
	v_mfma_f32_16x16x32_bf16 v[32:35], v[192:195], v[208:211], v[32:35]
	v_mfma_f32_16x16x32_bf16 v[20:23], v[166:169], v[216:219], v[20:23]
	v_mfma_f32_16x16x32_bf16 v[16:19], v[192:195], v[216:219], v[16:19]
	v_mfma_f32_16x16x32_bf16 v[4:7], v[166:169], v[224:227], v[4:7]
	v_mfma_f32_16x16x32_bf16 v[0:3], v[192:195], v[224:227], v[0:3]
	v_mfma_f32_16x16x32_bf16 v[52:55], v[188:191], v[204:207], v[52:55]
	v_mfma_f32_16x16x32_bf16 v[48:51], v[196:199], v[204:207], v[48:51]
	v_mfma_f32_16x16x32_bf16 v[36:39], v[188:191], v[212:215], v[36:39]
	v_mfma_f32_16x16x32_bf16 v[32:35], v[196:199], v[212:215], v[32:35]
	v_mfma_f32_16x16x32_bf16 v[20:23], v[188:191], v[220:223], v[20:23]
	v_mfma_f32_16x16x32_bf16 v[16:19], v[196:199], v[220:223], v[16:19]
	v_mfma_f32_16x16x32_bf16 v[4:7], v[188:191], v[228:231], v[4:7]
	v_mfma_f32_16x16x32_bf16 v[0:3], v[196:199], v[228:231], v[0:3]
	s_setprio 0
	s_barrier
	s_add_i32 s38, s38, 2
	s_add_u32 s62, s62, 0x100
	s_addc_u32 s63, s63, 0
	s_add_u32 s36, s36, 0x100
	s_addc_u32 s37, s37, 0
	s_cmp_gt_u32 s38, 13
	s_cbranch_scc0 .LBB0_720
	s_and_b64 vcc, exec, s[12:13]
	s_cbranch_vccz .LBB0_723
	s_barrier

; #define PG8_STAGE(bufoff, gbase, voff) do { _Pragma("unroll") for (int _i = 0; _i < 2; ++_i) \
;         __builtin_amdgcn_global_load_lds((const unsigned*)((const char*)(gbase) + (voff)[_i]), (LAS unsigned*)(lds + (bufoff) + ldsw + _i * 8192), 16, 0, 0); } while (0)
; #define PG8_LDA(dst, b, h) do { _Pragma("unroll") for (int m = 0; m < 4; ++m) _Pragma("unroll") for (int k = 0; k < 2; ++k) dst[m][k] = *(const LAS bf16x8*)(lds + PG8_SA(b, h) + aoff + m * 2048 + k * 1024); } while (0)
; #define PG8_LDB(dst, b, h) do { _Pragma("unroll") for (int n = 0; n < 2; ++n) _Pragma("unroll") for (int k = 0; k < 2; ++k) dst[n][k] = *(const LAS bf16x8*)(lds + PG8_SB(b, h) + boff + n * 2048 + k * 1024); } while (0)
; #define PG8_MMA(ai, bj, At, Bt) do { __builtin_amdgcn_s_setprio(1); _Pragma("unroll") for (int m = 0; m < 4; ++m) _Pragma("unroll") for (int n = 0; n < 2; ++n) _Pragma("unroll") for (int k = 0; k < 2; ++k) \
;         acc[ai][bj][m][n] = __builtin_amdgcn_mfma_f32_16x16x32_bf16(Bt[n][k], At[m][k], acc[ai][bj][m][n], 0, 0, 0); __builtin_amdgcn_s_setprio(0); } while (0)
; #define PG8_WAIT_V(n) asm volatile("s_waitcnt vmcnt(" #n ")" ::: "memory")
; #define PG8_WAIT_L(n) asm volatile("s_waitcnt lgkmcnt(" #n ")" ::: "memory")
; #define PG8_BAR __builtin_amdgcn_s_barrier()
; #define PG8_SCHED __builtin_amdgcn_sched_barrier(0)
; template <class Epi>
; __device__ __forceinline__ void gemm_phase(LAS unsigned char* lds, const Gemm g, const StaticOrder& S, const Epi& E) {
;     ...
;         for (int t = 0; t < nt; t += 2) {
;             const bool last = (t == nt - 2);
;             if constexpr (Epi::HAS_MID) { if (t == nt1) E.mid(acc, cur, wr, wc, fr, fq); }
;             const char* a1 = cA + ((Epi::HAS_MID && t >= nt1) ? dA2 : 0) + (size_t)(t + 1) * kstep;
;             const char* a2 = last ? nA : cA + ((Epi::HAS_MID && t + 2 >= nt1) ? dA2 : 0) + (size_t)(t + 2) * kstep; const char* b2 = last ? nB : cB + ((Epi::HAS_MID && t + 2 >= nt1) ? dB2 : 0) + (size_t)(t + 2) * kstep;
;             const char* a3 = a2 + kstep; const char* b3 = b2 + kstep;
;             PG8_LDB(B0, 0, 0); PG8_LDB(B1, 0, 1); PG8_SCHED; PG8_LDA(At, 0, 0); PG8_STAGE(PG8_SA(1, 1), a1 + hsA, voffA);
;             PG8_WAIT_V(8); PG8_WAIT_L(0); PG8_BAR; PG8_MMA(0, 0, At, B0); PG8_MMA(0, 1, At, B1); PG8_BAR; PG8_SCHED;
.LBB0_1083:
	s_add_i32 s33, s33, 2
	s_add_u32 s0, s52, s54
	s_addc_u32 s1, s53, s55
	s_add_u32 s0, s0, 0x100
	v_add_u32_e32 v153, s74, v171
	s_addc_u32 s1, s1, 0
	ds_read_b128 v[128:131], v153
	ds_read_b128 v[132:135], v153 offset:1024
	ds_read_b128 v[164:167], v153 offset:2048
	ds_read_b128 v[184:187], v153 offset:3072
	v_add_u32_e32 v153, s75, v171
	s_cmp_gt_u32 s33, 13
	ds_read_b128 v[188:191], v153
	ds_read_b128 v[192:195], v153 offset:1024
	ds_read_b128 v[196:199], v153 offset:2048
	ds_read_b128 v[200:203], v153 offset:3072
	s_cselect_b32 s17, 0x1ff800, 0
	s_add_u32 s17, s17, s54
	s_addc_u32 s24, 0, s55
	s_add_u32 s17, s22, s17
	s_addc_u32 s24, s23, s24
	s_cmpk_eq_i32 s54, 0xf00
	s_cselect_b32 s59, s6, s1
	s_cselect_b32 s58, s7, s0
	s_cselect_b32 s57, s16, s24
	s_cselect_b32 s56, s18, s17
	v_lshl_add_u64 v[168:169], v[158:159], 0, s[54:55]
	s_add_i32 m0, s61, 0xc000
	ds_read_b128 v[204:207], v173
	ds_read_b128 v[208:211], v173 offset:1024
	ds_read_b128 v[212:215], v173 offset:2048
	ds_read_b128 v[216:219], v173 offset:3072
	ds_read_b128 v[220:223], v173 offset:4096
	ds_read_b128 v[224:227], v173 offset:5120
	ds_read_b128 v[228:231], v173 offset:6144
	ds_read_b128 v[232:235], v173 offset:7168
	global_load_lds_dwordx4 v[168:169], off
	v_lshl_add_u64 v[168:169], v[162:163], 0, s[54:55]
	s_add_i32 m0, s61, 0xe000
	s_nop 0
	global_load_lds_dwordx4 v[168:169], off
	s_waitcnt vmcnt(8)
	s_waitcnt lgkmcnt(0)
	s_barrier
	s_setprio 1
	s_waitcnt lgkmcnt(0)
	v_mfma_f32_16x16x32_bf16 v[124:127], v[128:131], v[204:207], v[124:127]
	v_mfma_f32_16x16x32_bf16 v[120:123], v[164:167], v[204:207], v[120:123]
	v_mfma_f32_16x16x32_bf16 v[108:111], v[128:131], v[212:215], v[108:111]
	v_mfma_f32_16x16x32_bf16 v[104:107], v[164:167], v[212:215], v[104:107]
	v_mfma_f32_16x16x32_bf16 v[92:95], v[128:131], v[220:223], v[92:95]
	v_mfma_f32_16x16x32_bf16 v[88:91], v[164:167], v[220:223], v[88:91]
	v_mfma_f32_16x16x32_bf16 v[76:79], v[128:131], v[228:231], v[76:79]
	v_mfma_f32_16x16x32_bf16 v[72:75], v[164:167], v[228:231], v[72:75]
	v_mfma_f32_16x16x32_bf16 v[124:127], v[132:135], v[208:211], v[124:127]
	v_mfma_f32_16x16x32_bf16 v[120:123], v[184:187], v[208:211], v[120:123]
	v_mfma_f32_16x16x32_bf16 v[108:111], v[132:135], v[216:219], v[108:111]
	v_mfma_f32_16x16x32_bf16 v[104:107], v[184:187], v[216:219], v[104:107]
	v_mfma_f32_16x16x32_bf16 v[92:95], v[132:135], v[224:227], v[92:95]
	v_mfma_f32_16x16x32_bf16 v[88:91], v[184:187], v[224:227], v[88:91]
	v_mfma_f32_16x16x32_bf16 v[76:79], v[132:135], v[232:235], v[76:79]
	v_mfma_f32_16x16x32_bf16 v[72:75], v[184:187], v[232:235], v[72:75]


; #define PG8_STAGE(bufoff, gbase, voff) do { _Pragma("unroll") for (int _i = 0; _i < 2; ++_i) \
;         __builtin_amdgcn_global_load_lds((const unsigned*)((const char*)(gbase) + (voff)[_i]), (LAS unsigned*)(lds + (bufoff) + ldsw + _i * 8192), 16, 0, 0); } while (0)
; #define PG8_LDA(dst, b, h) do { _Pragma("unroll") for (int m = 0; m < 4; ++m) _Pragma("unroll") for (int k = 0; k < 2; ++k) dst[m][k] = *(const LAS bf16x8*)(lds + PG8_SA(b, h) + aoff + m * 2048 + k * 1024); } while (0)
; #define PG8_MMA(ai, bj, At, Bt) do { __builtin_amdgcn_s_setprio(1); _Pragma("unroll") for (int m = 0; m < 4; ++m) _Pragma("unroll") for (int n = 0; n < 2; ++n) _Pragma("unroll") for (int k = 0; k < 2; ++k) \
;         acc[ai][bj][m][n] = __builtin_amdgcn_mfma_f32_16x16x32_bf16(Bt[n][k], At[m][k], acc[ai][bj][m][n], 0, 0, 0); __builtin_amdgcn_s_setprio(0); } while (0)
; #define PG8_WAIT_V(n) asm volatile("s_waitcnt vmcnt(" #n ")" ::: "memory")
; #define PG8_WAIT_L(n) asm volatile("s_waitcnt lgkmcnt(" #n ")" ::: "memory")
; #define PG8_BAR __builtin_amdgcn_s_barrier()
; #define PG8_SCHED __builtin_amdgcn_sched_barrier(0)
; template <class Epi>
; __device__ __forceinline__ void gemm_phase(LAS unsigned char* lds, const Gemm g, const StaticOrder& S, const Epi& E) {
;     ...
;             PG8_WAIT_V(8); PG8_WAIT_L(0); PG8_BAR; PG8_MMA(0, 0, At, B0); PG8_MMA(0, 1, At, B1); PG8_BAR; PG8_SCHED;
;             PG8_LDA(At, 0, 1); PG8_STAGE(PG8_SB(0, 0), b2, voffB); PG8_STAGE(PG8_SB(0, 1), b2 + hsB, voffB); PG8_STAGE(PG8_SA(0, 0), a2, voffA);
;             PG8_WAIT_V(8); PG8_WAIT_L(0); PG8_BAR; PG8_MMA(1, 0, At, B0); PG8_MMA(1, 1, At, B1); PG8_BAR; PG8_SCHED;
	v_mfma_f32_16x16x32_bf16 v[116:119], v[188:191], v[204:207], v[116:119]
	v_mfma_f32_16x16x32_bf16 v[112:115], v[196:199], v[204:207], v[112:115]
	v_mfma_f32_16x16x32_bf16 v[100:103], v[188:191], v[212:215], v[100:103]
	v_mfma_f32_16x16x32_bf16 v[96:99], v[196:199], v[212:215], v[96:99]
	v_mfma_f32_16x16x32_bf16 v[84:87], v[188:191], v[220:223], v[84:87]
	v_mfma_f32_16x16x32_bf16 v[80:83], v[196:199], v[220:223], v[80:83]
	v_mfma_f32_16x16x32_bf16 v[68:71], v[188:191], v[228:231], v[68:71]
	v_mfma_f32_16x16x32_bf16 v[64:67], v[196:199], v[228:231], v[64:67]
	v_mfma_f32_16x16x32_bf16 v[116:119], v[192:195], v[208:211], v[116:119]
	v_mfma_f32_16x16x32_bf16 v[112:115], v[200:203], v[208:211], v[112:115]
	v_mfma_f32_16x16x32_bf16 v[100:103], v[192:195], v[216:219], v[100:103]
	v_mfma_f32_16x16x32_bf16 v[96:99], v[200:203], v[216:219], v[96:99]
	v_mfma_f32_16x16x32_bf16 v[84:87], v[192:195], v[224:227], v[84:87]
	v_mfma_f32_16x16x32_bf16 v[80:83], v[200:203], v[224:227], v[80:83]
	v_mfma_f32_16x16x32_bf16 v[68:71], v[192:195], v[232:235], v[68:71]
	v_mfma_f32_16x16x32_bf16 v[64:67], v[200:203], v[232:235], v[64:67]
	s_setprio 0
	s_barrier
	s_add_i32 s0, s74, s60
	v_lshl_add_u64 v[168:169], s[56:57], 0, v[138:139]
	s_mov_b32 m0, s0
	ds_read_b128 v[204:207], v173 offset:16384
	ds_read_b128 v[208:211], v173 offset:17408
	ds_read_b128 v[212:215], v173 offset:18432
	ds_read_b128 v[216:219], v173 offset:19456
	ds_read_b128 v[220:223], v173 offset:20480
	ds_read_b128 v[224:227], v173 offset:21504
	ds_read_b128 v[228:231], v173 offset:22528
	ds_read_b128 v[232:235], v173 offset:23552
	global_load_lds_dwordx4 v[168:169], off
	s_add_i32 m0, s0, 0x2000
	s_add_u32 s0, s56, 0x40000
	v_lshl_add_u64 v[236:237], s[56:57], 0, v[142:143]
	s_addc_u32 s1, s57, 0
	s_add_i32 s17, s75, s60
	global_load_lds_dwordx4 v[236:237], off
	v_lshl_add_u64 v[238:239], s[0:1], 0, v[138:139]
	s_mov_b32 m0, s17
	v_lshl_add_u64 v[240:241], s[58:59], 0, v[140:141]
	global_load_lds_dwordx4 v[238:239], off
	v_lshl_add_u64 v[238:239], s[0:1], 0, v[142:143]
	s_add_i32 m0, s17, 0x2000
	s_nop 0
	global_load_lds_dwordx4 v[238:239], off
	v_lshl_add_u64 v[238:239], s[58:59], 0, v[136:137]
	s_mov_b32 m0, s61
	s_nop 0
	global_load_lds_dwordx4 v[238:239], off
	s_mov_b32 m0, s4
	s_nop 0
	global_load_lds_dwordx4 v[240:241], off
	s_waitcnt vmcnt(8)
	s_waitcnt lgkmcnt(0)
	s_barrier
	s_setprio 1
	s_waitcnt lgkmcnt(0)
	v_mfma_f32_16x16x32_bf16 v[60:63], v[128:131], v[204:207], v[60:63]
	v_mfma_f32_16x16x32_bf16 v[56:59], v[164:167], v[204:207], v[56:59]
	v_mfma_f32_16x16x32_bf16 v[44:47], v[128:131], v[212:215], v[44:47]
	v_mfma_f32_16x16x32_bf16 v[40:43], v[164:167], v[212:215], v[40:43]
	v_mfma_f32_16x16x32_bf16 v[28:31], v[128:131], v[220:223], v[28:31]
	v_mfma_f32_16x16x32_bf16 v[24:27], v[164:167], v[220:223], v[24:27]
	v_mfma_f32_16x16x32_bf16 v[12:15], v[128:131], v[228:231], v[12:15]
	v_mfma_f32_16x16x32_bf16 v[8:11], v[164:167], v[228:231], v[8:11]
	v_mfma_f32_16x16x32_bf16 v[60:63], v[132:135], v[208:211], v[60:63]
	v_mfma_f32_16x16x32_bf16 v[56:59], v[184:187], v[208:211], v[56:59]
	v_mfma_f32_16x16x32_bf16 v[44:47], v[132:135], v[216:219], v[44:47]
	v_mfma_f32_16x16x32_bf16 v[40:43], v[184:187], v[216:219], v[40:43]
	v_mfma_f32_16x16x32_bf16 v[28:31], v[132:135], v[224:227], v[28:31]
	v_mfma_f32_16x16x32_bf16 v[24:27], v[184:187], v[224:227], v[24:27]
	v_mfma_f32_16x16x32_bf16 v[12:15], v[132:135], v[232:235], v[12:15]
	v_mfma_f32_16x16x32_bf16 v[8:11], v[184:187], v[232:235], v[8:11]


; #define PG8_STAGE(bufoff, gbase, voff) do { _Pragma("unroll") for (int _i = 0; _i < 2; ++_i) \
;         __builtin_amdgcn_global_load_lds((const unsigned*)((const char*)(gbase) + (voff)[_i]), (LAS unsigned*)(lds + (bufoff) + ldsw + _i * 8192), 16, 0, 0); } while (0)
; #define PG8_LDA(dst, b, h) do { _Pragma("unroll") for (int m = 0; m < 4; ++m) _Pragma("unroll") for (int k = 0; k < 2; ++k) dst[m][k] = *(const LAS bf16x8*)(lds + PG8_SA(b, h) + aoff + m * 2048 + k * 1024); } while (0)
; #define PG8_LDB(dst, b, h) do { _Pragma("unroll") for (int n = 0; n < 2; ++n) _Pragma("unroll") for (int k = 0; k < 2; ++k) dst[n][k] = *(const LAS bf16x8*)(lds + PG8_SB(b, h) + boff + n * 2048 + k * 1024); } while (0)
; #define PG8_MMA(ai, bj, At, Bt) do { __builtin_amdgcn_s_setprio(1); _Pragma("unroll") for (int m = 0; m < 4; ++m) _Pragma("unroll") for (int n = 0; n < 2; ++n) _Pragma("unroll") for (int k = 0; k < 2; ++k) \
;         acc[ai][bj][m][n] = __builtin_amdgcn_mfma_f32_16x16x32_bf16(Bt[n][k], At[m][k], acc[ai][bj][m][n], 0, 0, 0); __builtin_amdgcn_s_setprio(0); } while (0)
; #define PG8_WAIT_V(n) asm volatile("s_waitcnt vmcnt(" #n ")" ::: "memory")
; #define PG8_WAIT_L(n) asm volatile("s_waitcnt lgkmcnt(" #n ")" ::: "memory")
; #define PG8_BAR __builtin_amdgcn_s_barrier()
; #define PG8_SCHED __builtin_amdgcn_sched_barrier(0)
; template <class Epi>
; __device__ __forceinline__ void gemm_phase(LAS unsigned char* lds, const Gemm g, const StaticOrder& S, const Epi& E) {
;     ...
;             PG8_WAIT_V(8); PG8_WAIT_L(0); PG8_BAR; PG8_MMA(1, 0, At, B0); PG8_MMA(1, 1, At, B1); PG8_BAR; PG8_SCHED;
;             PG8_LDB(B0, 1, 0); PG8_LDB(B1, 1, 1); PG8_SCHED; PG8_LDA(At, 1, 0); PG8_STAGE(PG8_SA(0, 1), a2 + hsA, voffA);
;             PG8_WAIT_V(8); PG8_WAIT_L(0); PG8_BAR; PG8_MMA(0, 0, At, B0); PG8_MMA(0, 1, At, B1); PG8_BAR; PG8_SCHED;
	v_mfma_f32_16x16x32_bf16 v[52:55], v[188:191], v[204:207], v[52:55]
	v_mfma_f32_16x16x32_bf16 v[48:51], v[196:199], v[204:207], v[48:51]
	v_mfma_f32_16x16x32_bf16 v[36:39], v[188:191], v[212:215], v[36:39]
	v_mfma_f32_16x16x32_bf16 v[32:35], v[196:199], v[212:215], v[32:35]
	v_mfma_f32_16x16x32_bf16 v[20:23], v[188:191], v[220:223], v[20:23]
	v_mfma_f32_16x16x32_bf16 v[16:19], v[196:199], v[220:223], v[16:19]
	v_mfma_f32_16x16x32_bf16 v[4:7], v[188:191], v[228:231], v[4:7]
	v_mfma_f32_16x16x32_bf16 v[0:3], v[196:199], v[228:231], v[0:3]
	v_mfma_f32_16x16x32_bf16 v[52:55], v[192:195], v[208:211], v[52:55]
	v_mfma_f32_16x16x32_bf16 v[48:51], v[200:203], v[208:211], v[48:51]
	v_mfma_f32_16x16x32_bf16 v[36:39], v[192:195], v[216:219], v[36:39]
	v_mfma_f32_16x16x32_bf16 v[32:35], v[200:203], v[216:219], v[32:35]
	v_mfma_f32_16x16x32_bf16 v[20:23], v[192:195], v[224:227], v[20:23]
	v_mfma_f32_16x16x32_bf16 v[16:19], v[200:203], v[224:227], v[16:19]
	v_mfma_f32_16x16x32_bf16 v[4:7], v[192:195], v[232:235], v[4:7]
	v_mfma_f32_16x16x32_bf16 v[0:3], v[200:203], v[232:235], v[0:3]
	s_setprio 0
	s_barrier
	s_add_i32 s17, 0, 0x18000
	v_add_u32_e32 v153, s17, v171
	s_add_i32 s24, 0, 0x1c000
	ds_read_b128 v[128:131], v153
	ds_read_b128 v[132:135], v153 offset:1024
	ds_read_b128 v[164:167], v153 offset:2048
	ds_read_b128 v[184:187], v153 offset:3072
	v_add_u32_e32 v153, s24, v171
	ds_read_b128 v[188:191], v153
	ds_read_b128 v[192:195], v153 offset:1024
	ds_read_b128 v[196:199], v153 offset:2048
	ds_read_b128 v[200:203], v153 offset:3072
	s_add_u32 s0, s58, 0x100000
	s_addc_u32 s1, s59, 0
	s_mov_b32 m0, s5
	v_lshl_add_u64 v[242:243], s[0:1], 0, v[136:137]
	ds_read_b128 v[204:207], v173 offset:32768
	ds_read_b128 v[208:211], v173 offset:33792
	ds_read_b128 v[212:215], v173 offset:34816
	ds_read_b128 v[216:219], v173 offset:35840
	ds_read_b128 v[220:223], v173 offset:36864
	ds_read_b128 v[224:227], v173 offset:37888
	ds_read_b128 v[228:231], v173 offset:38912
	ds_read_b128 v[232:235], v173 offset:39936
	global_load_lds_dwordx4 v[242:243], off
	v_lshl_add_u64 v[242:243], s[0:1], 0, v[140:141]
	s_mov_b32 m0, s62
	s_nop 0
	global_load_lds_dwordx4 v[242:243], off
	s_waitcnt vmcnt(8)
	s_waitcnt lgkmcnt(0)
	s_barrier
	s_setprio 1
	s_waitcnt lgkmcnt(0)
	v_mfma_f32_16x16x32_bf16 v[124:127], v[128:131], v[204:207], v[124:127]
	v_mfma_f32_16x16x32_bf16 v[120:123], v[164:167], v[204:207], v[120:123]
	v_mfma_f32_16x16x32_bf16 v[108:111], v[128:131], v[212:215], v[108:111]
	v_mfma_f32_16x16x32_bf16 v[104:107], v[164:167], v[212:215], v[104:107]
	v_mfma_f32_16x16x32_bf16 v[92:95], v[128:131], v[220:223], v[92:95]
	v_mfma_f32_16x16x32_bf16 v[88:91], v[164:167], v[220:223], v[88:91]
	v_mfma_f32_16x16x32_bf16 v[76:79], v[128:131], v[228:231], v[76:79]
	v_mfma_f32_16x16x32_bf16 v[72:75], v[164:167], v[228:231], v[72:75]
	v_mfma_f32_16x16x32_bf16 v[124:127], v[132:135], v[208:211], v[124:127]
	v_mfma_f32_16x16x32_bf16 v[120:123], v[184:187], v[208:211], v[120:123]
	v_mfma_f32_16x16x32_bf16 v[108:111], v[132:135], v[216:219], v[108:111]
	v_mfma_f32_16x16x32_bf16 v[104:107], v[184:187], v[216:219], v[104:107]
	v_mfma_f32_16x16x32_bf16 v[92:95], v[132:135], v[224:227], v[92:95]
	v_mfma_f32_16x16x32_bf16 v[88:91], v[184:187], v[224:227], v[88:91]
	v_mfma_f32_16x16x32_bf16 v[76:79], v[132:135], v[232:235], v[76:79]
	v_mfma_f32_16x16x32_bf16 v[72:75], v[184:187], v[232:235], v[72:75]


; #define PG8_STAGE(bufoff, gbase, voff) do { _Pragma("unroll") for (int _i = 0; _i < 2; ++_i) \
;         __builtin_amdgcn_global_load_lds((const unsigned*)((const char*)(gbase) + (voff)[_i]), (LAS unsigned*)(lds + (bufoff) + ldsw + _i * 8192), 16, 0, 0); } while (0)
; #define PG8_LDA(dst, b, h) do { _Pragma("unroll") for (int m = 0; m < 4; ++m) _Pragma("unroll") for (int k = 0; k < 2; ++k) dst[m][k] = *(const LAS bf16x8*)(lds + PG8_SA(b, h) + aoff + m * 2048 + k * 1024); } while (0)
; #define PG8_MMA(ai, bj, At, Bt) do { __builtin_amdgcn_s_setprio(1); _Pragma("unroll") for (int m = 0; m < 4; ++m) _Pragma("unroll") for (int n = 0; n < 2; ++n) _Pragma("unroll") for (int k = 0; k < 2; ++k) \
;         acc[ai][bj][m][n] = __builtin_amdgcn_mfma_f32_16x16x32_bf16(Bt[n][k], At[m][k], acc[ai][bj][m][n], 0, 0, 0); __builtin_amdgcn_s_setprio(0); } while (0)
; #define PG8_WAIT_V(n) asm volatile("s_waitcnt vmcnt(" #n ")" ::: "memory")
; #define PG8_WAIT_L(n) asm volatile("s_waitcnt lgkmcnt(" #n ")" ::: "memory")
; #define PG8_BAR __builtin_amdgcn_s_barrier()
; #define PG8_SCHED __builtin_amdgcn_sched_barrier(0)
; template <class Epi>
; __device__ __forceinline__ void gemm_phase(LAS unsigned char* lds, const Gemm g, const StaticOrder& S, const Epi& E) {
;     ...
;             PG8_WAIT_V(8); PG8_WAIT_L(0); PG8_BAR; PG8_MMA(0, 0, At, B0); PG8_MMA(0, 1, At, B1); PG8_BAR; PG8_SCHED;
;             PG8_LDA(At, 1, 1); PG8_STAGE(PG8_SB(1, 0), b3, voffB); PG8_STAGE(PG8_SB(1, 1), b3 + hsB, voffB); PG8_STAGE(PG8_SA(1, 0), a3, voffA);
;             PG8_WAIT_V(8); PG8_WAIT_L(0); PG8_BAR; PG8_MMA(1, 0, At, B0); PG8_MMA(1, 1, At, B1); PG8_BAR; PG8_SCHED;
	v_mfma_f32_16x16x32_bf16 v[116:119], v[188:191], v[204:207], v[116:119]
	v_mfma_f32_16x16x32_bf16 v[112:115], v[196:199], v[204:207], v[112:115]
	v_mfma_f32_16x16x32_bf16 v[100:103], v[188:191], v[212:215], v[100:103]
	v_mfma_f32_16x16x32_bf16 v[96:99], v[196:199], v[212:215], v[96:99]
	v_mfma_f32_16x16x32_bf16 v[84:87], v[188:191], v[220:223], v[84:87]
	v_mfma_f32_16x16x32_bf16 v[80:83], v[196:199], v[220:223], v[80:83]
	v_mfma_f32_16x16x32_bf16 v[68:71], v[188:191], v[228:231], v[68:71]
	v_mfma_f32_16x16x32_bf16 v[64:67], v[196:199], v[228:231], v[64:67]
	v_mfma_f32_16x16x32_bf16 v[116:119], v[192:195], v[208:211], v[116:119]
	v_mfma_f32_16x16x32_bf16 v[112:115], v[200:203], v[208:211], v[112:115]
	v_mfma_f32_16x16x32_bf16 v[100:103], v[192:195], v[216:219], v[100:103]
	v_mfma_f32_16x16x32_bf16 v[96:99], v[200:203], v[216:219], v[96:99]
	v_mfma_f32_16x16x32_bf16 v[84:87], v[192:195], v[224:227], v[84:87]
	v_mfma_f32_16x16x32_bf16 v[80:83], v[200:203], v[224:227], v[80:83]
	v_mfma_f32_16x16x32_bf16 v[68:71], v[192:195], v[232:235], v[68:71]
	v_mfma_f32_16x16x32_bf16 v[64:67], v[200:203], v[232:235], v[64:67]
	s_setprio 0
	s_barrier
	s_add_i32 s0, s17, s60
	v_lshl_add_u64 v[168:169], v[168:169], 0, s[10:11]
	s_mov_b32 m0, s0
	ds_read_b128 v[204:207], v173 offset:49152
	ds_read_b128 v[208:211], v173 offset:50176
	ds_read_b128 v[212:215], v173 offset:51200
	ds_read_b128 v[216:219], v173 offset:52224
	ds_read_b128 v[220:223], v173 offset:53248
	ds_read_b128 v[224:227], v173 offset:54272
	ds_read_b128 v[228:231], v173 offset:55296
	ds_read_b128 v[232:235], v173 offset:56320
	global_load_lds_dwordx4 v[168:169], off
	s_add_i32 m0, s0, 0x2000
	s_add_u32 s0, s56, 0x40080
	v_lshl_add_u64 v[168:169], v[236:237], 0, s[10:11]
	s_addc_u32 s1, s57, 0
	s_add_i32 s17, s24, s60
	global_load_lds_dwordx4 v[168:169], off
	v_lshl_add_u64 v[168:169], s[0:1], 0, v[138:139]
	s_mov_b32 m0, s17
	s_nop 0
	global_load_lds_dwordx4 v[168:169], off
	v_lshl_add_u64 v[168:169], s[0:1], 0, v[142:143]
	s_add_i32 m0, s17, 0x2000
	s_nop 0
	global_load_lds_dwordx4 v[168:169], off
	v_lshl_add_u64 v[168:169], v[238:239], 0, s[10:11]
	s_mov_b32 m0, s64
	s_nop 0
	global_load_lds_dwordx4 v[168:169], off
	v_lshl_add_u64 v[168:169], v[240:241], 0, s[10:11]
	s_mov_b32 m0, s65
	s_nop 0
	global_load_lds_dwordx4 v[168:169], off
	s_waitcnt vmcnt(8)
	s_waitcnt lgkmcnt(0)
	s_barrier
	s_setprio 1
	s_waitcnt lgkmcnt(0)
	v_mfma_f32_16x16x32_bf16 v[60:63], v[128:131], v[204:207], v[60:63]
	v_mfma_f32_16x16x32_bf16 v[56:59], v[164:167], v[204:207], v[56:59]
	v_mfma_f32_16x16x32_bf16 v[44:47], v[128:131], v[212:215], v[44:47]
	v_mfma_f32_16x16x32_bf16 v[40:43], v[164:167], v[212:215], v[40:43]
	v_mfma_f32_16x16x32_bf16 v[28:31], v[128:131], v[220:223], v[28:31]
	v_mfma_f32_16x16x32_bf16 v[24:27], v[164:167], v[220:223], v[24:27]
	v_mfma_f32_16x16x32_bf16 v[12:15], v[128:131], v[228:231], v[12:15]
	v_mfma_f32_16x16x32_bf16 v[8:11], v[164:167], v[228:231], v[8:11]
	v_mfma_f32_16x16x32_bf16 v[60:63], v[132:135], v[208:211], v[60:63]
	v_mfma_f32_16x16x32_bf16 v[56:59], v[184:187], v[208:211], v[56:59]
	v_mfma_f32_16x16x32_bf16 v[44:47], v[132:135], v[216:219], v[44:47]
	v_mfma_f32_16x16x32_bf16 v[40:43], v[184:187], v[216:219], v[40:43]
	v_mfma_f32_16x16x32_bf16 v[28:31], v[132:135], v[224:227], v[28:31]
	v_mfma_f32_16x16x32_bf16 v[24:27], v[184:187], v[224:227], v[24:27]
	v_mfma_f32_16x16x32_bf16 v[12:15], v[132:135], v[232:235], v[12:15]
	v_mfma_f32_16x16x32_bf16 v[8:11], v[184:187], v[232:235], v[8:11]


; #define PG8_MMA(ai, bj, At, Bt) do { __builtin_amdgcn_s_setprio(1); _Pragma("unroll") for (int m = 0; m < 4; ++m) _Pragma("unroll") for (int n = 0; n < 2; ++n) _Pragma("unroll") for (int k = 0; k < 2; ++k) \
;         acc[ai][bj][m][n] = __builtin_amdgcn_mfma_f32_16x16x32_bf16(Bt[n][k], At[m][k], acc[ai][bj][m][n], 0, 0, 0); __builtin_amdgcn_s_setprio(0); } while (0)
; #define PG8_WAIT_V(n) asm volatile("s_waitcnt vmcnt(" #n ")" ::: "memory")
; #define PG8_WAIT_L(n) asm volatile("s_waitcnt lgkmcnt(" #n ")" ::: "memory")
; #define PG8_BAR __builtin_amdgcn_s_barrier()
; #define PG8_SCHED __builtin_amdgcn_sched_barrier(0)
; template <class Epi>
; __device__ __forceinline__ void gemm_phase(LAS unsigned char* lds, const Gemm g, const StaticOrder& S, const Epi& E) {
;     ...
;             PG8_WAIT_V(8); PG8_WAIT_L(0); PG8_BAR; PG8_MMA(1, 0, At, B0); PG8_MMA(1, 1, At, B1); PG8_BAR; PG8_SCHED;
;         }
	v_mfma_f32_16x16x32_bf16 v[52:55], v[188:191], v[204:207], v[52:55]
	v_mfma_f32_16x16x32_bf16 v[48:51], v[196:199], v[204:207], v[48:51]
	v_mfma_f32_16x16x32_bf16 v[36:39], v[188:191], v[212:215], v[36:39]
	v_mfma_f32_16x16x32_bf16 v[32:35], v[196:199], v[212:215], v[32:35]
	v_mfma_f32_16x16x32_bf16 v[20:23], v[188:191], v[220:223], v[20:23]
	v_mfma_f32_16x16x32_bf16 v[16:19], v[196:199], v[220:223], v[16:19]
	v_mfma_f32_16x16x32_bf16 v[4:7], v[188:191], v[228:231], v[4:7]
	v_mfma_f32_16x16x32_bf16 v[0:3], v[196:199], v[228:231], v[0:3]
	v_mfma_f32_16x16x32_bf16 v[52:55], v[192:195], v[208:211], v[52:55]
	v_mfma_f32_16x16x32_bf16 v[48:51], v[200:203], v[208:211], v[48:51]
	v_mfma_f32_16x16x32_bf16 v[36:39], v[192:195], v[216:219], v[36:39]
	v_mfma_f32_16x16x32_bf16 v[32:35], v[200:203], v[216:219], v[32:35]
	v_mfma_f32_16x16x32_bf16 v[20:23], v[192:195], v[224:227], v[20:23]
	v_mfma_f32_16x16x32_bf16 v[16:19], v[200:203], v[224:227], v[16:19]
	v_mfma_f32_16x16x32_bf16 v[4:7], v[192:195], v[232:235], v[4:7]
	v_mfma_f32_16x16x32_bf16 v[0:3], v[200:203], v[232:235], v[0:3]
	s_setprio 0
	s_barrier
	s_add_u32 s54, s54, 0x100
	s_addc_u32 s55, 0, s55
	s_cmp_gt_u32 s33, 29
	s_cbranch_scc1 .LBB0_1086

; #define PG8_STAGE(bufoff, gbase, voff) do { _Pragma("unroll") for (int _i = 0; _i < 2; ++_i) \
;         __builtin_amdgcn_global_load_lds((const unsigned*)((const char*)(gbase) + (voff)[_i]), (LAS unsigned*)(lds + (bufoff) + ldsw + _i * 8192), 16, 0, 0); } while (0)
; #define PG8_LDA(dst, b, h) do { _Pragma("unroll") for (int m = 0; m < 4; ++m) _Pragma("unroll") for (int k = 0; k < 2; ++k) dst[m][k] = *(const LAS bf16x8*)(lds + PG8_SA(b, h) + aoff + m * 2048 + k * 1024); } while (0)
; #define PG8_LDB(dst, b, h) do { _Pragma("unroll") for (int n = 0; n < 2; ++n) _Pragma("unroll") for (int k = 0; k < 2; ++k) dst[n][k] = *(const LAS bf16x8*)(lds + PG8_SB(b, h) + boff + n * 2048 + k * 1024); } while (0)
; #define PG8_MMA(ai, bj, At, Bt) do { __builtin_amdgcn_s_setprio(1); _Pragma("unroll") for (int m = 0; m < 4; ++m) _Pragma("unroll") for (int n = 0; n < 2; ++n) _Pragma("unroll") for (int k = 0; k < 2; ++k) \
;         acc[ai][bj][m][n] = __builtin_amdgcn_mfma_f32_16x16x32_bf16(Bt[n][k], At[m][k], acc[ai][bj][m][n], 0, 0, 0); __builtin_amdgcn_s_setprio(0); } while (0)
; #define PG8_WAIT_V(n) asm volatile("s_waitcnt vmcnt(" #n ")" ::: "memory")
; #define PG8_WAIT_L(n) asm volatile("s_waitcnt lgkmcnt(" #n ")" ::: "memory")
; #define PG8_BAR __builtin_amdgcn_s_barrier()
; #define PG8_SCHED __builtin_amdgcn_sched_barrier(0)
; template <class Epi>
; __device__ __forceinline__ void gemm_phase(LAS unsigned char* lds, const Gemm g, const StaticOrder& S, const Epi& E) {
;     ...
;             PG8_LDB(B0, 0, 0); PG8_LDB(B1, 0, 1); PG8_SCHED; PG8_LDA(At, 0, 0); PG8_STAGE(PG8_SA(1, 1), a1 + hsA, voffA);
;             PG8_WAIT_V(8); PG8_WAIT_L(0); PG8_BAR; PG8_MMA(0, 0, At, B0); PG8_MMA(0, 1, At, B1); PG8_BAR; PG8_SCHED;
.LBB0_1234:
	ds_read_b128 v[144:147], v155
	ds_read_b128 v[148:151], v155 offset:1024
	ds_read_b128 v[162:165], v155 offset:2048
	ds_read_b128 v[166:169], v155 offset:3072
	ds_read_b128 v[170:173], v156
	ds_read_b128 v[174:177], v156 offset:1024
	ds_read_b128 v[184:187], v156 offset:2048
	ds_read_b128 v[188:191], v156 offset:3072
	s_add_u32 s39, s48, 0xfffc0080
	s_addc_u32 s41, s49, -1
	s_cmp_eq_u32 s35, 12
	s_cselect_b32 s53, s0, s41
	s_cselect_b32 s52, s1, s39
	s_cselect_b32 s51, s6, s34
	s_cselect_b32 s50, s7, s13
	s_add_i32 m0, s5, 0xc000
	ds_read_b128 v[192:195], v157
	ds_read_b128 v[196:199], v157 offset:1024
	ds_read_b128 v[200:203], v157 offset:2048
	ds_read_b128 v[204:207], v157 offset:3072
	ds_read_b128 v[208:211], v157 offset:4096
	ds_read_b128 v[212:215], v157 offset:5120
	ds_read_b128 v[216:219], v157 offset:6144
	ds_read_b128 v[220:223], v157 offset:7168
	global_load_lds_dwordx4 v136, s[48:49]
	s_add_i32 m0, s5, 0xe000
	s_nop 0
	global_load_lds_dwordx4 v138, s[48:49]
	s_waitcnt vmcnt(8)
	s_waitcnt lgkmcnt(0)
	s_barrier
	s_setprio 1
	s_waitcnt lgkmcnt(0)
	v_mfma_f32_16x16x32_bf16 v[124:127], v[144:147], v[192:195], v[124:127]
	v_mfma_f32_16x16x32_bf16 v[120:123], v[162:165], v[192:195], v[120:123]
	v_mfma_f32_16x16x32_bf16 v[108:111], v[144:147], v[200:203], v[108:111]
	v_mfma_f32_16x16x32_bf16 v[104:107], v[162:165], v[200:203], v[104:107]
	v_mfma_f32_16x16x32_bf16 v[92:95], v[144:147], v[208:211], v[92:95]
	v_mfma_f32_16x16x32_bf16 v[88:91], v[162:165], v[208:211], v[88:91]
	v_mfma_f32_16x16x32_bf16 v[76:79], v[144:147], v[216:219], v[76:79]
	v_mfma_f32_16x16x32_bf16 v[72:75], v[162:165], v[216:219], v[72:75]
	v_mfma_f32_16x16x32_bf16 v[124:127], v[148:151], v[196:199], v[124:127]
	v_mfma_f32_16x16x32_bf16 v[120:123], v[166:169], v[196:199], v[120:123]
	v_mfma_f32_16x16x32_bf16 v[108:111], v[148:151], v[204:207], v[108:111]
	v_mfma_f32_16x16x32_bf16 v[104:107], v[166:169], v[204:207], v[104:107]
	v_mfma_f32_16x16x32_bf16 v[92:95], v[148:151], v[212:215], v[92:95]
	v_mfma_f32_16x16x32_bf16 v[88:91], v[166:169], v[212:215], v[88:91]
	v_mfma_f32_16x16x32_bf16 v[76:79], v[148:151], v[220:223], v[76:79]
	v_mfma_f32_16x16x32_bf16 v[72:75], v[166:169], v[220:223], v[72:75]


; #define PG8_STAGE(bufoff, gbase, voff) do { _Pragma("unroll") for (int _i = 0; _i < 2; ++_i) \
;         __builtin_amdgcn_global_load_lds((const unsigned*)((const char*)(gbase) + (voff)[_i]), (LAS unsigned*)(lds + (bufoff) + ldsw + _i * 8192), 16, 0, 0); } while (0)
; #define PG8_LDA(dst, b, h) do { _Pragma("unroll") for (int m = 0; m < 4; ++m) _Pragma("unroll") for (int k = 0; k < 2; ++k) dst[m][k] = *(const LAS bf16x8*)(lds + PG8_SA(b, h) + aoff + m * 2048 + k * 1024); } while (0)
; #define PG8_MMA(ai, bj, At, Bt) do { __builtin_amdgcn_s_setprio(1); _Pragma("unroll") for (int m = 0; m < 4; ++m) _Pragma("unroll") for (int n = 0; n < 2; ++n) _Pragma("unroll") for (int k = 0; k < 2; ++k) \
;         acc[ai][bj][m][n] = __builtin_amdgcn_mfma_f32_16x16x32_bf16(Bt[n][k], At[m][k], acc[ai][bj][m][n], 0, 0, 0); __builtin_amdgcn_s_setprio(0); } while (0)
; #define PG8_WAIT_V(n) asm volatile("s_waitcnt vmcnt(" #n ")" ::: "memory")
; #define PG8_WAIT_L(n) asm volatile("s_waitcnt lgkmcnt(" #n ")" ::: "memory")
; #define PG8_BAR __builtin_amdgcn_s_barrier()
; #define PG8_SCHED __builtin_amdgcn_sched_barrier(0)
; template <class Epi>
; __device__ __forceinline__ void gemm_phase(LAS unsigned char* lds, const Gemm g, const StaticOrder& S, const Epi& E) {
;     ...
;             PG8_WAIT_V(8); PG8_WAIT_L(0); PG8_BAR; PG8_MMA(0, 0, At, B0); PG8_MMA(0, 1, At, B1); PG8_BAR; PG8_SCHED;
;             PG8_LDA(At, 0, 1); PG8_STAGE(PG8_SB(0, 0), b2, voffB); PG8_STAGE(PG8_SB(0, 1), b2 + hsB, voffB); PG8_STAGE(PG8_SA(0, 0), a2, voffA);
;             PG8_WAIT_V(8); PG8_WAIT_L(0); PG8_BAR; PG8_MMA(1, 0, At, B0); PG8_MMA(1, 1, At, B1); PG8_BAR; PG8_SCHED;
	v_mfma_f32_16x16x32_bf16 v[116:119], v[170:173], v[192:195], v[116:119]
	v_mfma_f32_16x16x32_bf16 v[112:115], v[184:187], v[192:195], v[112:115]
	v_mfma_f32_16x16x32_bf16 v[100:103], v[170:173], v[200:203], v[100:103]
	v_mfma_f32_16x16x32_bf16 v[96:99], v[184:187], v[200:203], v[96:99]
	v_mfma_f32_16x16x32_bf16 v[84:87], v[170:173], v[208:211], v[84:87]
	v_mfma_f32_16x16x32_bf16 v[80:83], v[184:187], v[208:211], v[80:83]
	v_mfma_f32_16x16x32_bf16 v[68:71], v[170:173], v[216:219], v[68:71]
	v_mfma_f32_16x16x32_bf16 v[64:67], v[184:187], v[216:219], v[64:67]
	v_mfma_f32_16x16x32_bf16 v[116:119], v[174:177], v[196:199], v[116:119]
	v_mfma_f32_16x16x32_bf16 v[112:115], v[188:191], v[196:199], v[112:115]
	v_mfma_f32_16x16x32_bf16 v[100:103], v[174:177], v[204:207], v[100:103]
	v_mfma_f32_16x16x32_bf16 v[96:99], v[188:191], v[204:207], v[96:99]
	v_mfma_f32_16x16x32_bf16 v[84:87], v[174:177], v[212:215], v[84:87]
	v_mfma_f32_16x16x32_bf16 v[80:83], v[188:191], v[212:215], v[80:83]
	v_mfma_f32_16x16x32_bf16 v[68:71], v[174:177], v[220:223], v[68:71]
	v_mfma_f32_16x16x32_bf16 v[64:67], v[188:191], v[220:223], v[64:67]
	s_setprio 0
	s_barrier
	s_add_i32 s39, s31, s4
	s_mov_b32 m0, s39
	ds_read_b128 v[192:195], v157 offset:16384
	ds_read_b128 v[196:199], v157 offset:17408
	ds_read_b128 v[200:203], v157 offset:18432
	ds_read_b128 v[204:207], v157 offset:19456
	ds_read_b128 v[208:211], v157 offset:20480
	ds_read_b128 v[212:215], v157 offset:21504
	ds_read_b128 v[216:219], v157 offset:22528
	ds_read_b128 v[220:223], v157 offset:23552
	global_load_lds_dwordx4 v130, s[50:51]
	s_add_i32 m0, s39, 0x2000
	s_add_u32 s54, s50, 0x40000
	s_addc_u32 s55, s51, 0
	s_add_i32 s39, s33, s4
	global_load_lds_dwordx4 v134, s[50:51]
	s_mov_b32 m0, s39
	s_nop 0
	global_load_lds_dwordx4 v130, s[54:55]
	s_add_i32 m0, s39, 0x2000
	s_nop 0
	global_load_lds_dwordx4 v134, s[54:55]
	s_mov_b32 m0, s5
	s_nop 0
	global_load_lds_dwordx4 v128, s[52:53]
	s_mov_b32 m0, s16
	s_nop 0
	global_load_lds_dwordx4 v132, s[52:53]
	s_waitcnt vmcnt(8)
	s_waitcnt lgkmcnt(0)
	s_barrier
	s_setprio 1
	s_waitcnt lgkmcnt(0)
	v_mfma_f32_16x16x32_bf16 v[60:63], v[144:147], v[192:195], v[60:63]
	v_mfma_f32_16x16x32_bf16 v[56:59], v[162:165], v[192:195], v[56:59]
	v_mfma_f32_16x16x32_bf16 v[44:47], v[144:147], v[200:203], v[44:47]
	v_mfma_f32_16x16x32_bf16 v[40:43], v[162:165], v[200:203], v[40:43]
	v_mfma_f32_16x16x32_bf16 v[28:31], v[144:147], v[208:211], v[28:31]
	v_mfma_f32_16x16x32_bf16 v[24:27], v[162:165], v[208:211], v[24:27]
	v_mfma_f32_16x16x32_bf16 v[12:15], v[144:147], v[216:219], v[12:15]
	v_mfma_f32_16x16x32_bf16 v[8:11], v[162:165], v[216:219], v[8:11]
	v_mfma_f32_16x16x32_bf16 v[60:63], v[148:151], v[196:199], v[60:63]
	v_mfma_f32_16x16x32_bf16 v[56:59], v[166:169], v[196:199], v[56:59]
	v_mfma_f32_16x16x32_bf16 v[44:47], v[148:151], v[204:207], v[44:47]
	v_mfma_f32_16x16x32_bf16 v[40:43], v[166:169], v[204:207], v[40:43]
	v_mfma_f32_16x16x32_bf16 v[28:31], v[148:151], v[212:215], v[28:31]
	v_mfma_f32_16x16x32_bf16 v[24:27], v[166:169], v[212:215], v[24:27]
	v_mfma_f32_16x16x32_bf16 v[12:15], v[148:151], v[220:223], v[12:15]
	v_mfma_f32_16x16x32_bf16 v[8:11], v[166:169], v[220:223], v[8:11]


; #define PG8_STAGE(bufoff, gbase, voff) do { _Pragma("unroll") for (int _i = 0; _i < 2; ++_i) \
;         __builtin_amdgcn_global_load_lds((const unsigned*)((const char*)(gbase) + (voff)[_i]), (LAS unsigned*)(lds + (bufoff) + ldsw + _i * 8192), 16, 0, 0); } while (0)
; #define PG8_LDA(dst, b, h) do { _Pragma("unroll") for (int m = 0; m < 4; ++m) _Pragma("unroll") for (int k = 0; k < 2; ++k) dst[m][k] = *(const LAS bf16x8*)(lds + PG8_SA(b, h) + aoff + m * 2048 + k * 1024); } while (0)
; #define PG8_LDB(dst, b, h) do { _Pragma("unroll") for (int n = 0; n < 2; ++n) _Pragma("unroll") for (int k = 0; k < 2; ++k) dst[n][k] = *(const LAS bf16x8*)(lds + PG8_SB(b, h) + boff + n * 2048 + k * 1024); } while (0)
; #define PG8_MMA(ai, bj, At, Bt) do { __builtin_amdgcn_s_setprio(1); _Pragma("unroll") for (int m = 0; m < 4; ++m) _Pragma("unroll") for (int n = 0; n < 2; ++n) _Pragma("unroll") for (int k = 0; k < 2; ++k) \
;         acc[ai][bj][m][n] = __builtin_amdgcn_mfma_f32_16x16x32_bf16(Bt[n][k], At[m][k], acc[ai][bj][m][n], 0, 0, 0); __builtin_amdgcn_s_setprio(0); } while (0)
; #define PG8_WAIT_V(n) asm volatile("s_waitcnt vmcnt(" #n ")" ::: "memory")
; #define PG8_WAIT_L(n) asm volatile("s_waitcnt lgkmcnt(" #n ")" ::: "memory")
; #define PG8_BAR __builtin_amdgcn_s_barrier()
; #define PG8_SCHED __builtin_amdgcn_sched_barrier(0)
; template <class Epi>
; __device__ __forceinline__ void gemm_phase(LAS unsigned char* lds, const Gemm g, const StaticOrder& S, const Epi& E) {
;     ...
;             PG8_WAIT_V(8); PG8_WAIT_L(0); PG8_BAR; PG8_MMA(1, 0, At, B0); PG8_MMA(1, 1, At, B1); PG8_BAR; PG8_SCHED;
;             PG8_LDB(B0, 1, 0); PG8_LDB(B1, 1, 1); PG8_SCHED; PG8_LDA(At, 1, 0); PG8_STAGE(PG8_SA(0, 1), a2 + hsA, voffA);
;             PG8_WAIT_V(8); PG8_WAIT_L(0); PG8_BAR; PG8_MMA(0, 0, At, B0); PG8_MMA(0, 1, At, B1); PG8_BAR; PG8_SCHED;
	v_mfma_f32_16x16x32_bf16 v[52:55], v[170:173], v[192:195], v[52:55]
	v_mfma_f32_16x16x32_bf16 v[48:51], v[184:187], v[192:195], v[48:51]
	v_mfma_f32_16x16x32_bf16 v[36:39], v[170:173], v[200:203], v[36:39]
	v_mfma_f32_16x16x32_bf16 v[32:35], v[184:187], v[200:203], v[32:35]
	v_mfma_f32_16x16x32_bf16 v[20:23], v[170:173], v[208:211], v[20:23]
	v_mfma_f32_16x16x32_bf16 v[16:19], v[184:187], v[208:211], v[16:19]
	v_mfma_f32_16x16x32_bf16 v[4:7], v[170:173], v[216:219], v[4:7]
	v_mfma_f32_16x16x32_bf16 v[0:3], v[184:187], v[216:219], v[0:3]
	v_mfma_f32_16x16x32_bf16 v[52:55], v[174:177], v[196:199], v[52:55]
	v_mfma_f32_16x16x32_bf16 v[48:51], v[188:191], v[196:199], v[48:51]
	v_mfma_f32_16x16x32_bf16 v[36:39], v[174:177], v[204:207], v[36:39]
	v_mfma_f32_16x16x32_bf16 v[32:35], v[188:191], v[204:207], v[32:35]
	v_mfma_f32_16x16x32_bf16 v[20:23], v[174:177], v[212:215], v[20:23]
	v_mfma_f32_16x16x32_bf16 v[16:19], v[188:191], v[212:215], v[16:19]
	v_mfma_f32_16x16x32_bf16 v[4:7], v[174:177], v[220:223], v[4:7]
	v_mfma_f32_16x16x32_bf16 v[0:3], v[188:191], v[220:223], v[0:3]
	s_setprio 0
	s_barrier
	s_add_i32 s39, 0, 0x18000
	v_add_u32_e32 v160, s39, v153
	s_add_i32 s41, 0, 0x1c000
	ds_read_b128 v[144:147], v160
	ds_read_b128 v[148:151], v160 offset:1024
	ds_read_b128 v[162:165], v160 offset:2048
	ds_read_b128 v[166:169], v160 offset:3072
	v_add_u32_e32 v160, s41, v153
	ds_read_b128 v[170:173], v160
	ds_read_b128 v[174:177], v160 offset:1024
	ds_read_b128 v[184:187], v160 offset:2048
	ds_read_b128 v[188:191], v160 offset:3072
	s_add_u32 s52, s52, 0x40000
	s_addc_u32 s53, s53, 0
	s_mov_b32 m0, s17
	ds_read_b128 v[192:195], v157 offset:32768
	ds_read_b128 v[196:199], v157 offset:33792
	ds_read_b128 v[200:203], v157 offset:34816
	ds_read_b128 v[204:207], v157 offset:35840
	ds_read_b128 v[208:211], v157 offset:36864
	ds_read_b128 v[212:215], v157 offset:37888
	ds_read_b128 v[216:219], v157 offset:38912
	ds_read_b128 v[220:223], v157 offset:39936
	global_load_lds_dwordx4 v128, s[52:53]
	s_mov_b32 m0, s18
	s_nop 0
	global_load_lds_dwordx4 v132, s[52:53]
	s_waitcnt vmcnt(8)
	s_waitcnt lgkmcnt(0)
	s_barrier
	s_setprio 1
	s_waitcnt lgkmcnt(0)
	v_mfma_f32_16x16x32_bf16 v[124:127], v[144:147], v[192:195], v[124:127]
	v_mfma_f32_16x16x32_bf16 v[120:123], v[162:165], v[192:195], v[120:123]
	v_mfma_f32_16x16x32_bf16 v[108:111], v[144:147], v[200:203], v[108:111]
	v_mfma_f32_16x16x32_bf16 v[104:107], v[162:165], v[200:203], v[104:107]
	v_mfma_f32_16x16x32_bf16 v[92:95], v[144:147], v[208:211], v[92:95]
	v_mfma_f32_16x16x32_bf16 v[88:91], v[162:165], v[208:211], v[88:91]
	v_mfma_f32_16x16x32_bf16 v[76:79], v[144:147], v[216:219], v[76:79]
	v_mfma_f32_16x16x32_bf16 v[72:75], v[162:165], v[216:219], v[72:75]
	v_mfma_f32_16x16x32_bf16 v[124:127], v[148:151], v[196:199], v[124:127]
	v_mfma_f32_16x16x32_bf16 v[120:123], v[166:169], v[196:199], v[120:123]
	v_mfma_f32_16x16x32_bf16 v[108:111], v[148:151], v[204:207], v[108:111]
	v_mfma_f32_16x16x32_bf16 v[104:107], v[166:169], v[204:207], v[104:107]
	v_mfma_f32_16x16x32_bf16 v[92:95], v[148:151], v[212:215], v[92:95]
	v_mfma_f32_16x16x32_bf16 v[88:91], v[166:169], v[212:215], v[88:91]
	v_mfma_f32_16x16x32_bf16 v[76:79], v[148:151], v[220:223], v[76:79]
	v_mfma_f32_16x16x32_bf16 v[72:75], v[166:169], v[220:223], v[72:75]


; #define PG8_STAGE(bufoff, gbase, voff) do { _Pragma("unroll") for (int _i = 0; _i < 2; ++_i) \
;         __builtin_amdgcn_global_load_lds((const unsigned*)((const char*)(gbase) + (voff)[_i]), (LAS unsigned*)(lds + (bufoff) + ldsw + _i * 8192), 16, 0, 0); } while (0)
; #define PG8_LDA(dst, b, h) do { _Pragma("unroll") for (int m = 0; m < 4; ++m) _Pragma("unroll") for (int k = 0; k < 2; ++k) dst[m][k] = *(const LAS bf16x8*)(lds + PG8_SA(b, h) + aoff + m * 2048 + k * 1024); } while (0)
; #define PG8_MMA(ai, bj, At, Bt) do { __builtin_amdgcn_s_setprio(1); _Pragma("unroll") for (int m = 0; m < 4; ++m) _Pragma("unroll") for (int n = 0; n < 2; ++n) _Pragma("unroll") for (int k = 0; k < 2; ++k) \
;         acc[ai][bj][m][n] = __builtin_amdgcn_mfma_f32_16x16x32_bf16(Bt[n][k], At[m][k], acc[ai][bj][m][n], 0, 0, 0); __builtin_amdgcn_s_setprio(0); } while (0)
; #define PG8_WAIT_V(n) asm volatile("s_waitcnt vmcnt(" #n ")" ::: "memory")
; #define PG8_WAIT_L(n) asm volatile("s_waitcnt lgkmcnt(" #n ")" ::: "memory")
; #define PG8_BAR __builtin_amdgcn_s_barrier()
; #define PG8_SCHED __builtin_amdgcn_sched_barrier(0)
; template <class Epi>
; __device__ __forceinline__ void gemm_phase(LAS unsigned char* lds, const Gemm g, const StaticOrder& S, const Epi& E) {
;     ...
;             PG8_WAIT_V(8); PG8_WAIT_L(0); PG8_BAR; PG8_MMA(0, 0, At, B0); PG8_MMA(0, 1, At, B1); PG8_BAR; PG8_SCHED;
;             PG8_LDA(At, 1, 1); PG8_STAGE(PG8_SB(1, 0), b3, voffB); PG8_STAGE(PG8_SB(1, 1), b3 + hsB, voffB); PG8_STAGE(PG8_SA(1, 0), a3, voffA);
;             PG8_WAIT_V(8); PG8_WAIT_L(0); PG8_BAR; PG8_MMA(1, 0, At, B0); PG8_MMA(1, 1, At, B1); PG8_BAR; PG8_SCHED;
	v_mfma_f32_16x16x32_bf16 v[116:119], v[170:173], v[192:195], v[116:119]
	v_mfma_f32_16x16x32_bf16 v[112:115], v[184:187], v[192:195], v[112:115]
	v_mfma_f32_16x16x32_bf16 v[100:103], v[170:173], v[200:203], v[100:103]
	v_mfma_f32_16x16x32_bf16 v[96:99], v[184:187], v[200:203], v[96:99]
	v_mfma_f32_16x16x32_bf16 v[84:87], v[170:173], v[208:211], v[84:87]
	v_mfma_f32_16x16x32_bf16 v[80:83], v[184:187], v[208:211], v[80:83]
	v_mfma_f32_16x16x32_bf16 v[68:71], v[170:173], v[216:219], v[68:71]
	v_mfma_f32_16x16x32_bf16 v[64:67], v[184:187], v[216:219], v[64:67]
	v_mfma_f32_16x16x32_bf16 v[116:119], v[174:177], v[196:199], v[116:119]
	v_mfma_f32_16x16x32_bf16 v[112:115], v[188:191], v[196:199], v[112:115]
	v_mfma_f32_16x16x32_bf16 v[100:103], v[174:177], v[204:207], v[100:103]
	v_mfma_f32_16x16x32_bf16 v[96:99], v[188:191], v[204:207], v[96:99]
	v_mfma_f32_16x16x32_bf16 v[84:87], v[174:177], v[212:215], v[84:87]
	v_mfma_f32_16x16x32_bf16 v[80:83], v[188:191], v[212:215], v[80:83]
	v_mfma_f32_16x16x32_bf16 v[68:71], v[174:177], v[220:223], v[68:71]
	v_mfma_f32_16x16x32_bf16 v[64:67], v[188:191], v[220:223], v[64:67]
	s_setprio 0
	s_barrier
	s_add_u32 s98, s50, 0x80
	s_addc_u32 s99, s51, 0
	s_add_u32 s100, s52, 0xfffc0080
	s_addc_u32 s101, s53, -1
	s_add_i32 s39, s39, s4
	s_mov_b32 m0, s39
	ds_read_b128 v[192:195], v157 offset:49152
	ds_read_b128 v[196:199], v157 offset:50176
	ds_read_b128 v[200:203], v157 offset:51200
	ds_read_b128 v[204:207], v157 offset:52224
	ds_read_b128 v[208:211], v157 offset:53248
	ds_read_b128 v[212:215], v157 offset:54272
	ds_read_b128 v[216:219], v157 offset:55296
	ds_read_b128 v[220:223], v157 offset:56320
	global_load_lds_dwordx4 v130, s[98:99]
	s_add_i32 m0, s39, 0x2000
	s_add_u32 s50, s50, 0x40080
	s_addc_u32 s51, s51, 0
	s_add_i32 s39, s41, s4
	global_load_lds_dwordx4 v134, s[98:99]
	s_mov_b32 m0, s39
	s_nop 0
	global_load_lds_dwordx4 v130, s[50:51]
	s_add_i32 m0, s39, 0x2000
	s_nop 0
	global_load_lds_dwordx4 v134, s[50:51]
	s_mov_b32 m0, s22
	s_nop 0
	global_load_lds_dwordx4 v128, s[100:101]
	s_mov_b32 m0, s23
	s_nop 0
	global_load_lds_dwordx4 v132, s[100:101]
	s_waitcnt vmcnt(8)
	s_waitcnt lgkmcnt(0)
	s_barrier
	s_setprio 1
	s_waitcnt lgkmcnt(0)
	v_mfma_f32_16x16x32_bf16 v[60:63], v[144:147], v[192:195], v[60:63]
	v_mfma_f32_16x16x32_bf16 v[56:59], v[162:165], v[192:195], v[56:59]
	v_mfma_f32_16x16x32_bf16 v[44:47], v[144:147], v[200:203], v[44:47]
	v_mfma_f32_16x16x32_bf16 v[40:43], v[162:165], v[200:203], v[40:43]
	v_mfma_f32_16x16x32_bf16 v[28:31], v[144:147], v[208:211], v[28:31]
	v_mfma_f32_16x16x32_bf16 v[24:27], v[162:165], v[208:211], v[24:27]
	v_mfma_f32_16x16x32_bf16 v[12:15], v[144:147], v[216:219], v[12:15]
	v_mfma_f32_16x16x32_bf16 v[8:11], v[162:165], v[216:219], v[8:11]
	v_mfma_f32_16x16x32_bf16 v[60:63], v[148:151], v[196:199], v[60:63]
	v_mfma_f32_16x16x32_bf16 v[56:59], v[166:169], v[196:199], v[56:59]
	v_mfma_f32_16x16x32_bf16 v[44:47], v[148:151], v[204:207], v[44:47]
	v_mfma_f32_16x16x32_bf16 v[40:43], v[166:169], v[204:207], v[40:43]
	v_mfma_f32_16x16x32_bf16 v[28:31], v[148:151], v[212:215], v[28:31]
	v_mfma_f32_16x16x32_bf16 v[24:27], v[166:169], v[212:215], v[24:27]
	v_mfma_f32_16x16x32_bf16 v[12:15], v[148:151], v[220:223], v[12:15]
	v_mfma_f32_16x16x32_bf16 v[8:11], v[166:169], v[220:223], v[8:11]


; #define PG8_MMA(ai, bj, At, Bt) do { __builtin_amdgcn_s_setprio(1); _Pragma("unroll") for (int m = 0; m < 4; ++m) _Pragma("unroll") for (int n = 0; n < 2; ++n) _Pragma("unroll") for (int k = 0; k < 2; ++k) \
;         acc[ai][bj][m][n] = __builtin_amdgcn_mfma_f32_16x16x32_bf16(Bt[n][k], At[m][k], acc[ai][bj][m][n], 0, 0, 0); __builtin_amdgcn_s_setprio(0); } while (0)
; #define PG8_WAIT_V(n) asm volatile("s_waitcnt vmcnt(" #n ")" ::: "memory")
; #define PG8_WAIT_L(n) asm volatile("s_waitcnt lgkmcnt(" #n ")" ::: "memory")
; #define PG8_BAR __builtin_amdgcn_s_barrier()
; #define PG8_SCHED __builtin_amdgcn_sched_barrier(0)
; template <class Epi>
; __device__ __forceinline__ void gemm_phase(LAS unsigned char* lds, const Gemm g, const StaticOrder& S, const Epi& E) {
;     ...
;         for (int t = 0; t < nt; t += 2) {
;     ...
;             PG8_WAIT_V(8); PG8_WAIT_L(0); PG8_BAR; PG8_MMA(1, 0, At, B0); PG8_MMA(1, 1, At, B1); PG8_BAR; PG8_SCHED;
;         }
	v_mfma_f32_16x16x32_bf16 v[52:55], v[170:173], v[192:195], v[52:55]
	v_mfma_f32_16x16x32_bf16 v[48:51], v[184:187], v[192:195], v[48:51]
	v_mfma_f32_16x16x32_bf16 v[36:39], v[170:173], v[200:203], v[36:39]
	v_mfma_f32_16x16x32_bf16 v[32:35], v[184:187], v[200:203], v[32:35]
	v_mfma_f32_16x16x32_bf16 v[20:23], v[170:173], v[208:211], v[20:23]
	v_mfma_f32_16x16x32_bf16 v[16:19], v[184:187], v[208:211], v[16:19]
	v_mfma_f32_16x16x32_bf16 v[4:7], v[170:173], v[216:219], v[4:7]
	v_mfma_f32_16x16x32_bf16 v[0:3], v[184:187], v[216:219], v[0:3]
	v_mfma_f32_16x16x32_bf16 v[52:55], v[174:177], v[196:199], v[52:55]
	v_mfma_f32_16x16x32_bf16 v[48:51], v[188:191], v[196:199], v[48:51]
	v_mfma_f32_16x16x32_bf16 v[36:39], v[174:177], v[204:207], v[36:39]
	v_mfma_f32_16x16x32_bf16 v[32:35], v[188:191], v[204:207], v[32:35]
	v_mfma_f32_16x16x32_bf16 v[20:23], v[174:177], v[212:215], v[20:23]
	v_mfma_f32_16x16x32_bf16 v[16:19], v[188:191], v[212:215], v[16:19]
	v_mfma_f32_16x16x32_bf16 v[4:7], v[174:177], v[220:223], v[4:7]
	v_mfma_f32_16x16x32_bf16 v[0:3], v[188:191], v[220:223], v[0:3]
	s_setprio 0
	s_barrier
	s_add_i32 s35, s35, 2
	s_add_u32 s48, s48, 0x100
	s_addc_u32 s49, s49, 0
	s_add_u32 s13, s13, 0x100
	s_addc_u32 s34, s34, 0
	s_cmp_gt_u32 s35, 13
	s_cbranch_scc0 .LBB0_1234
	s_and_b64 vcc, exec, s[26:27]
	s_cbranch_vccz .LBB0_1237
	s_barrier

; #define PG8_STAGE(bufoff, gbase, voff) do { _Pragma("unroll") for (int _i = 0; _i < 2; ++_i) \
;         __builtin_amdgcn_global_load_lds((const unsigned*)((const char*)(gbase) + (voff)[_i]), (LAS unsigned*)(lds + (bufoff) + ldsw + _i * 8192), 16, 0, 0); } while (0)
; #define PG8_LDA(dst, b, h) do { _Pragma("unroll") for (int m = 0; m < 4; ++m) _Pragma("unroll") for (int k = 0; k < 2; ++k) dst[m][k] = *(const LAS bf16x8*)(lds + PG8_SA(b, h) + aoff + m * 2048 + k * 1024); } while (0)
; #define PG8_LDB(dst, b, h) do { _Pragma("unroll") for (int n = 0; n < 2; ++n) _Pragma("unroll") for (int k = 0; k < 2; ++k) dst[n][k] = *(const LAS bf16x8*)(lds + PG8_SB(b, h) + boff + n * 2048 + k * 1024); } while (0)
; #define PG8_MMA(ai, bj, At, Bt) do { __builtin_amdgcn_s_setprio(1); _Pragma("unroll") for (int m = 0; m < 4; ++m) _Pragma("unroll") for (int n = 0; n < 2; ++n) _Pragma("unroll") for (int k = 0; k < 2; ++k) \
;         acc[ai][bj][m][n] = __builtin_amdgcn_mfma_f32_16x16x32_bf16(Bt[n][k], At[m][k], acc[ai][bj][m][n], 0, 0, 0); __builtin_amdgcn_s_setprio(0); } while (0)
; #define PG8_WAIT_V(n) asm volatile("s_waitcnt vmcnt(" #n ")" ::: "memory")
; #define PG8_WAIT_L(n) asm volatile("s_waitcnt lgkmcnt(" #n ")" ::: "memory")
; #define PG8_BAR __builtin_amdgcn_s_barrier()
; #define PG8_SCHED __builtin_amdgcn_sched_barrier(0)
; template <class Epi>
; __device__ __forceinline__ void gemm_phase(LAS unsigned char* lds, const Gemm g, const StaticOrder& S, const Epi& E) {
;     ...
;             const bool last = (t == nt - 2);
;             if constexpr (Epi::HAS_MID) { if (t == nt1) E.mid(acc, cur, wr, wc, fr, fq); }
;             const char* a1 = cA + ((Epi::HAS_MID && t >= nt1) ? dA2 : 0) + (size_t)(t + 1) * kstep;
;             const char* a2 = last ? nA : cA + ((Epi::HAS_MID && t + 2 >= nt1) ? dA2 : 0) + (size_t)(t + 2) * kstep; const char* b2 = last ? nB : cB + ((Epi::HAS_MID && t + 2 >= nt1) ? dB2 : 0) + (size_t)(t + 2) * kstep;
;             const char* a3 = a2 + kstep; const char* b3 = b2 + kstep;
;             PG8_LDB(B0, 0, 0); PG8_LDB(B1, 0, 1); PG8_SCHED; PG8_LDA(At, 0, 0); PG8_STAGE(PG8_SA(1, 1), a1 + hsA, voffA);
;             PG8_WAIT_V(8); PG8_WAIT_L(0); PG8_BAR; PG8_MMA(0, 0, At, B0); PG8_MMA(0, 1, At, B1); PG8_BAR; PG8_SCHED;
.LBB0_1350:
	ds_read_b128 v[144:147], v155
	ds_read_b128 v[148:151], v155 offset:1024
	ds_read_b128 v[162:165], v155 offset:2048
	ds_read_b128 v[166:169], v155 offset:3072
	ds_read_b128 v[170:173], v156
	ds_read_b128 v[174:177], v156 offset:1024
	ds_read_b128 v[184:187], v156 offset:2048
	ds_read_b128 v[188:191], v156 offset:3072
	s_add_u32 s40, s38, 0xfffc0080
	s_addc_u32 s41, s39, -1
	s_cmp_eq_u32 s48, 12
	s_cselect_b32 s43, s25, s41
	s_cselect_b32 s42, s44, s40
	s_cselect_b32 s41, s15, s47
	s_cselect_b32 s40, s45, s46
	s_add_i32 m0, s17, 0xc000
	ds_read_b128 v[192:195], v157
	ds_read_b128 v[196:199], v157 offset:1024
	ds_read_b128 v[200:203], v157 offset:2048
	ds_read_b128 v[204:207], v157 offset:3072
	ds_read_b128 v[208:211], v157 offset:4096
	ds_read_b128 v[212:215], v157 offset:5120
	ds_read_b128 v[216:219], v157 offset:6144
	ds_read_b128 v[220:223], v157 offset:7168
	global_load_lds_dwordx4 v136, s[38:39]
	s_add_i32 m0, s17, 0xe000
	s_nop 0
	global_load_lds_dwordx4 v138, s[38:39]
	s_waitcnt vmcnt(8)
	s_waitcnt lgkmcnt(0)
	s_barrier
	s_setprio 1
	s_waitcnt lgkmcnt(0)
	v_mfma_f32_16x16x32_bf16 v[124:127], v[144:147], v[192:195], v[124:127]
	v_mfma_f32_16x16x32_bf16 v[120:123], v[162:165], v[192:195], v[120:123]
	v_mfma_f32_16x16x32_bf16 v[108:111], v[144:147], v[200:203], v[108:111]
	v_mfma_f32_16x16x32_bf16 v[104:107], v[162:165], v[200:203], v[104:107]
	v_mfma_f32_16x16x32_bf16 v[92:95], v[144:147], v[208:211], v[92:95]
	v_mfma_f32_16x16x32_bf16 v[88:91], v[162:165], v[208:211], v[88:91]
	v_mfma_f32_16x16x32_bf16 v[76:79], v[144:147], v[216:219], v[76:79]
	v_mfma_f32_16x16x32_bf16 v[72:75], v[162:165], v[216:219], v[72:75]
	v_mfma_f32_16x16x32_bf16 v[124:127], v[148:151], v[196:199], v[124:127]
	v_mfma_f32_16x16x32_bf16 v[120:123], v[166:169], v[196:199], v[120:123]
	v_mfma_f32_16x16x32_bf16 v[108:111], v[148:151], v[204:207], v[108:111]
	v_mfma_f32_16x16x32_bf16 v[104:107], v[166:169], v[204:207], v[104:107]
	v_mfma_f32_16x16x32_bf16 v[92:95], v[148:151], v[212:215], v[92:95]
	v_mfma_f32_16x16x32_bf16 v[88:91], v[166:169], v[212:215], v[88:91]
	v_mfma_f32_16x16x32_bf16 v[76:79], v[148:151], v[220:223], v[76:79]
	v_mfma_f32_16x16x32_bf16 v[72:75], v[166:169], v[220:223], v[72:75]


; #define PG8_STAGE(bufoff, gbase, voff) do { _Pragma("unroll") for (int _i = 0; _i < 2; ++_i) \
;         __builtin_amdgcn_global_load_lds((const unsigned*)((const char*)(gbase) + (voff)[_i]), (LAS unsigned*)(lds + (bufoff) + ldsw + _i * 8192), 16, 0, 0); } while (0)
; #define PG8_LDA(dst, b, h) do { _Pragma("unroll") for (int m = 0; m < 4; ++m) _Pragma("unroll") for (int k = 0; k < 2; ++k) dst[m][k] = *(const LAS bf16x8*)(lds + PG8_SA(b, h) + aoff + m * 2048 + k * 1024); } while (0)
; #define PG8_MMA(ai, bj, At, Bt) do { __builtin_amdgcn_s_setprio(1); _Pragma("unroll") for (int m = 0; m < 4; ++m) _Pragma("unroll") for (int n = 0; n < 2; ++n) _Pragma("unroll") for (int k = 0; k < 2; ++k) \
;         acc[ai][bj][m][n] = __builtin_amdgcn_mfma_f32_16x16x32_bf16(Bt[n][k], At[m][k], acc[ai][bj][m][n], 0, 0, 0); __builtin_amdgcn_s_setprio(0); } while (0)
; #define PG8_WAIT_V(n) asm volatile("s_waitcnt vmcnt(" #n ")" ::: "memory")
; #define PG8_WAIT_L(n) asm volatile("s_waitcnt lgkmcnt(" #n ")" ::: "memory")
; #define PG8_BAR __builtin_amdgcn_s_barrier()
; #define PG8_SCHED __builtin_amdgcn_sched_barrier(0)
; template <class Epi>
; __device__ __forceinline__ void gemm_phase(LAS unsigned char* lds, const Gemm g, const StaticOrder& S, const Epi& E) {
;     ...
;             PG8_WAIT_V(8); PG8_WAIT_L(0); PG8_BAR; PG8_MMA(0, 0, At, B0); PG8_MMA(0, 1, At, B1); PG8_BAR; PG8_SCHED;
;             PG8_LDA(At, 0, 1); PG8_STAGE(PG8_SB(0, 0), b2, voffB); PG8_STAGE(PG8_SB(0, 1), b2 + hsB, voffB); PG8_STAGE(PG8_SA(0, 0), a2, voffA);
;             PG8_WAIT_V(8); PG8_WAIT_L(0); PG8_BAR; PG8_MMA(1, 0, At, B0); PG8_MMA(1, 1, At, B1); PG8_BAR; PG8_SCHED;
	v_mfma_f32_16x16x32_bf16 v[116:119], v[170:173], v[192:195], v[116:119]
	v_mfma_f32_16x16x32_bf16 v[112:115], v[184:187], v[192:195], v[112:115]
	v_mfma_f32_16x16x32_bf16 v[100:103], v[170:173], v[200:203], v[100:103]
	v_mfma_f32_16x16x32_bf16 v[96:99], v[184:187], v[200:203], v[96:99]
	v_mfma_f32_16x16x32_bf16 v[84:87], v[170:173], v[208:211], v[84:87]
	v_mfma_f32_16x16x32_bf16 v[80:83], v[184:187], v[208:211], v[80:83]
	v_mfma_f32_16x16x32_bf16 v[68:71], v[170:173], v[216:219], v[68:71]
	v_mfma_f32_16x16x32_bf16 v[64:67], v[184:187], v[216:219], v[64:67]
	v_mfma_f32_16x16x32_bf16 v[116:119], v[174:177], v[196:199], v[116:119]
	v_mfma_f32_16x16x32_bf16 v[112:115], v[188:191], v[196:199], v[112:115]
	v_mfma_f32_16x16x32_bf16 v[100:103], v[174:177], v[204:207], v[100:103]
	v_mfma_f32_16x16x32_bf16 v[96:99], v[188:191], v[204:207], v[96:99]
	v_mfma_f32_16x16x32_bf16 v[84:87], v[174:177], v[212:215], v[84:87]
	v_mfma_f32_16x16x32_bf16 v[80:83], v[188:191], v[212:215], v[80:83]
	v_mfma_f32_16x16x32_bf16 v[68:71], v[174:177], v[220:223], v[68:71]
	v_mfma_f32_16x16x32_bf16 v[64:67], v[188:191], v[220:223], v[64:67]
	s_setprio 0
	s_barrier
	s_add_i32 s49, s30, s4
	s_mov_b32 m0, s49
	ds_read_b128 v[192:195], v157 offset:16384
	ds_read_b128 v[196:199], v157 offset:17408
	ds_read_b128 v[200:203], v157 offset:18432
	ds_read_b128 v[204:207], v157 offset:19456
	ds_read_b128 v[208:211], v157 offset:20480
	ds_read_b128 v[212:215], v157 offset:21504
	ds_read_b128 v[216:219], v157 offset:22528
	ds_read_b128 v[220:223], v157 offset:23552
	global_load_lds_dwordx4 v132, s[40:41]
	s_add_i32 m0, s49, 0x2000
	s_add_u32 s50, s40, 0x40000
	s_addc_u32 s51, s41, 0
	s_add_i32 s49, s31, s4
	global_load_lds_dwordx4 v128, s[40:41]
	s_mov_b32 m0, s49
	s_nop 0
	global_load_lds_dwordx4 v132, s[50:51]
	s_add_i32 m0, s49, 0x2000
	s_nop 0
	global_load_lds_dwordx4 v128, s[50:51]
	s_mov_b32 m0, s17
	s_nop 0
	global_load_lds_dwordx4 v134, s[42:43]
	s_mov_b32 m0, s18
	s_nop 0
	global_load_lds_dwordx4 v130, s[42:43]
	s_waitcnt vmcnt(8)
	s_waitcnt lgkmcnt(0)
	s_barrier
	s_setprio 1
	s_waitcnt lgkmcnt(0)
	v_mfma_f32_16x16x32_bf16 v[60:63], v[144:147], v[192:195], v[60:63]
	v_mfma_f32_16x16x32_bf16 v[56:59], v[162:165], v[192:195], v[56:59]
	v_mfma_f32_16x16x32_bf16 v[44:47], v[144:147], v[200:203], v[44:47]
	v_mfma_f32_16x16x32_bf16 v[40:43], v[162:165], v[200:203], v[40:43]
	v_mfma_f32_16x16x32_bf16 v[28:31], v[144:147], v[208:211], v[28:31]
	v_mfma_f32_16x16x32_bf16 v[24:27], v[162:165], v[208:211], v[24:27]
	v_mfma_f32_16x16x32_bf16 v[12:15], v[144:147], v[216:219], v[12:15]
	v_mfma_f32_16x16x32_bf16 v[8:11], v[162:165], v[216:219], v[8:11]
	v_mfma_f32_16x16x32_bf16 v[60:63], v[148:151], v[196:199], v[60:63]
	v_mfma_f32_16x16x32_bf16 v[56:59], v[166:169], v[196:199], v[56:59]
	v_mfma_f32_16x16x32_bf16 v[44:47], v[148:151], v[204:207], v[44:47]
	v_mfma_f32_16x16x32_bf16 v[40:43], v[166:169], v[204:207], v[40:43]
	v_mfma_f32_16x16x32_bf16 v[28:31], v[148:151], v[212:215], v[28:31]
	v_mfma_f32_16x16x32_bf16 v[24:27], v[166:169], v[212:215], v[24:27]
	v_mfma_f32_16x16x32_bf16 v[12:15], v[148:151], v[220:223], v[12:15]
	v_mfma_f32_16x16x32_bf16 v[8:11], v[166:169], v[220:223], v[8:11]


; #define PG8_STAGE(bufoff, gbase, voff) do { _Pragma("unroll") for (int _i = 0; _i < 2; ++_i) \
;         __builtin_amdgcn_global_load_lds((const unsigned*)((const char*)(gbase) + (voff)[_i]), (LAS unsigned*)(lds + (bufoff) + ldsw + _i * 8192), 16, 0, 0); } while (0)
; #define PG8_LDA(dst, b, h) do { _Pragma("unroll") for (int m = 0; m < 4; ++m) _Pragma("unroll") for (int k = 0; k < 2; ++k) dst[m][k] = *(const LAS bf16x8*)(lds + PG8_SA(b, h) + aoff + m * 2048 + k * 1024); } while (0)
; #define PG8_LDB(dst, b, h) do { _Pragma("unroll") for (int n = 0; n < 2; ++n) _Pragma("unroll") for (int k = 0; k < 2; ++k) dst[n][k] = *(const LAS bf16x8*)(lds + PG8_SB(b, h) + boff + n * 2048 + k * 1024); } while (0)
; #define PG8_MMA(ai, bj, At, Bt) do { __builtin_amdgcn_s_setprio(1); _Pragma("unroll") for (int m = 0; m < 4; ++m) _Pragma("unroll") for (int n = 0; n < 2; ++n) _Pragma("unroll") for (int k = 0; k < 2; ++k) \
;         acc[ai][bj][m][n] = __builtin_amdgcn_mfma_f32_16x16x32_bf16(Bt[n][k], At[m][k], acc[ai][bj][m][n], 0, 0, 0); __builtin_amdgcn_s_setprio(0); } while (0)
; #define PG8_WAIT_V(n) asm volatile("s_waitcnt vmcnt(" #n ")" ::: "memory")
; #define PG8_WAIT_L(n) asm volatile("s_waitcnt lgkmcnt(" #n ")" ::: "memory")
; #define PG8_BAR __builtin_amdgcn_s_barrier()
; #define PG8_SCHED __builtin_amdgcn_sched_barrier(0)
; template <class Epi>
; __device__ __forceinline__ void gemm_phase(LAS unsigned char* lds, const Gemm g, const StaticOrder& S, const Epi& E) {
;     ...
;             PG8_WAIT_V(8); PG8_WAIT_L(0); PG8_BAR; PG8_MMA(1, 0, At, B0); PG8_MMA(1, 1, At, B1); PG8_BAR; PG8_SCHED;
;             PG8_LDB(B0, 1, 0); PG8_LDB(B1, 1, 1); PG8_SCHED; PG8_LDA(At, 1, 0); PG8_STAGE(PG8_SA(0, 1), a2 + hsA, voffA);
;             PG8_WAIT_V(8); PG8_WAIT_L(0); PG8_BAR; PG8_MMA(0, 0, At, B0); PG8_MMA(0, 1, At, B1); PG8_BAR; PG8_SCHED;
	v_mfma_f32_16x16x32_bf16 v[52:55], v[170:173], v[192:195], v[52:55]
	v_mfma_f32_16x16x32_bf16 v[48:51], v[184:187], v[192:195], v[48:51]
	v_mfma_f32_16x16x32_bf16 v[36:39], v[170:173], v[200:203], v[36:39]
	v_mfma_f32_16x16x32_bf16 v[32:35], v[184:187], v[200:203], v[32:35]
	v_mfma_f32_16x16x32_bf16 v[20:23], v[170:173], v[208:211], v[20:23]
	v_mfma_f32_16x16x32_bf16 v[16:19], v[184:187], v[208:211], v[16:19]
	v_mfma_f32_16x16x32_bf16 v[4:7], v[170:173], v[216:219], v[4:7]
	v_mfma_f32_16x16x32_bf16 v[0:3], v[184:187], v[216:219], v[0:3]
	v_mfma_f32_16x16x32_bf16 v[52:55], v[174:177], v[196:199], v[52:55]
	v_mfma_f32_16x16x32_bf16 v[48:51], v[188:191], v[196:199], v[48:51]
	v_mfma_f32_16x16x32_bf16 v[36:39], v[174:177], v[204:207], v[36:39]
	v_mfma_f32_16x16x32_bf16 v[32:35], v[188:191], v[204:207], v[32:35]
	v_mfma_f32_16x16x32_bf16 v[20:23], v[174:177], v[212:215], v[20:23]
	v_mfma_f32_16x16x32_bf16 v[16:19], v[188:191], v[212:215], v[16:19]
	v_mfma_f32_16x16x32_bf16 v[4:7], v[174:177], v[220:223], v[4:7]
	v_mfma_f32_16x16x32_bf16 v[0:3], v[188:191], v[220:223], v[0:3]
	s_setprio 0
	s_barrier
	s_add_i32 s49, 0, 0x18000
	v_add_u32_e32 v159, s49, v153
	s_add_i32 s50, 0, 0x1c000
	ds_read_b128 v[144:147], v159
	ds_read_b128 v[148:151], v159 offset:1024
	ds_read_b128 v[162:165], v159 offset:2048
	ds_read_b128 v[166:169], v159 offset:3072
	v_add_u32_e32 v159, s50, v153
	ds_read_b128 v[170:173], v159
	ds_read_b128 v[174:177], v159 offset:1024
	ds_read_b128 v[184:187], v159 offset:2048
	ds_read_b128 v[188:191], v159 offset:3072
	s_add_u32 s42, s42, 0x40000
	s_addc_u32 s43, s43, 0
	s_mov_b32 m0, s19
	ds_read_b128 v[192:195], v157 offset:32768
	ds_read_b128 v[196:199], v157 offset:33792
	ds_read_b128 v[200:203], v157 offset:34816
	ds_read_b128 v[204:207], v157 offset:35840
	ds_read_b128 v[208:211], v157 offset:36864
	ds_read_b128 v[212:215], v157 offset:37888
	ds_read_b128 v[216:219], v157 offset:38912
	ds_read_b128 v[220:223], v157 offset:39936
	global_load_lds_dwordx4 v134, s[42:43]
	s_mov_b32 m0, s22
	s_nop 0
	global_load_lds_dwordx4 v130, s[42:43]
	s_waitcnt vmcnt(8)
	s_waitcnt lgkmcnt(0)
	s_barrier
	s_setprio 1
	s_waitcnt lgkmcnt(0)
	v_mfma_f32_16x16x32_bf16 v[124:127], v[144:147], v[192:195], v[124:127]
	v_mfma_f32_16x16x32_bf16 v[120:123], v[162:165], v[192:195], v[120:123]
	v_mfma_f32_16x16x32_bf16 v[108:111], v[144:147], v[200:203], v[108:111]
	v_mfma_f32_16x16x32_bf16 v[104:107], v[162:165], v[200:203], v[104:107]
	v_mfma_f32_16x16x32_bf16 v[92:95], v[144:147], v[208:211], v[92:95]
	v_mfma_f32_16x16x32_bf16 v[88:91], v[162:165], v[208:211], v[88:91]
	v_mfma_f32_16x16x32_bf16 v[76:79], v[144:147], v[216:219], v[76:79]
	v_mfma_f32_16x16x32_bf16 v[72:75], v[162:165], v[216:219], v[72:75]
	v_mfma_f32_16x16x32_bf16 v[124:127], v[148:151], v[196:199], v[124:127]
	v_mfma_f32_16x16x32_bf16 v[120:123], v[166:169], v[196:199], v[120:123]
	v_mfma_f32_16x16x32_bf16 v[108:111], v[148:151], v[204:207], v[108:111]
	v_mfma_f32_16x16x32_bf16 v[104:107], v[166:169], v[204:207], v[104:107]
	v_mfma_f32_16x16x32_bf16 v[92:95], v[148:151], v[212:215], v[92:95]
	v_mfma_f32_16x16x32_bf16 v[88:91], v[166:169], v[212:215], v[88:91]
	v_mfma_f32_16x16x32_bf16 v[76:79], v[148:151], v[220:223], v[76:79]
	v_mfma_f32_16x16x32_bf16 v[72:75], v[166:169], v[220:223], v[72:75]


; #define PG8_STAGE(bufoff, gbase, voff) do { _Pragma("unroll") for (int _i = 0; _i < 2; ++_i) \
;         __builtin_amdgcn_global_load_lds((const unsigned*)((const char*)(gbase) + (voff)[_i]), (LAS unsigned*)(lds + (bufoff) + ldsw + _i * 8192), 16, 0, 0); } while (0)
; #define PG8_LDA(dst, b, h) do { _Pragma("unroll") for (int m = 0; m < 4; ++m) _Pragma("unroll") for (int k = 0; k < 2; ++k) dst[m][k] = *(const LAS bf16x8*)(lds + PG8_SA(b, h) + aoff + m * 2048 + k * 1024); } while (0)
; #define PG8_MMA(ai, bj, At, Bt) do { __builtin_amdgcn_s_setprio(1); _Pragma("unroll") for (int m = 0; m < 4; ++m) _Pragma("unroll") for (int n = 0; n < 2; ++n) _Pragma("unroll") for (int k = 0; k < 2; ++k) \
;         acc[ai][bj][m][n] = __builtin_amdgcn_mfma_f32_16x16x32_bf16(Bt[n][k], At[m][k], acc[ai][bj][m][n], 0, 0, 0); __builtin_amdgcn_s_setprio(0); } while (0)
; #define PG8_WAIT_V(n) asm volatile("s_waitcnt vmcnt(" #n ")" ::: "memory")
; #define PG8_WAIT_L(n) asm volatile("s_waitcnt lgkmcnt(" #n ")" ::: "memory")
; #define PG8_BAR __builtin_amdgcn_s_barrier()
; #define PG8_SCHED __builtin_amdgcn_sched_barrier(0)
; template <class Epi>
; __device__ __forceinline__ void gemm_phase(LAS unsigned char* lds, const Gemm g, const StaticOrder& S, const Epi& E) {
;     ...
;             PG8_WAIT_V(8); PG8_WAIT_L(0); PG8_BAR; PG8_MMA(0, 0, At, B0); PG8_MMA(0, 1, At, B1); PG8_BAR; PG8_SCHED;
;             PG8_LDA(At, 1, 1); PG8_STAGE(PG8_SB(1, 0), b3, voffB); PG8_STAGE(PG8_SB(1, 1), b3 + hsB, voffB); PG8_STAGE(PG8_SA(1, 0), a3, voffA);
;             PG8_WAIT_V(8); PG8_WAIT_L(0); PG8_BAR; PG8_MMA(1, 0, At, B0); PG8_MMA(1, 1, At, B1); PG8_BAR; PG8_SCHED;
	v_mfma_f32_16x16x32_bf16 v[116:119], v[170:173], v[192:195], v[116:119]
	v_mfma_f32_16x16x32_bf16 v[112:115], v[184:187], v[192:195], v[112:115]
	v_mfma_f32_16x16x32_bf16 v[100:103], v[170:173], v[200:203], v[100:103]
	v_mfma_f32_16x16x32_bf16 v[96:99], v[184:187], v[200:203], v[96:99]
	v_mfma_f32_16x16x32_bf16 v[84:87], v[170:173], v[208:211], v[84:87]
	v_mfma_f32_16x16x32_bf16 v[80:83], v[184:187], v[208:211], v[80:83]
	v_mfma_f32_16x16x32_bf16 v[68:71], v[170:173], v[216:219], v[68:71]
	v_mfma_f32_16x16x32_bf16 v[64:67], v[184:187], v[216:219], v[64:67]
	v_mfma_f32_16x16x32_bf16 v[116:119], v[174:177], v[196:199], v[116:119]
	v_mfma_f32_16x16x32_bf16 v[112:115], v[188:191], v[196:199], v[112:115]
	v_mfma_f32_16x16x32_bf16 v[100:103], v[174:177], v[204:207], v[100:103]
	v_mfma_f32_16x16x32_bf16 v[96:99], v[188:191], v[204:207], v[96:99]
	v_mfma_f32_16x16x32_bf16 v[84:87], v[174:177], v[212:215], v[84:87]
	v_mfma_f32_16x16x32_bf16 v[80:83], v[188:191], v[212:215], v[80:83]
	v_mfma_f32_16x16x32_bf16 v[68:71], v[174:177], v[220:223], v[68:71]
	v_mfma_f32_16x16x32_bf16 v[64:67], v[188:191], v[220:223], v[64:67]
	s_setprio 0
	s_barrier
	s_add_u32 s98, s40, 0x80
	s_addc_u32 s99, s41, 0
	s_add_u32 s100, s42, 0xfffc0080
	s_addc_u32 s101, s43, -1
	s_add_i32 s42, s49, s4
	s_mov_b32 m0, s42
	ds_read_b128 v[192:195], v157 offset:49152
	ds_read_b128 v[196:199], v157 offset:50176
	ds_read_b128 v[200:203], v157 offset:51200
	ds_read_b128 v[204:207], v157 offset:52224
	ds_read_b128 v[208:211], v157 offset:53248
	ds_read_b128 v[212:215], v157 offset:54272
	ds_read_b128 v[216:219], v157 offset:55296
	ds_read_b128 v[220:223], v157 offset:56320
	global_load_lds_dwordx4 v132, s[98:99]
	s_add_i32 m0, s42, 0x2000
	s_add_u32 s40, s40, 0x40080
	s_addc_u32 s41, s41, 0
	s_add_i32 s42, s50, s4
	global_load_lds_dwordx4 v128, s[98:99]
	s_mov_b32 m0, s42
	s_nop 0
	global_load_lds_dwordx4 v132, s[40:41]
	s_add_i32 m0, s42, 0x2000
	s_nop 0
	global_load_lds_dwordx4 v128, s[40:41]
	s_mov_b32 m0, s0
	s_nop 0
	global_load_lds_dwordx4 v134, s[100:101]
	s_mov_b32 m0, s1
	s_nop 0
	global_load_lds_dwordx4 v130, s[100:101]
	s_waitcnt vmcnt(8)
	s_waitcnt lgkmcnt(0)
	s_barrier
	s_setprio 1
	s_waitcnt lgkmcnt(0)
	v_mfma_f32_16x16x32_bf16 v[60:63], v[144:147], v[192:195], v[60:63]
	v_mfma_f32_16x16x32_bf16 v[56:59], v[162:165], v[192:195], v[56:59]
	v_mfma_f32_16x16x32_bf16 v[44:47], v[144:147], v[200:203], v[44:47]
	v_mfma_f32_16x16x32_bf16 v[40:43], v[162:165], v[200:203], v[40:43]
	v_mfma_f32_16x16x32_bf16 v[28:31], v[144:147], v[208:211], v[28:31]
	v_mfma_f32_16x16x32_bf16 v[24:27], v[162:165], v[208:211], v[24:27]
	v_mfma_f32_16x16x32_bf16 v[12:15], v[144:147], v[216:219], v[12:15]
	v_mfma_f32_16x16x32_bf16 v[8:11], v[162:165], v[216:219], v[8:11]
	v_mfma_f32_16x16x32_bf16 v[60:63], v[148:151], v[196:199], v[60:63]
	v_mfma_f32_16x16x32_bf16 v[56:59], v[166:169], v[196:199], v[56:59]
	v_mfma_f32_16x16x32_bf16 v[44:47], v[148:151], v[204:207], v[44:47]
	v_mfma_f32_16x16x32_bf16 v[40:43], v[166:169], v[204:207], v[40:43]
	v_mfma_f32_16x16x32_bf16 v[28:31], v[148:151], v[212:215], v[28:31]
	v_mfma_f32_16x16x32_bf16 v[24:27], v[166:169], v[212:215], v[24:27]
	v_mfma_f32_16x16x32_bf16 v[12:15], v[148:151], v[220:223], v[12:15]
	v_mfma_f32_16x16x32_bf16 v[8:11], v[166:169], v[220:223], v[8:11]


; #define PG8_MMA(ai, bj, At, Bt) do { __builtin_amdgcn_s_setprio(1); _Pragma("unroll") for (int m = 0; m < 4; ++m) _Pragma("unroll") for (int n = 0; n < 2; ++n) _Pragma("unroll") for (int k = 0; k < 2; ++k) \
;         acc[ai][bj][m][n] = __builtin_amdgcn_mfma_f32_16x16x32_bf16(Bt[n][k], At[m][k], acc[ai][bj][m][n], 0, 0, 0); __builtin_amdgcn_s_setprio(0); } while (0)
; #define PG8_WAIT_V(n) asm volatile("s_waitcnt vmcnt(" #n ")" ::: "memory")
; #define PG8_WAIT_L(n) asm volatile("s_waitcnt lgkmcnt(" #n ")" ::: "memory")
; #define PG8_BAR __builtin_amdgcn_s_barrier()
; #define PG8_SCHED __builtin_amdgcn_sched_barrier(0)
; template <class Epi>
; __device__ __forceinline__ void gemm_phase(LAS unsigned char* lds, const Gemm g, const StaticOrder& S, const Epi& E) {
;     ...
;             PG8_WAIT_V(8); PG8_WAIT_L(0); PG8_BAR; PG8_MMA(1, 0, At, B0); PG8_MMA(1, 1, At, B1); PG8_BAR; PG8_SCHED;
;         }
;         if (wr == 0) PG8_BAR;
	v_mfma_f32_16x16x32_bf16 v[52:55], v[170:173], v[192:195], v[52:55]
	v_mfma_f32_16x16x32_bf16 v[48:51], v[184:187], v[192:195], v[48:51]
	v_mfma_f32_16x16x32_bf16 v[36:39], v[170:173], v[200:203], v[36:39]
	v_mfma_f32_16x16x32_bf16 v[32:35], v[184:187], v[200:203], v[32:35]
	v_mfma_f32_16x16x32_bf16 v[20:23], v[170:173], v[208:211], v[20:23]
	v_mfma_f32_16x16x32_bf16 v[16:19], v[184:187], v[208:211], v[16:19]
	v_mfma_f32_16x16x32_bf16 v[4:7], v[170:173], v[216:219], v[4:7]
	v_mfma_f32_16x16x32_bf16 v[0:3], v[184:187], v[216:219], v[0:3]
	v_mfma_f32_16x16x32_bf16 v[52:55], v[174:177], v[196:199], v[52:55]
	v_mfma_f32_16x16x32_bf16 v[48:51], v[188:191], v[196:199], v[48:51]
	v_mfma_f32_16x16x32_bf16 v[36:39], v[174:177], v[204:207], v[36:39]
	v_mfma_f32_16x16x32_bf16 v[32:35], v[188:191], v[204:207], v[32:35]
	v_mfma_f32_16x16x32_bf16 v[20:23], v[174:177], v[212:215], v[20:23]
	v_mfma_f32_16x16x32_bf16 v[16:19], v[188:191], v[212:215], v[16:19]
	v_mfma_f32_16x16x32_bf16 v[4:7], v[174:177], v[220:223], v[4:7]
	v_mfma_f32_16x16x32_bf16 v[0:3], v[188:191], v[220:223], v[0:3]
	s_setprio 0
	s_barrier
	s_add_i32 s48, s48, 2
	s_add_u32 s38, s38, 0x100
	s_addc_u32 s39, s39, 0
	s_add_u32 s46, s46, 0x100
	s_addc_u32 s47, s47, 0
	s_cmp_gt_u32 s48, 13
	s_cbranch_scc0 .LBB0_1350
	s_and_b64 vcc, exec, s[12:13]
	s_cbranch_vccz .LBB0_1353
	s_barrier

; #define PG8_STAGE(bufoff, gbase, voff) do { _Pragma("unroll") for (int _i = 0; _i < 2; ++_i) \
;         __builtin_amdgcn_global_load_lds((const unsigned*)((const char*)(gbase) + (voff)[_i]), (LAS unsigned*)(lds + (bufoff) + ldsw + _i * 8192), 16, 0, 0); } while (0)
; #define PG8_LDA(dst, b, h) do { _Pragma("unroll") for (int m = 0; m < 4; ++m) _Pragma("unroll") for (int k = 0; k < 2; ++k) dst[m][k] = *(const LAS bf16x8*)(lds + PG8_SA(b, h) + aoff + m * 2048 + k * 1024); } while (0)
; #define PG8_LDB(dst, b, h) do { _Pragma("unroll") for (int n = 0; n < 2; ++n) _Pragma("unroll") for (int k = 0; k < 2; ++k) dst[n][k] = *(const LAS bf16x8*)(lds + PG8_SB(b, h) + boff + n * 2048 + k * 1024); } while (0)
; #define PG8_MMA(ai, bj, At, Bt) do { __builtin_amdgcn_s_setprio(1); _Pragma("unroll") for (int m = 0; m < 4; ++m) _Pragma("unroll") for (int n = 0; n < 2; ++n) _Pragma("unroll") for (int k = 0; k < 2; ++k) \
;         acc[ai][bj][m][n] = __builtin_amdgcn_mfma_f32_16x16x32_bf16(Bt[n][k], At[m][k], acc[ai][bj][m][n], 0, 0, 0); __builtin_amdgcn_s_setprio(0); } while (0)
; #define PG8_WAIT_V(n) asm volatile("s_waitcnt vmcnt(" #n ")" ::: "memory")
; #define PG8_WAIT_L(n) asm volatile("s_waitcnt lgkmcnt(" #n ")" ::: "memory")
; #define PG8_BAR __builtin_amdgcn_s_barrier()
; #define PG8_SCHED __builtin_amdgcn_sched_barrier(0)
; template <class Epi>
; __device__ __forceinline__ void gemm_phase(LAS unsigned char* lds, const Gemm g, const StaticOrder& S, const Epi& E) {
;     ...
;             const bool last = (t == nt - 2);
;             if constexpr (Epi::HAS_MID) { if (t == nt1) E.mid(acc, cur, wr, wc, fr, fq); }
;             const char* a1 = cA + ((Epi::HAS_MID && t >= nt1) ? dA2 : 0) + (size_t)(t + 1) * kstep;
;             const char* a2 = last ? nA : cA + ((Epi::HAS_MID && t + 2 >= nt1) ? dA2 : 0) + (size_t)(t + 2) * kstep; const char* b2 = last ? nB : cB + ((Epi::HAS_MID && t + 2 >= nt1) ? dB2 : 0) + (size_t)(t + 2) * kstep;
;             const char* a3 = a2 + kstep; const char* b3 = b2 + kstep;
;             PG8_LDB(B0, 0, 0); PG8_LDB(B1, 0, 1); PG8_SCHED; PG8_LDA(At, 0, 0); PG8_STAGE(PG8_SA(1, 1), a1 + hsA, voffA);
;             PG8_WAIT_V(8); PG8_WAIT_L(0); PG8_BAR; PG8_MMA(0, 0, At, B0); PG8_MMA(0, 1, At, B1); PG8_BAR; PG8_SCHED;
.LBB0_1433:
	ds_read_b128 v[144:147], v202
	ds_read_b128 v[148:151], v202 offset:1024
	ds_read_b128 v[152:155], v202 offset:2048
	ds_read_b128 v[156:159], v202 offset:3072
	ds_read_b128 v[160:163], v203
	ds_read_b128 v[164:167], v203 offset:1024
	ds_read_b128 v[168:171], v203 offset:2048
	ds_read_b128 v[172:175], v203 offset:3072
	s_add_u32 s34, s26, 0x100
	s_addc_u32 s35, s27, 0
	s_cmp_eq_u32 s51, 40
	s_cselect_b32 s39, s1, s35
	s_cselect_b32 s38, s0, s34
	s_cselect_b32 s37, s23, s50
	s_cselect_b32 s36, s22, s25
	s_add_i32 m0, s17, 0xc000
	ds_read_b128 v[216:219], v204
	ds_read_b128 v[220:223], v204 offset:1024
	ds_read_b128 v[224:227], v204 offset:2048
	ds_read_b128 v[228:231], v204 offset:3072
	ds_read_b128 v[232:235], v204 offset:4096
	ds_read_b128 v[236:239], v204 offset:5120
	ds_read_b128 v[240:243], v204 offset:6144
	ds_read_b128 v[244:247], v204 offset:7168
	global_load_lds_dwordx4 v136, s[26:27]
	s_add_i32 m0, s17, 0xe000
	s_nop 0
	global_load_lds_dwordx4 v138, s[26:27]
	s_waitcnt vmcnt(8)
	s_waitcnt lgkmcnt(0)
	s_barrier
	s_setprio 1
	s_waitcnt lgkmcnt(0)
	v_mfma_f32_16x16x32_bf16 v[124:127], v[144:147], v[216:219], v[124:127]
	v_mfma_f32_16x16x32_bf16 v[120:123], v[152:155], v[216:219], v[120:123]
	v_mfma_f32_16x16x32_bf16 v[108:111], v[144:147], v[224:227], v[108:111]
	v_mfma_f32_16x16x32_bf16 v[104:107], v[152:155], v[224:227], v[104:107]
	v_mfma_f32_16x16x32_bf16 v[92:95], v[144:147], v[232:235], v[92:95]
	v_mfma_f32_16x16x32_bf16 v[88:91], v[152:155], v[232:235], v[88:91]
	v_mfma_f32_16x16x32_bf16 v[76:79], v[144:147], v[240:243], v[76:79]
	v_mfma_f32_16x16x32_bf16 v[72:75], v[152:155], v[240:243], v[72:75]
	v_mfma_f32_16x16x32_bf16 v[124:127], v[148:151], v[220:223], v[124:127]
	v_mfma_f32_16x16x32_bf16 v[120:123], v[156:159], v[220:223], v[120:123]
	v_mfma_f32_16x16x32_bf16 v[108:111], v[148:151], v[228:231], v[108:111]
	v_mfma_f32_16x16x32_bf16 v[104:107], v[156:159], v[228:231], v[104:107]
	v_mfma_f32_16x16x32_bf16 v[92:95], v[148:151], v[236:239], v[92:95]
	v_mfma_f32_16x16x32_bf16 v[88:91], v[156:159], v[236:239], v[88:91]
	v_mfma_f32_16x16x32_bf16 v[76:79], v[148:151], v[244:247], v[76:79]
	v_mfma_f32_16x16x32_bf16 v[72:75], v[156:159], v[244:247], v[72:75]


; #define PG8_STAGE(bufoff, gbase, voff) do { _Pragma("unroll") for (int _i = 0; _i < 2; ++_i) \
;         __builtin_amdgcn_global_load_lds((const unsigned*)((const char*)(gbase) + (voff)[_i]), (LAS unsigned*)(lds + (bufoff) + ldsw + _i * 8192), 16, 0, 0); } while (0)
; #define PG8_LDA(dst, b, h) do { _Pragma("unroll") for (int m = 0; m < 4; ++m) _Pragma("unroll") for (int k = 0; k < 2; ++k) dst[m][k] = *(const LAS bf16x8*)(lds + PG8_SA(b, h) + aoff + m * 2048 + k * 1024); } while (0)
; #define PG8_MMA(ai, bj, At, Bt) do { __builtin_amdgcn_s_setprio(1); _Pragma("unroll") for (int m = 0; m < 4; ++m) _Pragma("unroll") for (int n = 0; n < 2; ++n) _Pragma("unroll") for (int k = 0; k < 2; ++k) \
;         acc[ai][bj][m][n] = __builtin_amdgcn_mfma_f32_16x16x32_bf16(Bt[n][k], At[m][k], acc[ai][bj][m][n], 0, 0, 0); __builtin_amdgcn_s_setprio(0); } while (0)
; #define PG8_WAIT_V(n) asm volatile("s_waitcnt vmcnt(" #n ")" ::: "memory")
; #define PG8_WAIT_L(n) asm volatile("s_waitcnt lgkmcnt(" #n ")" ::: "memory")
; #define PG8_BAR __builtin_amdgcn_s_barrier()
; #define PG8_SCHED __builtin_amdgcn_sched_barrier(0)
; template <class Epi>
; __device__ __forceinline__ void gemm_phase(LAS unsigned char* lds, const Gemm g, const StaticOrder& S, const Epi& E) {
;     ...
;             PG8_WAIT_V(8); PG8_WAIT_L(0); PG8_BAR; PG8_MMA(0, 0, At, B0); PG8_MMA(0, 1, At, B1); PG8_BAR; PG8_SCHED;
;             PG8_LDA(At, 0, 1); PG8_STAGE(PG8_SB(0, 0), b2, voffB); PG8_STAGE(PG8_SB(0, 1), b2 + hsB, voffB); PG8_STAGE(PG8_SA(0, 0), a2, voffA);
;             PG8_WAIT_V(8); PG8_WAIT_L(0); PG8_BAR; PG8_MMA(1, 0, At, B0); PG8_MMA(1, 1, At, B1); PG8_BAR; PG8_SCHED;
	v_mfma_f32_16x16x32_bf16 v[116:119], v[160:163], v[216:219], v[116:119]
	v_mfma_f32_16x16x32_bf16 v[112:115], v[168:171], v[216:219], v[112:115]
	v_mfma_f32_16x16x32_bf16 v[100:103], v[160:163], v[224:227], v[100:103]
	v_mfma_f32_16x16x32_bf16 v[96:99], v[168:171], v[224:227], v[96:99]
	v_mfma_f32_16x16x32_bf16 v[84:87], v[160:163], v[232:235], v[84:87]
	v_mfma_f32_16x16x32_bf16 v[80:83], v[168:171], v[232:235], v[80:83]
	v_mfma_f32_16x16x32_bf16 v[68:71], v[160:163], v[240:243], v[68:71]
	v_mfma_f32_16x16x32_bf16 v[64:67], v[168:171], v[240:243], v[64:67]
	v_mfma_f32_16x16x32_bf16 v[116:119], v[164:167], v[220:223], v[116:119]
	v_mfma_f32_16x16x32_bf16 v[112:115], v[172:175], v[220:223], v[112:115]
	v_mfma_f32_16x16x32_bf16 v[100:103], v[164:167], v[228:231], v[100:103]
	v_mfma_f32_16x16x32_bf16 v[96:99], v[172:175], v[228:231], v[96:99]
	v_mfma_f32_16x16x32_bf16 v[84:87], v[164:167], v[236:239], v[84:87]
	v_mfma_f32_16x16x32_bf16 v[80:83], v[172:175], v[236:239], v[80:83]
	v_mfma_f32_16x16x32_bf16 v[68:71], v[164:167], v[244:247], v[68:71]
	v_mfma_f32_16x16x32_bf16 v[64:67], v[172:175], v[244:247], v[64:67]
	s_setprio 0
	s_barrier
	s_add_i32 s26, s45, s16
	s_mov_b32 m0, s26
	ds_read_b128 v[216:219], v204 offset:16384
	ds_read_b128 v[220:223], v204 offset:17408
	ds_read_b128 v[224:227], v204 offset:18432
	ds_read_b128 v[228:231], v204 offset:19456
	ds_read_b128 v[232:235], v204 offset:20480
	ds_read_b128 v[236:239], v204 offset:21504
	ds_read_b128 v[240:243], v204 offset:22528
	ds_read_b128 v[244:247], v204 offset:23552
	global_load_lds_dwordx4 v130, s[36:37]
	s_add_i32 m0, s26, 0x2000
	s_add_u32 s26, s36, 0xb0000
	s_addc_u32 s27, s37, 0
	s_add_i32 s52, s46, s16
	global_load_lds_dwordx4 v134, s[36:37]
	s_mov_b32 m0, s52
	s_nop 0
	global_load_lds_dwordx4 v130, s[26:27]
	s_add_i32 m0, s52, 0x2000
	s_nop 0
	global_load_lds_dwordx4 v134, s[26:27]
	s_mov_b32 m0, s17
	s_nop 0
	global_load_lds_dwordx4 v128, s[38:39]
	s_mov_b32 m0, s28
	s_nop 0
	global_load_lds_dwordx4 v132, s[38:39]
	s_waitcnt vmcnt(8)
	s_waitcnt lgkmcnt(0)
	s_barrier
	s_setprio 1
	s_waitcnt lgkmcnt(0)
	v_mfma_f32_16x16x32_bf16 v[60:63], v[144:147], v[216:219], v[60:63]
	v_mfma_f32_16x16x32_bf16 v[56:59], v[152:155], v[216:219], v[56:59]
	v_mfma_f32_16x16x32_bf16 v[44:47], v[144:147], v[224:227], v[44:47]
	v_mfma_f32_16x16x32_bf16 v[40:43], v[152:155], v[224:227], v[40:43]
	v_mfma_f32_16x16x32_bf16 v[28:31], v[144:147], v[232:235], v[28:31]
	v_mfma_f32_16x16x32_bf16 v[24:27], v[152:155], v[232:235], v[24:27]
	v_mfma_f32_16x16x32_bf16 v[12:15], v[144:147], v[240:243], v[12:15]
	v_mfma_f32_16x16x32_bf16 v[8:11], v[152:155], v[240:243], v[8:11]
	v_mfma_f32_16x16x32_bf16 v[60:63], v[148:151], v[220:223], v[60:63]
	v_mfma_f32_16x16x32_bf16 v[56:59], v[156:159], v[220:223], v[56:59]
	v_mfma_f32_16x16x32_bf16 v[44:47], v[148:151], v[228:231], v[44:47]
	v_mfma_f32_16x16x32_bf16 v[40:43], v[156:159], v[228:231], v[40:43]
	v_mfma_f32_16x16x32_bf16 v[28:31], v[148:151], v[236:239], v[28:31]
	v_mfma_f32_16x16x32_bf16 v[24:27], v[156:159], v[236:239], v[24:27]
	v_mfma_f32_16x16x32_bf16 v[12:15], v[148:151], v[244:247], v[12:15]
	v_mfma_f32_16x16x32_bf16 v[8:11], v[156:159], v[244:247], v[8:11]


; #define PG8_STAGE(bufoff, gbase, voff) do { _Pragma("unroll") for (int _i = 0; _i < 2; ++_i) \
;         __builtin_amdgcn_global_load_lds((const unsigned*)((const char*)(gbase) + (voff)[_i]), (LAS unsigned*)(lds + (bufoff) + ldsw + _i * 8192), 16, 0, 0); } while (0)
; #define PG8_LDA(dst, b, h) do { _Pragma("unroll") for (int m = 0; m < 4; ++m) _Pragma("unroll") for (int k = 0; k < 2; ++k) dst[m][k] = *(const LAS bf16x8*)(lds + PG8_SA(b, h) + aoff + m * 2048 + k * 1024); } while (0)
; #define PG8_LDB(dst, b, h) do { _Pragma("unroll") for (int n = 0; n < 2; ++n) _Pragma("unroll") for (int k = 0; k < 2; ++k) dst[n][k] = *(const LAS bf16x8*)(lds + PG8_SB(b, h) + boff + n * 2048 + k * 1024); } while (0)
; #define PG8_MMA(ai, bj, At, Bt) do { __builtin_amdgcn_s_setprio(1); _Pragma("unroll") for (int m = 0; m < 4; ++m) _Pragma("unroll") for (int n = 0; n < 2; ++n) _Pragma("unroll") for (int k = 0; k < 2; ++k) \
;         acc[ai][bj][m][n] = __builtin_amdgcn_mfma_f32_16x16x32_bf16(Bt[n][k], At[m][k], acc[ai][bj][m][n], 0, 0, 0); __builtin_amdgcn_s_setprio(0); } while (0)
; #define PG8_WAIT_V(n) asm volatile("s_waitcnt vmcnt(" #n ")" ::: "memory")
; #define PG8_WAIT_L(n) asm volatile("s_waitcnt lgkmcnt(" #n ")" ::: "memory")
; #define PG8_BAR __builtin_amdgcn_s_barrier()
; #define PG8_SCHED __builtin_amdgcn_sched_barrier(0)
; template <class Epi>
; __device__ __forceinline__ void gemm_phase(LAS unsigned char* lds, const Gemm g, const StaticOrder& S, const Epi& E) {
;     ...
;             PG8_WAIT_V(8); PG8_WAIT_L(0); PG8_BAR; PG8_MMA(1, 0, At, B0); PG8_MMA(1, 1, At, B1); PG8_BAR; PG8_SCHED;
;             PG8_LDB(B0, 1, 0); PG8_LDB(B1, 1, 1); PG8_SCHED; PG8_LDA(At, 1, 0); PG8_STAGE(PG8_SA(0, 1), a2 + hsA, voffA);
;             PG8_WAIT_V(8); PG8_WAIT_L(0); PG8_BAR; PG8_MMA(0, 0, At, B0); PG8_MMA(0, 1, At, B1); PG8_BAR; PG8_SCHED;
	v_mfma_f32_16x16x32_bf16 v[52:55], v[160:163], v[216:219], v[52:55]
	v_mfma_f32_16x16x32_bf16 v[48:51], v[168:171], v[216:219], v[48:51]
	v_mfma_f32_16x16x32_bf16 v[36:39], v[160:163], v[224:227], v[36:39]
	v_mfma_f32_16x16x32_bf16 v[32:35], v[168:171], v[224:227], v[32:35]
	v_mfma_f32_16x16x32_bf16 v[20:23], v[160:163], v[232:235], v[20:23]
	v_mfma_f32_16x16x32_bf16 v[16:19], v[168:171], v[232:235], v[16:19]
	v_mfma_f32_16x16x32_bf16 v[4:7], v[160:163], v[240:243], v[4:7]
	v_mfma_f32_16x16x32_bf16 v[0:3], v[168:171], v[240:243], v[0:3]
	v_mfma_f32_16x16x32_bf16 v[52:55], v[164:167], v[220:223], v[52:55]
	v_mfma_f32_16x16x32_bf16 v[48:51], v[172:175], v[220:223], v[48:51]
	v_mfma_f32_16x16x32_bf16 v[36:39], v[164:167], v[228:231], v[36:39]
	v_mfma_f32_16x16x32_bf16 v[32:35], v[172:175], v[228:231], v[32:35]
	v_mfma_f32_16x16x32_bf16 v[20:23], v[164:167], v[236:239], v[20:23]
	v_mfma_f32_16x16x32_bf16 v[16:19], v[172:175], v[236:239], v[16:19]
	v_mfma_f32_16x16x32_bf16 v[4:7], v[164:167], v[244:247], v[4:7]
	v_mfma_f32_16x16x32_bf16 v[0:3], v[172:175], v[244:247], v[0:3]
	s_setprio 0
	s_barrier
	s_add_i32 s52, 0, 0x18000
	s_add_i32 s53, 0, 0x1c000
	v_add_u32_e32 v156, s52, v184
	v_add_u32_e32 v172, s53, v184
	ds_read_b128 v[144:147], v156
	ds_read_b128 v[148:151], v156 offset:1024
	ds_read_b128 v[152:155], v156 offset:2048
	ds_read_b128 v[156:159], v156 offset:3072
	ds_read_b128 v[160:163], v172
	ds_read_b128 v[164:167], v172 offset:1024
	ds_read_b128 v[168:171], v172 offset:2048
	ds_read_b128 v[172:175], v172 offset:3072
	s_add_u32 s26, s38, 0xb0000
	s_addc_u32 s27, s39, 0
	s_mov_b32 m0, s29
	ds_read_b128 v[216:219], v204 offset:32768
	ds_read_b128 v[220:223], v204 offset:33792
	ds_read_b128 v[224:227], v204 offset:34816
	ds_read_b128 v[228:231], v204 offset:35840
	ds_read_b128 v[232:235], v204 offset:36864
	ds_read_b128 v[236:239], v204 offset:37888
	ds_read_b128 v[240:243], v204 offset:38912
	ds_read_b128 v[244:247], v204 offset:39936
	global_load_lds_dwordx4 v128, s[26:27]
	s_mov_b32 m0, s30
	s_nop 0
	global_load_lds_dwordx4 v132, s[26:27]
	s_waitcnt vmcnt(8)
	s_waitcnt lgkmcnt(0)
	s_barrier
	s_setprio 1
	s_waitcnt lgkmcnt(0)
	v_mfma_f32_16x16x32_bf16 v[124:127], v[144:147], v[216:219], v[124:127]
	v_mfma_f32_16x16x32_bf16 v[120:123], v[152:155], v[216:219], v[120:123]
	v_mfma_f32_16x16x32_bf16 v[108:111], v[144:147], v[224:227], v[108:111]
	v_mfma_f32_16x16x32_bf16 v[104:107], v[152:155], v[224:227], v[104:107]
	v_mfma_f32_16x16x32_bf16 v[92:95], v[144:147], v[232:235], v[92:95]
	v_mfma_f32_16x16x32_bf16 v[88:91], v[152:155], v[232:235], v[88:91]
	v_mfma_f32_16x16x32_bf16 v[76:79], v[144:147], v[240:243], v[76:79]
	v_mfma_f32_16x16x32_bf16 v[72:75], v[152:155], v[240:243], v[72:75]
	v_mfma_f32_16x16x32_bf16 v[124:127], v[148:151], v[220:223], v[124:127]
	v_mfma_f32_16x16x32_bf16 v[120:123], v[156:159], v[220:223], v[120:123]
	v_mfma_f32_16x16x32_bf16 v[108:111], v[148:151], v[228:231], v[108:111]
	v_mfma_f32_16x16x32_bf16 v[104:107], v[156:159], v[228:231], v[104:107]
	v_mfma_f32_16x16x32_bf16 v[92:95], v[148:151], v[236:239], v[92:95]
	v_mfma_f32_16x16x32_bf16 v[88:91], v[156:159], v[236:239], v[88:91]
	v_mfma_f32_16x16x32_bf16 v[76:79], v[148:151], v[244:247], v[76:79]
	v_mfma_f32_16x16x32_bf16 v[72:75], v[156:159], v[244:247], v[72:75]


; #define PG8_STAGE(bufoff, gbase, voff) do { _Pragma("unroll") for (int _i = 0; _i < 2; ++_i) \
;         __builtin_amdgcn_global_load_lds((const unsigned*)((const char*)(gbase) + (voff)[_i]), (LAS unsigned*)(lds + (bufoff) + ldsw + _i * 8192), 16, 0, 0); } while (0)
; #define PG8_LDA(dst, b, h) do { _Pragma("unroll") for (int m = 0; m < 4; ++m) _Pragma("unroll") for (int k = 0; k < 2; ++k) dst[m][k] = *(const LAS bf16x8*)(lds + PG8_SA(b, h) + aoff + m * 2048 + k * 1024); } while (0)
; #define PG8_MMA(ai, bj, At, Bt) do { __builtin_amdgcn_s_setprio(1); _Pragma("unroll") for (int m = 0; m < 4; ++m) _Pragma("unroll") for (int n = 0; n < 2; ++n) _Pragma("unroll") for (int k = 0; k < 2; ++k) \
;         acc[ai][bj][m][n] = __builtin_amdgcn_mfma_f32_16x16x32_bf16(Bt[n][k], At[m][k], acc[ai][bj][m][n], 0, 0, 0); __builtin_amdgcn_s_setprio(0); } while (0)
; #define PG8_WAIT_V(n) asm volatile("s_waitcnt vmcnt(" #n ")" ::: "memory")
; #define PG8_WAIT_L(n) asm volatile("s_waitcnt lgkmcnt(" #n ")" ::: "memory")
; #define PG8_BAR __builtin_amdgcn_s_barrier()
; #define PG8_SCHED __builtin_amdgcn_sched_barrier(0)
; template <class Epi>
; __device__ __forceinline__ void gemm_phase(LAS unsigned char* lds, const Gemm g, const StaticOrder& S, const Epi& E) {
;     ...
;             PG8_WAIT_V(8); PG8_WAIT_L(0); PG8_BAR; PG8_MMA(0, 0, At, B0); PG8_MMA(0, 1, At, B1); PG8_BAR; PG8_SCHED;
;             PG8_LDA(At, 1, 1); PG8_STAGE(PG8_SB(1, 0), b3, voffB); PG8_STAGE(PG8_SB(1, 1), b3 + hsB, voffB); PG8_STAGE(PG8_SA(1, 0), a3, voffA);
;             PG8_WAIT_V(8); PG8_WAIT_L(0); PG8_BAR; PG8_MMA(1, 0, At, B0); PG8_MMA(1, 1, At, B1); PG8_BAR; PG8_SCHED;
	v_mfma_f32_16x16x32_bf16 v[116:119], v[160:163], v[216:219], v[116:119]
	v_mfma_f32_16x16x32_bf16 v[112:115], v[168:171], v[216:219], v[112:115]
	v_mfma_f32_16x16x32_bf16 v[100:103], v[160:163], v[224:227], v[100:103]
	v_mfma_f32_16x16x32_bf16 v[96:99], v[168:171], v[224:227], v[96:99]
	v_mfma_f32_16x16x32_bf16 v[84:87], v[160:163], v[232:235], v[84:87]
	v_mfma_f32_16x16x32_bf16 v[80:83], v[168:171], v[232:235], v[80:83]
	v_mfma_f32_16x16x32_bf16 v[68:71], v[160:163], v[240:243], v[68:71]
	v_mfma_f32_16x16x32_bf16 v[64:67], v[168:171], v[240:243], v[64:67]
	v_mfma_f32_16x16x32_bf16 v[116:119], v[164:167], v[220:223], v[116:119]
	v_mfma_f32_16x16x32_bf16 v[112:115], v[172:175], v[220:223], v[112:115]
	v_mfma_f32_16x16x32_bf16 v[100:103], v[164:167], v[228:231], v[100:103]
	v_mfma_f32_16x16x32_bf16 v[96:99], v[172:175], v[228:231], v[96:99]
	v_mfma_f32_16x16x32_bf16 v[84:87], v[164:167], v[236:239], v[84:87]
	v_mfma_f32_16x16x32_bf16 v[80:83], v[172:175], v[236:239], v[80:83]
	v_mfma_f32_16x16x32_bf16 v[68:71], v[164:167], v[244:247], v[68:71]
	v_mfma_f32_16x16x32_bf16 v[64:67], v[172:175], v[244:247], v[64:67]
	s_setprio 0
	s_barrier
	s_add_u32 s98, s36, 0x80
	s_addc_u32 s99, s37, 0
	s_add_u32 s100, s38, 0x80
	s_addc_u32 s101, s39, 0
	s_add_i32 s26, s52, s16
	s_mov_b32 m0, s26
	ds_read_b128 v[216:219], v204 offset:49152
	ds_read_b128 v[220:223], v204 offset:50176
	ds_read_b128 v[224:227], v204 offset:51200
	ds_read_b128 v[228:231], v204 offset:52224
	ds_read_b128 v[232:235], v204 offset:53248
	ds_read_b128 v[236:239], v204 offset:54272
	ds_read_b128 v[240:243], v204 offset:55296
	ds_read_b128 v[244:247], v204 offset:56320
	global_load_lds_dwordx4 v130, s[98:99]
	s_add_i32 m0, s26, 0x2000
	s_add_u32 s26, s36, 0xb0080
	s_addc_u32 s27, s37, 0
	s_add_i32 s36, s53, s16
	global_load_lds_dwordx4 v134, s[98:99]
	s_mov_b32 m0, s36
	s_nop 0
	global_load_lds_dwordx4 v130, s[26:27]
	s_add_i32 m0, s36, 0x2000
	s_nop 0
	global_load_lds_dwordx4 v134, s[26:27]
	s_mov_b32 m0, s41
	s_nop 0
	global_load_lds_dwordx4 v128, s[100:101]
	s_mov_b32 m0, s42
	s_nop 0
	global_load_lds_dwordx4 v132, s[100:101]
	s_waitcnt vmcnt(8)
	s_waitcnt lgkmcnt(0)
	s_barrier
	s_setprio 1
	s_waitcnt lgkmcnt(0)
	v_mfma_f32_16x16x32_bf16 v[60:63], v[144:147], v[216:219], v[60:63]
	v_mfma_f32_16x16x32_bf16 v[56:59], v[152:155], v[216:219], v[56:59]
	v_mfma_f32_16x16x32_bf16 v[44:47], v[144:147], v[224:227], v[44:47]
	v_mfma_f32_16x16x32_bf16 v[40:43], v[152:155], v[224:227], v[40:43]
	v_mfma_f32_16x16x32_bf16 v[28:31], v[144:147], v[232:235], v[28:31]
	v_mfma_f32_16x16x32_bf16 v[24:27], v[152:155], v[232:235], v[24:27]
	v_mfma_f32_16x16x32_bf16 v[12:15], v[144:147], v[240:243], v[12:15]
	v_mfma_f32_16x16x32_bf16 v[8:11], v[152:155], v[240:243], v[8:11]
	v_mfma_f32_16x16x32_bf16 v[60:63], v[148:151], v[220:223], v[60:63]
	v_mfma_f32_16x16x32_bf16 v[56:59], v[156:159], v[220:223], v[56:59]
	v_mfma_f32_16x16x32_bf16 v[44:47], v[148:151], v[228:231], v[44:47]
	v_mfma_f32_16x16x32_bf16 v[40:43], v[156:159], v[228:231], v[40:43]
	v_mfma_f32_16x16x32_bf16 v[28:31], v[148:151], v[236:239], v[28:31]
	v_mfma_f32_16x16x32_bf16 v[24:27], v[156:159], v[236:239], v[24:27]
	v_mfma_f32_16x16x32_bf16 v[12:15], v[148:151], v[244:247], v[12:15]
	v_mfma_f32_16x16x32_bf16 v[8:11], v[156:159], v[244:247], v[8:11]


; #define PG8_MMA(ai, bj, At, Bt) do { __builtin_amdgcn_s_setprio(1); _Pragma("unroll") for (int m = 0; m < 4; ++m) _Pragma("unroll") for (int n = 0; n < 2; ++n) _Pragma("unroll") for (int k = 0; k < 2; ++k) \
;         acc[ai][bj][m][n] = __builtin_amdgcn_mfma_f32_16x16x32_bf16(Bt[n][k], At[m][k], acc[ai][bj][m][n], 0, 0, 0); __builtin_amdgcn_s_setprio(0); } while (0)
; #define PG8_WAIT_V(n) asm volatile("s_waitcnt vmcnt(" #n ")" ::: "memory")
; #define PG8_WAIT_L(n) asm volatile("s_waitcnt lgkmcnt(" #n ")" ::: "memory")
; #define PG8_BAR __builtin_amdgcn_s_barrier()
; #define PG8_SCHED __builtin_amdgcn_sched_barrier(0)
; template <class Epi>
; __device__ __forceinline__ void gemm_phase(LAS unsigned char* lds, const Gemm g, const StaticOrder& S, const Epi& E) {
;     ...
;             PG8_WAIT_V(8); PG8_WAIT_L(0); PG8_BAR; PG8_MMA(1, 0, At, B0); PG8_MMA(1, 1, At, B1); PG8_BAR; PG8_SCHED;
;         }
;         if (wr == 0) PG8_BAR;
	v_mfma_f32_16x16x32_bf16 v[52:55], v[160:163], v[216:219], v[52:55]
	v_mfma_f32_16x16x32_bf16 v[48:51], v[168:171], v[216:219], v[48:51]
	v_mfma_f32_16x16x32_bf16 v[36:39], v[160:163], v[224:227], v[36:39]
	v_mfma_f32_16x16x32_bf16 v[32:35], v[168:171], v[224:227], v[32:35]
	v_mfma_f32_16x16x32_bf16 v[20:23], v[160:163], v[232:235], v[20:23]
	v_mfma_f32_16x16x32_bf16 v[16:19], v[168:171], v[232:235], v[16:19]
	v_mfma_f32_16x16x32_bf16 v[4:7], v[160:163], v[240:243], v[4:7]
	v_mfma_f32_16x16x32_bf16 v[0:3], v[168:171], v[240:243], v[0:3]
	v_mfma_f32_16x16x32_bf16 v[52:55], v[164:167], v[220:223], v[52:55]
	v_mfma_f32_16x16x32_bf16 v[48:51], v[172:175], v[220:223], v[48:51]
	v_mfma_f32_16x16x32_bf16 v[36:39], v[164:167], v[228:231], v[36:39]
	v_mfma_f32_16x16x32_bf16 v[32:35], v[172:175], v[228:231], v[32:35]
	v_mfma_f32_16x16x32_bf16 v[20:23], v[164:167], v[236:239], v[20:23]
	v_mfma_f32_16x16x32_bf16 v[16:19], v[172:175], v[236:239], v[16:19]
	v_mfma_f32_16x16x32_bf16 v[4:7], v[164:167], v[244:247], v[4:7]
	v_mfma_f32_16x16x32_bf16 v[0:3], v[172:175], v[244:247], v[0:3]
	s_setprio 0
	s_barrier
	s_add_i32 s51, s51, 2
	s_add_u32 s25, s25, 0x100
	s_addc_u32 s50, s50, 0
	s_cmp_gt_u32 s51, 41
	s_mov_b64 s[26:27], s[34:35]
	s_cbranch_scc0 .LBB0_1433
	s_and_b64 vcc, exec, s[18:19]
	s_cbranch_vccz .LBB0_1436
	s_barrier
